# v18 + LRU-A/B gate constants (ba,bx,c8) read one group ahead (3 rotating register sets, uses renamed), MFMA->VALU distances re-padded and machine-checked
# speedup vs baseline: 1.0193x; 1.0068x over previous
; #define LAS __attribute__((address_space(3)))
; __device__ __forceinline__ unsigned pk2(float lo, float hi) { return f2bf(lo) | (f2bf(hi) << 16); }
; template <bool PHASE_B>
; __device__ __forceinline__ void lru_item(const Params& p, LAS unsigned char* lds, int ci, int ci_next, int jb, const int tid, v4u (&xvn)[3]) {
;     ...
;     for (int ks = 0; ks < 2; ++ks) { const int cb0 = 32 * ks + 8 * fq;
;         f32x4 s0 = *(const LAS f32x4*)(CB + cb0), s1 = *(const LAS f32x4*)(CB + cb0 + 4);
; #pragma unroll
;         for (int tap = 0; tap < 4; ++tap) { const v4u v = *(const LAS v4u*)(lds + LR_XR + (16 * rt + fr + tap) * 144 + cb0 * 2);
;             const f32x4 w0 = *(const LAS f32x4*)(CW + tap * 64 + cb0), w1 = *(const LAS f32x4*)(CW + tap * 64 + cb0 + 4);
;             s0 += (f32x4){bflo(v.x), bfhi(v.x), bflo(v.y), bfhi(v.y)} * w0; s1 += (f32x4){bflo(v.z), bfhi(v.z), bflo(v.w), bfhi(v.w)} * w1; }
;         v4u o; o.x = pk2(s0[0], s0[1]); o.y = pk2(s0[2], s0[3]); o.z = pk2(s1[0], s1[1]); o.w = pk2(s1[2], s1[3]);
;         af[ks] = __builtin_bit_cast(bf16x8, o); }
.LBB0_339:
	v_add_u32_e32 v1, v167, v157
	ds_read_b128 v[14:17], v165 offset:56832
	ds_read_b128 v[18:21], v165 offset:56848
	ds_read_b128 v[22:25], v1
	v_add_u32_e32 v31, v167, v166
	ds_read_b128 v[26:29], v31 offset:55808
	ds_read_b128 v[36:39], v31 offset:55824
	v_add_u32_e32 v50, 0xd800, v170
	v_add_u32_e32 v51, 0xdc00, v170
	s_waitcnt lgkmcnt(2)
	v_lshlrev_b32_e32 v40, 16, v22
	v_and_b32_e32 v41, 0xffff0000, v22
	v_lshlrev_b32_e32 v22, 16, v23
	v_and_b32_e32 v23, 0xffff0000, v23
	s_waitcnt lgkmcnt(1)
	v_pk_fma_f32 v[28:29], v[28:29], v[22:23], v[16:17]
	v_pk_fma_f32 v[26:27], v[26:27], v[40:41], v[14:15]
	v_lshlrev_b32_e32 v14, 16, v24
	v_and_b32_e32 v15, 0xffff0000, v24
	v_lshlrev_b32_e32 v16, 16, v25
	v_and_b32_e32 v17, 0xffff0000, v25
	s_waitcnt lgkmcnt(0)
	v_pk_fma_f32 v[38:39], v[38:39], v[16:17], v[20:21]
	v_pk_fma_f32 v[36:37], v[36:37], v[14:15], v[18:19]
	ds_read_b128 v[14:17], v1 offset:144
	ds_read_b128 v[18:21], v31 offset:56064
	ds_read_b128 v[22:25], v31 offset:56080
	v_add_u32_e32 v132, v173, v166
	s_and_b64 vcc, exec, s[6:7]
	s_waitcnt lgkmcnt(2)
	v_lshlrev_b32_e32 v40, 16, v14
	v_and_b32_e32 v41, 0xffff0000, v14
	v_lshlrev_b32_e32 v14, 16, v15
	v_and_b32_e32 v15, 0xffff0000, v15
	s_waitcnt lgkmcnt(1)
	v_pk_fma_f32 v[28:29], v[20:21], v[14:15], v[28:29]
	v_lshlrev_b32_e32 v14, 16, v16
	v_and_b32_e32 v15, 0xffff0000, v16
	v_lshlrev_b32_e32 v16, 16, v17
	v_and_b32_e32 v17, 0xffff0000, v17
	v_pk_fma_f32 v[26:27], v[18:19], v[40:41], v[26:27]
	s_waitcnt lgkmcnt(0)
	v_pk_fma_f32 v[38:39], v[24:25], v[16:17], v[38:39]
	v_pk_fma_f32 v[36:37], v[22:23], v[14:15], v[36:37]
	ds_read_b128 v[14:17], v1 offset:288
	ds_read_b128 v[18:21], v31 offset:56320
	ds_read_b128 v[22:25], v31 offset:56336
	s_waitcnt lgkmcnt(2)
	v_lshlrev_b32_e32 v40, 16, v14
	v_and_b32_e32 v41, 0xffff0000, v14
	v_lshlrev_b32_e32 v14, 16, v15
	v_and_b32_e32 v15, 0xffff0000, v15
	s_waitcnt lgkmcnt(1)
	v_pk_fma_f32 v[28:29], v[20:21], v[14:15], v[28:29]
	v_lshlrev_b32_e32 v14, 16, v16
	v_and_b32_e32 v15, 0xffff0000, v16
	v_lshlrev_b32_e32 v16, 16, v17
	v_and_b32_e32 v17, 0xffff0000, v17
	v_pk_fma_f32 v[26:27], v[18:19], v[40:41], v[26:27]
	s_waitcnt lgkmcnt(0)
	v_pk_fma_f32 v[36:37], v[22:23], v[14:15], v[36:37]
	v_pk_fma_f32 v[38:39], v[24:25], v[16:17], v[38:39]
	ds_read_b128 v[14:17], v1 offset:432
	ds_read_b128 v[18:21], v31 offset:56576
	ds_read_b128 v[22:25], v31 offset:56592
	s_waitcnt lgkmcnt(2)
	v_lshlrev_b32_e32 v40, 16, v14
	v_and_b32_e32 v41, 0xffff0000, v14
	v_lshlrev_b32_e32 v14, 16, v15
	v_and_b32_e32 v15, 0xffff0000, v15
	s_waitcnt lgkmcnt(1)
	v_pk_fma_f32 v[20:21], v[20:21], v[14:15], v[28:29]
	v_pk_fma_f32 v[14:15], v[18:19], v[40:41], v[26:27]
	v_lshlrev_b32_e32 v18, 16, v16
	v_bfe_u32 v1, v14, 16, 1
	v_add3_u32 v1, v14, v1, s33
	v_bfe_u32 v14, v15, 16, 1
	v_lshrrev_b32_e32 v1, 16, v1
	v_add3_u32 v14, v15, v14, s33
	v_and_or_b32 v14, v14, s11, v1
	v_and_b32_e32 v19, 0xffff0000, v16
	v_lshlrev_b32_e32 v16, 16, v17
	v_and_b32_e32 v17, 0xffff0000, v17
	s_waitcnt lgkmcnt(0)
	v_pk_fma_f32 v[24:25], v[24:25], v[16:17], v[38:39]
	v_pk_fma_f32 v[16:17], v[22:23], v[18:19], v[36:37]
	v_cvt_pk_bf16_f32 v15, v20, v21
	v_bfe_u32 v1, v16, 16, 1
	v_add3_u32 v1, v16, v1, s33
	v_bfe_u32 v16, v17, 16, 1
	v_lshrrev_b32_e32 v1, 16, v1
	v_add3_u32 v16, v17, v16, s33
	v_and_or_b32 v16, v16, s11, v1
	v_bfe_u32 v1, v24, 16, 1
	v_bfe_u32 v17, v25, 16, 1
	v_add3_u32 v1, v24, v1, s33
	v_add3_u32 v17, v25, v17, s33
	ds_read_b128 v[18:21], v31 offset:56960
	ds_read_b128 v[22:25], v31 offset:56976
	ds_read_b128 v[26:29], v198
	ds_read_b128 v[36:39], v31 offset:55936
	ds_read_b128 v[40:43], v31 offset:55952
	v_lshrrev_b32_e32 v1, 16, v1
	v_and_or_b32 v17, v17, s11, v1
	s_waitcnt lgkmcnt(2)
	v_lshlrev_b32_e32 v44, 16, v26
	v_and_b32_e32 v45, 0xffff0000, v26
	v_lshlrev_b32_e32 v26, 16, v27
	v_and_b32_e32 v27, 0xffff0000, v27
	s_waitcnt lgkmcnt(1)
	v_pk_fma_f32 v[38:39], v[38:39], v[26:27], v[20:21]
	v_pk_fma_f32 v[36:37], v[36:37], v[44:45], v[18:19]
	v_lshlrev_b32_e32 v18, 16, v28
	v_and_b32_e32 v19, 0xffff0000, v28
	v_lshlrev_b32_e32 v20, 16, v29
	v_and_b32_e32 v21, 0xffff0000, v29
	s_waitcnt lgkmcnt(0)
	v_pk_fma_f32 v[42:43], v[42:43], v[20:21], v[24:25]
	v_pk_fma_f32 v[40:41], v[40:41], v[18:19], v[22:23]
	ds_read_b128 v[18:21], v198 offset:144
	ds_read_b128 v[22:25], v31 offset:56192
	ds_read_b128 v[26:29], v31 offset:56208
	s_waitcnt lgkmcnt(2)
	v_lshlrev_b32_e32 v44, 16, v18
	v_and_b32_e32 v45, 0xffff0000, v18
	v_lshlrev_b32_e32 v18, 16, v19
	v_and_b32_e32 v19, 0xffff0000, v19
	s_waitcnt lgkmcnt(1)
	v_pk_fma_f32 v[38:39], v[24:25], v[18:19], v[38:39]
	v_lshlrev_b32_e32 v18, 16, v20
	v_and_b32_e32 v19, 0xffff0000, v20
	v_lshlrev_b32_e32 v20, 16, v21
	v_and_b32_e32 v21, 0xffff0000, v21
	v_pk_fma_f32 v[36:37], v[22:23], v[44:45], v[36:37]
	s_waitcnt lgkmcnt(0)
	v_pk_fma_f32 v[42:43], v[28:29], v[20:21], v[42:43]
	v_pk_fma_f32 v[40:41], v[26:27], v[18:19], v[40:41]
	ds_read_b128 v[18:21], v198 offset:288
	ds_read_b128 v[22:25], v31 offset:56448
	ds_read_b128 v[26:29], v31 offset:56464
	s_waitcnt lgkmcnt(2)
	v_lshlrev_b32_e32 v44, 16, v18
	v_and_b32_e32 v45, 0xffff0000, v18
	v_lshlrev_b32_e32 v18, 16, v19
	v_and_b32_e32 v19, 0xffff0000, v19
	s_waitcnt lgkmcnt(1)
	v_pk_fma_f32 v[38:39], v[24:25], v[18:19], v[38:39]
	v_lshlrev_b32_e32 v18, 16, v20
	v_and_b32_e32 v19, 0xffff0000, v20
	v_lshlrev_b32_e32 v20, 16, v21
	v_and_b32_e32 v21, 0xffff0000, v21
	v_pk_fma_f32 v[36:37], v[22:23], v[44:45], v[36:37]
	s_waitcnt lgkmcnt(0)
	v_pk_fma_f32 v[42:43], v[28:29], v[20:21], v[42:43]
	v_pk_fma_f32 v[40:41], v[26:27], v[18:19], v[40:41]
	ds_read_b128 v[18:21], v198 offset:432
	ds_read_b128 v[22:25], v31 offset:56704
	ds_read_b128 v[26:29], v31 offset:56720
	s_waitcnt lgkmcnt(2)
; #define LAS __attribute__((address_space(3)))
; template <bool PHASE_B>
; __device__ __forceinline__ void lru_item(const Params& p, LAS unsigned char* lds, int ci, int ci_next, int jb, const int tid, v4u (&xvn)[3]) {
;     ...
;     float xc[4][4];
; #pragma unroll
;     for (int ct = 0; ct < 4; ++ct) { const int ch = 16 * ct + fr; float xr7[7];
; #pragma unroll
;         for (int j = 0; j < 7; ++j) xr7[j] = __builtin_bit_cast(float, (unsigned)(*(const LAS bf16*)(lds + LR_XR + (16 * rt + 4 * fq + j) * 144 + ch * 2)) << 16);
;         const float w0 = CW[ch], w1 = CW[64 + ch], w2 = CW[128 + ch], w3 = CW[192 + ch], b = CB[ch];
; #pragma unroll
;         for (int e = 0; e < 4; ++e) xc[ct][e] = b + xr7[e] * w0 + xr7[e + 1] * w1 + xr7[e + 2] * w2 + xr7[e + 3] * w3; }
	v_lshlrev_b32_e32 v44, 16, v18
	v_and_b32_e32 v45, 0xffff0000, v18
	v_lshlrev_b32_e32 v18, 16, v19
	v_and_b32_e32 v19, 0xffff0000, v19
	s_waitcnt lgkmcnt(1)
	v_pk_fma_f32 v[24:25], v[24:25], v[18:19], v[38:39]
	v_pk_fma_f32 v[18:19], v[22:23], v[44:45], v[36:37]
	v_lshlrev_b32_e32 v22, 16, v20
	v_bfe_u32 v1, v18, 16, 1
	v_add3_u32 v1, v18, v1, s33
	v_bfe_u32 v18, v19, 16, 1
	v_lshrrev_b32_e32 v1, 16, v1
	v_add3_u32 v18, v19, v18, s33
	v_and_or_b32 v18, v18, s11, v1
	v_and_b32_e32 v23, 0xffff0000, v20
	v_lshlrev_b32_e32 v20, 16, v21
	v_and_b32_e32 v21, 0xffff0000, v21
	s_waitcnt lgkmcnt(0)
	v_pk_fma_f32 v[28:29], v[28:29], v[20:21], v[42:43]
	v_pk_fma_f32 v[20:21], v[26:27], v[22:23], v[40:41]
	v_cvt_pk_bf16_f32 v19, v24, v25
	v_bfe_u32 v1, v20, 16, 1
	v_add3_u32 v1, v20, v1, s33
	v_bfe_u32 v20, v21, 16, 1
	v_lshrrev_b32_e32 v1, 16, v1
	v_add3_u32 v20, v21, v20, s33
	v_and_or_b32 v20, v20, s11, v1
	v_cvt_pk_bf16_f32 v21, v28, v29
	v_add_u32_e32 v1, v168, v169
	ds_read_u16 v22, v1
	s_waitcnt lgkmcnt(0)
	v_lshlrev_b32_e32 v23, 16, v22
	ds_read_u16 v22, v1 offset:144
	ds_read_u16 v31, v1 offset:288
	ds_read_u16 v38, v1 offset:432
	ds_read_u16 v39, v1 offset:576
	ds_read_u16 v46, v1 offset:720
	ds_read_u16 v1, v1 offset:864
	ds_read2_b32 v[24:25], v50 offset0:128 offset1:144
	ds_read2_b32 v[26:27], v50 offset0:192 offset1:208
	ds_read2_b32 v[28:29], v51 offset1:16
	ds_read2_b32 v[36:37], v51 offset0:64 offset1:80
	ds_read2_b32 v[40:41], v51 offset0:128 offset1:144
	s_waitcnt lgkmcnt(10)
	v_lshlrev_b32_e32 v45, 16, v22
	s_waitcnt lgkmcnt(8)
	v_lshlrev_b32_e32 v43, 16, v38
	s_waitcnt lgkmcnt(7)
	v_lshlrev_b32_e32 v42, 16, v39
	s_waitcnt lgkmcnt(3)
	v_mov_b32_e32 v38, v26
	v_mov_b32_e32 v39, v24
	v_mov_b32_e32 v22, v45
	v_pk_mul_f32 v[22:23], v[38:39], v[22:23]
	v_lshlrev_b32_e32 v44, 16, v31
	s_waitcnt lgkmcnt(0)
	v_add_f32_e32 v23, v23, v40
	v_add_f32_e32 v24, v22, v23
	v_pk_mul_f32 v[22:23], v[38:39], v[44:45]
	v_mov_b32_e32 v47, v28
	v_add_f32_e32 v23, v23, v40
	v_add_f32_e32 v26, v22, v23
	v_pk_mov_b32 v[22:23], v[42:43], v[44:45] op_sel:[1,0]
	s_nop 0
	v_pk_mul_f32 v[44:45], v[38:39], v[22:23]
	v_pk_mul_f32 v[38:39], v[38:39], v[42:43]
	v_add_f32_e32 v31, v45, v40
	v_lshlrev_b32_e32 v45, 16, v46
	v_mov_b32_e32 v46, v36
	v_pk_mul_f32 v[48:49], v[46:47], v[22:23]
	v_pk_mul_f32 v[22:23], v[46:47], v[42:43]
	v_add_f32_e32 v31, v44, v31
	v_lshlrev_b32_e32 v44, 16, v1
	v_add_f32_e32 v1, v23, v26
	v_add_f32_e32 v108, v22, v1
	v_pk_mov_b32 v[22:23], v[44:45], v[42:43] op_sel:[1,0]
	v_add_f32_e32 v39, v39, v40
	v_pk_mul_f32 v[22:23], v[46:47], v[22:23]
	v_add_f32_e32 v38, v38, v39
	v_add_f32_e32 v1, v23, v31
	v_add_f32_e32 v106, v22, v1
	v_pk_mul_f32 v[22:23], v[46:47], v[44:45]
	v_add_f32_e32 v39, v49, v24
	v_add_f32_e32 v1, v23, v38
	v_add_f32_e32 v101, v22, v1
	ds_read_u16 v1, v199
	v_add_f32_e32 v110, v48, v39
	s_waitcnt lgkmcnt(0)
	v_lshlrev_b32_e32 v23, 16, v1
	ds_read_u16 v1, v199 offset:144
	ds_read_u16 v22, v199 offset:288
	ds_read_u16 v24, v199 offset:432
	ds_read_u16 v26, v199 offset:576
	ds_read_u16 v28, v199 offset:720
	ds_read_u16 v31, v199 offset:864
	s_waitcnt lgkmcnt(3)
	v_lshlrev_b32_e32 v43, 16, v24
	v_mov_b32_e32 v24, v27
	v_lshlrev_b32_e32 v27, 16, v1
	s_waitcnt lgkmcnt(2)
	v_lshlrev_b32_e32 v42, 16, v26
	v_lshlrev_b32_e32 v26, 16, v22
	v_mov_b32_e32 v22, v27
	v_pk_mul_f32 v[22:23], v[24:25], v[22:23]
	s_nop 0
	v_add_f32_e32 v1, v23, v41
	v_add_f32_e32 v1, v22, v1
	v_pk_mul_f32 v[22:23], v[24:25], v[26:27]
	s_nop 0
	v_add_f32_e32 v23, v23, v41
	v_add_f32_e32 v36, v22, v23
	v_pk_mov_b32 v[22:23], v[42:43], v[26:27] op_sel:[1,0]
	s_nop 0
	v_pk_mul_f32 v[26:27], v[24:25], v[22:23]
	v_pk_mul_f32 v[24:25], v[24:25], v[42:43]
	v_add_f32_e32 v27, v27, v41
	v_add_f32_e32 v25, v25, v41
	v_add_f32_e32 v26, v26, v27
	v_add_f32_e32 v27, v24, v25
	s_waitcnt lgkmcnt(1)
	v_lshlrev_b32_e32 v25, 16, v28
	v_mov_b32_e32 v28, v37
	v_pk_mul_f32 v[64:65], v[28:29], v[22:23]
	v_pk_mul_f32 v[22:23], v[28:29], v[42:43]
	s_waitcnt lgkmcnt(0)
	v_lshlrev_b32_e32 v24, 16, v31
	v_add_f32_e32 v57, v65, v1
	v_add_f32_e32 v1, v23, v36
	v_add_f32_e32 v120, v22, v1
	v_pk_mov_b32 v[22:23], v[24:25], v[42:43] op_sel:[1,0]
	v_add_f32_e32 v122, v64, v57
	v_pk_mul_f32 v[22:23], v[28:29], v[22:23]
	s_nop 0
	v_add_f32_e32 v1, v23, v26
	v_add_f32_e32 v118, v22, v1
	v_pk_mul_f32 v[22:23], v[28:29], v[24:25]
	s_nop 0
	v_add_f32_e32 v1, v23, v27
	v_add_f32_e32 v113, v22, v1
	ds_read_u16 v1, v200
	s_waitcnt lgkmcnt(0)
	v_lshlrev_b32_e32 v23, 16, v1
	ds_read_u16 v1, v200 offset:144
	ds_read_u16 v22, v200 offset:288
	ds_read_u16 v31, v200 offset:432
	ds_read_u16 v38, v200 offset:576
	ds_read_u16 v49, v200 offset:720
	ds_read_u16 v52, v200 offset:864
	ds_read2_b32 v[24:25], v50 offset0:160 offset1:176
	ds_read2_b32 v[26:27], v50 offset0:224 offset1:240
	ds_read2_b32 v[28:29], v51 offset0:32 offset1:48
	ds_read2_b32 v[36:37], v51 offset0:96 offset1:112
	ds_read2_b32 v[40:41], v51 offset0:160 offset1:176
	s_waitcnt lgkmcnt(10)
	v_lshlrev_b32_e32 v47, 16, v1
	s_waitcnt lgkmcnt(3)
	v_mov_b32_e32 v44, v26
	v_mov_b32_e32 v45, v24
	v_lshlrev_b32_e32 v46, 16, v22
	v_mov_b32_e32 v22, v47
	v_pk_mul_f32 v[22:23], v[44:45], v[22:23]
	v_lshlrev_b32_e32 v43, 16, v31
	s_waitcnt lgkmcnt(0)
; #define LAS __attribute__((address_space(3)))
; #define MFMA16(a, b, c) __builtin_amdgcn_mfma_f32_16x16x32_bf16(a, b, c, 0, 0, 0)
; template <bool PHASE_B>
; __device__ __forceinline__ void lru_item(const Params& p, LAS unsigned char* lds, int ci, int ci_next, int jb, const int tid, v4u (&xvn)[3]) {
;     ...
;     for (int ct = 0; ct < 4; ++ct) { const int ch = 16 * ct + fr; float xr7[7];
; #pragma unroll
;         for (int j = 0; j < 7; ++j) xr7[j] = __builtin_bit_cast(float, (unsigned)(*(const LAS bf16*)(lds + LR_XR + (16 * rt + 4 * fq + j) * 144 + ch * 2)) << 16);
;         const float w0 = CW[ch], w1 = CW[64 + ch], w2 = CW[128 + ch], w3 = CW[192 + ch], b = CB[ch];
; #pragma unroll
;         for (int e = 0; e < 4; ++e) xc[ct][e] = b + xr7[e] * w0 + xr7[e + 1] * w1 + xr7[e + 2] * w2 + xr7[e + 3] * w3; }
;     float av[2][4][4], uv[2][4][4], pA[2][4], pH[2][4];
; #pragma unroll
;     for (int dir = 0; dir < 2; ++dir) {
; #pragma unroll
;         for (int ct = 0; ct < 4; ++ct) {
;             f32x4 ga = (f32x4){0.f, 0.f, 0.f, 0.f}, gx = (f32x4){0.f, 0.f, 0.f, 0.f};
; #pragma unroll
;             for (int ks = 0; ks < 2; ++ks) {
;                 const bf16x8 wa = *(const LAS bf16x8*)(lds + LR_WG + ((dir * 2 + 0) * 64 + 16 * ct + fr) * 144 + (32 * ks + 8 * fq) * 2);
;                 const bf16x8 wx = *(const LAS bf16x8*)(lds + LR_WG + ((dir * 2 + 1) * 64 + 16 * ct + fr) * 144 + (32 * ks + 8 * fq) * 2);
;                 ga = MFMA16(af[ks], wa, ga); gx = MFMA16(af[ks], wx, gx); }
;             const int ch = 16 * ct + fr; const float bav = GC[(dir * 3 + 0) * 64 + ch], bxv = GC[(dir * 3 + 1) * 64 + ch], c8 = GC[(dir * 3 + 2) * 64 + ch];
;             float Al = 1.f, Hl = 0.f;
; #pragma unroll
;             for (int ee = 0; ee < 4; ++ee) { const int e = dir ? 3 - ee : ee;
;                 const float r = __builtin_amdgcn_rcpf(1.f + __expf(-(ga[e] + bav))), ig = __builtin_amdgcn_rcpf(1.f + __expf(-(gx[e] + bxv)));
;                 const float la = -c8 * r; const float a = __expf(la); const float u = __builtin_amdgcn_sqrtf((1.f - a) * (1.f + a)) * (ig * xc[ct][e]);
;                 av[dir][ct][e] = a; uv[dir][ct][e] = u; Hl = a * Hl + u; Al *= a; }
	v_add_f32_e32 v1, v23, v40
	v_add_f32_e32 v1, v22, v1
	v_pk_mul_f32 v[22:23], v[44:45], v[46:47]
	v_lshlrev_b32_e32 v42, 16, v38
	v_add_f32_e32 v23, v23, v40
	v_add_f32_e32 v24, v22, v23
	v_pk_mov_b32 v[22:23], v[42:43], v[46:47] op_sel:[1,0]
	v_mov_b32_e32 v50, v36
	v_pk_mul_f32 v[46:47], v[44:45], v[22:23]
	v_pk_mul_f32 v[44:45], v[44:45], v[42:43]
	v_mov_b32_e32 v51, v28
	v_add_f32_e32 v31, v45, v40
	v_add_f32_e32 v26, v47, v40
	v_add_f32_e32 v31, v44, v31
	v_pk_mul_f32 v[44:45], v[50:51], v[22:23]
	v_pk_mul_f32 v[22:23], v[50:51], v[42:43]
	v_add_f32_e32 v26, v46, v26
	v_lshlrev_b32_e32 v47, 16, v49
	v_lshlrev_b32_e32 v46, 16, v52
	v_add_f32_e32 v45, v45, v1
	v_add_f32_e32 v1, v23, v24
	v_add_f32_e32 v130, v22, v1
	v_pk_mov_b32 v[22:23], v[46:47], v[42:43] op_sel:[1,0]
	s_nop 0
	v_pk_mul_f32 v[22:23], v[50:51], v[22:23]
	s_nop 0
	v_add_f32_e32 v1, v23, v26
	v_add_f32_e32 v128, v22, v1
	v_pk_mul_f32 v[22:23], v[50:51], v[46:47]
	s_nop 0
	v_add_f32_e32 v1, v23, v31
	v_add_f32_e32 v125, v22, v1
	ds_read_u16 v1, v201
	s_waitcnt lgkmcnt(0)
	v_lshlrev_b32_e32 v23, 16, v1
	ds_read_u16 v1, v201 offset:144
	ds_read_u16 v22, v201 offset:288
	ds_read_u16 v24, v201 offset:432
	ds_read_u16 v26, v201 offset:576
	ds_read_u16 v28, v201 offset:720
	ds_read_u16 v31, v201 offset:864
	s_waitcnt lgkmcnt(3)
	v_lshlrev_b32_e32 v43, 16, v24
	v_mov_b32_e32 v24, v27
	v_lshlrev_b32_e32 v27, 16, v1
	s_waitcnt lgkmcnt(2)
	v_lshlrev_b32_e32 v42, 16, v26
	v_lshlrev_b32_e32 v26, 16, v22
	v_mov_b32_e32 v22, v27
	v_pk_mul_f32 v[22:23], v[24:25], v[22:23]
	s_nop 0
	v_add_f32_e32 v1, v23, v41
	v_add_f32_e32 v1, v22, v1
	v_pk_mul_f32 v[22:23], v[24:25], v[26:27]
	s_nop 0
	v_add_f32_e32 v23, v23, v41
	v_add_f32_e32 v38, v22, v23
	v_pk_mov_b32 v[22:23], v[42:43], v[26:27] op_sel:[1,0]
	s_nop 0
	v_pk_mul_f32 v[26:27], v[24:25], v[22:23]
	v_pk_mul_f32 v[24:25], v[24:25], v[42:43]
	v_add_f32_e32 v27, v27, v41
	v_add_f32_e32 v25, v25, v41
	v_add_f32_e32 v26, v26, v27
	v_add_f32_e32 v27, v24, v25
	s_waitcnt lgkmcnt(1)
	v_lshlrev_b32_e32 v25, 16, v28
	v_mov_b32_e32 v28, v37
	v_pk_mul_f32 v[36:37], v[28:29], v[22:23]
	v_pk_mul_f32 v[22:23], v[28:29], v[42:43]
	s_waitcnt lgkmcnt(0)
	v_lshlrev_b32_e32 v24, 16, v31
	v_add_f32_e32 v37, v37, v1
	v_add_f32_e32 v1, v23, v38
	v_add_f32_e32 v31, v22, v1
	v_pk_mov_b32 v[22:23], v[24:25], v[42:43] op_sel:[1,0]
	s_nop 0
	v_pk_mul_f32 v[22:23], v[28:29], v[22:23]
	s_nop 0
	v_add_f32_e32 v1, v23, v26
	v_add_f32_e32 v136, v22, v1
	v_pk_mul_f32 v[22:23], v[28:29], v[24:25]
	s_nop 0
	v_add_f32_e32 v1, v23, v27
	v_add_f32_e32 v133, v22, v1
	ds_read_b128 v[22:25], v132 offset:18944
	ds_read_b128 v[26:29], v132 offset:28160
	s_waitcnt lgkmcnt(1)
	v_mfma_f32_16x16x32_bf16 v[22:25], v[14:17], v[22:25], 0
	s_waitcnt lgkmcnt(0)
	v_mfma_f32_16x16x32_bf16 v[40:43], v[14:17], v[26:29], 0
	ds_read_b128 v[26:29], v132 offset:19008
	ds_read_b128 v[50:53], v132 offset:28224
	ds_read_b32 v49, v174 offset:57088
	ds_read_b32 v47, v174 offset:57344
	ds_read_b32 v46, v174 offset:57600
	s_waitcnt lgkmcnt(4)
	v_mfma_f32_16x16x32_bf16 v[26:29], v[18:21], v[26:29], v[22:25]
	s_waitcnt lgkmcnt(3)
	v_mfma_f32_16x16x32_bf16 v[22:25], v[18:21], v[50:53], v[40:43]
	ds_read_b32 v227, v174 offset:57152
	ds_read_b32 v228, v174 offset:57408
	ds_read_b32 v229, v174 offset:57664
	ds_read_b128 v[208:211], v132 offset:21248
	ds_read_b128 v[212:215], v132 offset:30464
	ds_read_b128 v[216:219], v132 offset:21312
	ds_read_b128 v[220:223], v132 offset:30528
	s_waitcnt lgkmcnt(2)
	s_nop 4
	v_add_f32_e32 v1, v26, v49
	v_mul_f32_e32 v1, 0xbfb8aa3b, v1
	v_exp_f32_e32 v1, v1
	s_nop 0
	v_add_f32_e32 v1, 1.0, v1
	v_rcp_f32_e32 v1, v1
	s_waitcnt lgkmcnt(1)
	v_add_f32_e32 v22, v22, v47
	v_mul_f32_e32 v22, 0xbfb8aa3b, v22
	v_exp_f32_e32 v22, v22
	s_waitcnt lgkmcnt(0)
	v_mul_f32_e32 v1, v1, v46
	v_mul_f32_e32 v1, 0xbfb8aa3b, v1
	v_exp_f32_e32 v38, v1
	v_add_f32_e32 v22, 1.0, v22
	v_rcp_f32_e32 v50, v22
	v_add_f32_e32 v23, v23, v47
	v_sub_f32_e32 v1, 1.0, v38
	v_add_f32_e32 v22, 1.0, v38
	v_mul_f32_e32 v1, v1, v22
	v_add_f32_e32 v22, v27, v49
	v_mul_f32_e32 v22, 0xbfb8aa3b, v22
	v_exp_f32_e32 v22, v22
	v_mul_f32_e32 v23, 0xbfb8aa3b, v23
	v_exp_f32_e32 v23, v23
	v_add_f32_e32 v24, v24, v47
	v_add_f32_e32 v22, 1.0, v22
	v_rcp_f32_e32 v22, v22
	v_add_f32_e32 v23, 1.0, v23
	v_rcp_f32_e32 v23, v23
	v_add_f32_e32 v25, v25, v47
	v_mul_f32_e32 v22, v22, v46
	v_mul_f32_e32 v22, 0xbfb8aa3b, v22
	v_exp_f32_e32 v41, v22
	v_mul_f32_e32 v24, 0xbfb8aa3b, v24
	v_mul_f32_e32 v25, 0xbfb8aa3b, v25
	v_sqrt_f32_e32 v1, v1
	v_sub_f32_e32 v22, 1.0, v41
	v_add_f32_e32 v26, 1.0, v41
	v_mul_f32_e32 v22, v22, v26
	v_add_f32_e32 v26, v28, v49
	v_mul_f32_e32 v26, 0xbfb8aa3b, v26
	v_exp_f32_e32 v26, v26
	v_sqrt_f32_e32 v40, v22
	v_mul_f32_e32 v22, v108, v23
	v_mul_f32_e32 v23, v38, v41
	v_add_f32_e32 v26, 1.0, v26
	v_rcp_f32_e32 v26, v26
	v_exp_f32_e32 v24, v24
	v_exp_f32_e32 v25, v25
	v_mul_f32_e32 v39, v110, v50
	v_mul_f32_e32 v26, v26, v46
	v_mul_f32_e32 v26, 0xbfb8aa3b, v26
	v_exp_f32_e32 v43, v26
	v_add_f32_e32 v24, 1.0, v24
	v_add_f32_e32 v25, 1.0, v25
	v_rcp_f32_e32 v24, v24
	v_sub_f32_e32 v26, 1.0, v43
	v_add_f32_e32 v27, 1.0, v43
	v_mul_f32_e32 v26, v26, v27
	v_sqrt_f32_e32 v42, v26
	v_add_f32_e32 v26, v29, v49
	v_mul_f32_e32 v26, 0xbfb8aa3b, v26
	v_exp_f32_e32 v26, v26
	v_mul_f32_e32 v23, v43, v23
	v_pk_mul_f32 v[48:49], v[38:39], v[0:1]
	v_rcp_f32_e32 v25, v25
	v_add_f32_e32 v26, 1.0, v26
	v_rcp_f32_e32 v26, v26
	v_pk_fma_f32 v[50:51], v[38:39], v[0:1], v[48:49] op_sel_hi:[1,1,0]
	v_mul_f32_e32 v24, v106, v24
	v_mul_f32_e32 v26, v26, v46
	v_mul_f32_e32 v26, 0xbfb8aa3b, v26
	v_exp_f32_e32 v47, v26
	s_nop 0
	v_mul_f32_e32 v29, v47, v23
	ds_bpermute_b32 v56, v171, v29
	v_sub_f32_e32 v26, 1.0, v47
	v_add_f32_e32 v27, 1.0, v47
	v_mul_f32_e32 v26, v26, v27
	v_sqrt_f32_e32 v46, v26
	s_waitcnt lgkmcnt(0)
; #define LAS __attribute__((address_space(3)))
; #define MFMA16(a, b, c) __builtin_amdgcn_mfma_f32_16x16x32_bf16(a, b, c, 0, 0, 0)
; template <bool PHASE_B>
; __device__ __forceinline__ void lru_item(const Params& p, LAS unsigned char* lds, int ci, int ci_next, int jb, const int tid, v4u (&xvn)[3]) {
;     ...
;                 const bf16x8 wa = *(const LAS bf16x8*)(lds + LR_WG + ((dir * 2 + 0) * 64 + 16 * ct + fr) * 144 + (32 * ks + 8 * fq) * 2);
;                 const bf16x8 wx = *(const LAS bf16x8*)(lds + LR_WG + ((dir * 2 + 1) * 64 + 16 * ct + fr) * 144 + (32 * ks + 8 * fq) * 2);
;                 ga = MFMA16(af[ks], wa, ga); gx = MFMA16(af[ks], wx, gx); }
;             const int ch = 16 * ct + fr; const float bav = GC[(dir * 3 + 0) * 64 + ch], bxv = GC[(dir * 3 + 1) * 64 + ch], c8 = GC[(dir * 3 + 2) * 64 + ch];
;             float Al = 1.f, Hl = 0.f;
; #pragma unroll
;             for (int ee = 0; ee < 4; ++ee) { const int e = dir ? 3 - ee : ee;
;                 const float r = __builtin_amdgcn_rcpf(1.f + __expf(-(ga[e] + bav))), ig = __builtin_amdgcn_rcpf(1.f + __expf(-(gx[e] + bxv)));
;                 const float la = -c8 * r; const float a = __expf(la); const float u = __builtin_amdgcn_sqrtf((1.f - a) * (1.f + a)) * (ig * xc[ct][e]);
;                 av[dir][ct][e] = a; uv[dir][ct][e] = u; Hl = a * Hl + u; Al *= a; }
;             const int o = dir ? 3 - fq : fq; const bool odd = (o & 1) != 0, hi2 = (o & 2) != 0;
;             const float A1 = __shfl_xor(Al, 16), H1 = __shfl_xor(Hl, 16);
;             const float pxA = odd ? A1 : 1.f, pxH = odd ? H1 : 0.f;
;             const float gA = Al * A1, gH = odd ? (Al * H1 + Hl) : (A1 * Hl + H1);
;             const float A2 = __shfl_xor(gA, 32), H2 = __shfl_xor(gH, 32);
;             const float PA = hi2 ? pxA * A2 : pxA, PH = hi2 ? (pxA * H2 + pxH) : pxH;
;             const float TA = gA * A2, TH = hi2 ? (gA * H2 + gH) : (A2 * gH + H2);
;             pA[dir][ct] = PA; pH[dir][ct] = PH;
;             ((LAS f32x2*)(lds + LR_SEG))[(dir * 8 + rt) * 64 + ch] = (f32x2){TA, TH};
	v_mul_f32_e32 v59, v29, v56
	ds_bpermute_b32 v60, v172, v59
	v_cndmask_b32_e64 v58, v56, 1.0, s[50:51]
	v_mul_f32_e32 v26, v101, v25
	s_waitcnt lgkmcnt(0)
	v_mul_f32_e32 v23, v58, v60
	v_cndmask_b32_e64 v206, v23, v58, s[52:53]
	v_mov_b32_e32 v23, v51
	v_pk_mul_f32 v[50:51], v[22:23], v[40:41]
	v_mul_f32_e32 v28, v59, v60
	v_pk_fma_f32 v[22:23], v[22:23], v[40:41], v[50:51] op_sel_hi:[1,1,0]
	s_nop 0
	v_mov_b32_e32 v25, v23
	v_pk_mul_f32 v[52:53], v[24:25], v[42:43]
	s_nop 0
	v_pk_fma_f32 v[22:23], v[24:25], v[42:43], v[52:53] op_sel_hi:[1,1,0]
	s_nop 0
	v_mov_b32_e32 v27, v23
	v_pk_mul_f32 v[54:55], v[26:27], v[46:47]
	s_nop 0
	v_add_f32_e32 v1, v54, v55
	ds_bpermute_b32 v22, v171, v1
	s_waitcnt lgkmcnt(0)
	v_cndmask_b32_e64 v23, v22, 0, s[50:51]
	v_fma_f32 v24, v29, v22, v1
	v_fmac_f32_e32 v22, v1, v56
	v_cndmask_b32_e64 v1, v24, v22, s[50:51]
	ds_bpermute_b32 v22, v172, v1
	s_waitcnt lgkmcnt(0)
	v_fma_f32 v24, v58, v22, v23
	v_cndmask_b32_e64 v39, v24, v23, s[52:53]
	v_fma_f32 v23, v59, v22, v1
	v_fmac_f32_e32 v22, v1, v60
	v_cndmask_b32_e64 v29, v23, v22, s[52:53]
	ds_write_b64 v175, v[28:29] offset:58624
	s_waitcnt lgkmcnt(1)
	v_mfma_f32_16x16x32_bf16 v[22:25], v[14:17], v[208:211], 0
	s_waitcnt lgkmcnt(0)
	v_mfma_f32_16x16x32_bf16 v[58:61], v[14:17], v[212:215], 0
	s_waitcnt lgkmcnt(4)
	v_mfma_f32_16x16x32_bf16 v[26:29], v[18:21], v[216:219], v[22:25]
	s_waitcnt lgkmcnt(3)
	v_mfma_f32_16x16x32_bf16 v[22:25], v[18:21], v[220:223], v[58:61]
	ds_read_b128 v[208:211], v132 offset:23552
	ds_read_b128 v[212:215], v132 offset:32768
	ds_read_b128 v[216:219], v132 offset:23616
	ds_read_b128 v[220:223], v132 offset:32832
	s_waitcnt lgkmcnt(2)
	s_nop 4
	v_add_f32_e32 v1, v26, v227
	v_mul_f32_e32 v1, 0xbfb8aa3b, v1
	v_exp_f32_e32 v1, v1
	s_nop 0
	v_add_f32_e32 v1, 1.0, v1
	v_rcp_f32_e32 v1, v1
	s_waitcnt lgkmcnt(1)
	v_add_f32_e32 v22, v22, v228
	v_mul_f32_e32 v22, 0xbfb8aa3b, v22
	v_exp_f32_e32 v22, v22
	s_waitcnt lgkmcnt(0)
	v_mul_f32_e32 v1, v1, v229
	v_mul_f32_e32 v1, 0xbfb8aa3b, v1
	v_exp_f32_e32 v56, v1
	v_add_f32_e32 v22, 1.0, v22
	v_rcp_f32_e32 v48, v22
	v_add_f32_e32 v23, v23, v228
	v_sub_f32_e32 v1, 1.0, v56
	v_add_f32_e32 v22, 1.0, v56
	v_mul_f32_e32 v1, v1, v22
	v_add_f32_e32 v22, v27, v227
	v_mul_f32_e32 v22, 0xbfb8aa3b, v22
	v_exp_f32_e32 v22, v22
	v_mul_f32_e32 v23, 0xbfb8aa3b, v23
	v_exp_f32_e32 v23, v23
	v_add_f32_e32 v24, v24, v228
	v_add_f32_e32 v22, 1.0, v22
	v_rcp_f32_e32 v22, v22
	v_add_f32_e32 v23, 1.0, v23
	v_rcp_f32_e32 v23, v23
	v_add_f32_e32 v25, v25, v228
	v_mul_f32_e32 v22, v22, v229
	v_mul_f32_e32 v22, 0xbfb8aa3b, v22
	v_exp_f32_e32 v59, v22
	v_mul_f32_e32 v24, 0xbfb8aa3b, v24
	v_mul_f32_e32 v25, 0xbfb8aa3b, v25
	v_sqrt_f32_e32 v1, v1
	v_sub_f32_e32 v22, 1.0, v59
	v_add_f32_e32 v26, 1.0, v59
	v_mul_f32_e32 v22, v22, v26
	v_add_f32_e32 v26, v28, v227
	v_mul_f32_e32 v26, 0xbfb8aa3b, v26
	v_exp_f32_e32 v26, v26
	v_sqrt_f32_e32 v58, v22
	v_mul_f32_e32 v22, v120, v23
	v_mul_f32_e32 v23, v56, v59
	v_add_f32_e32 v26, 1.0, v26
	v_rcp_f32_e32 v26, v26
	v_exp_f32_e32 v24, v24
	v_exp_f32_e32 v25, v25
	v_mul_f32_e32 v57, v122, v48
	v_mul_f32_e32 v26, v26, v229
	v_mul_f32_e32 v26, 0xbfb8aa3b, v26
	v_exp_f32_e32 v61, v26
	v_add_f32_e32 v24, 1.0, v24
	v_add_f32_e32 v25, 1.0, v25
	v_pk_mul_f32 v[64:65], v[56:57], v[0:1]
	v_sub_f32_e32 v26, 1.0, v61
	v_add_f32_e32 v27, 1.0, v61
	v_mul_f32_e32 v26, v26, v27
	v_sqrt_f32_e32 v60, v26
	v_add_f32_e32 v26, v29, v227
	v_mul_f32_e32 v26, 0xbfb8aa3b, v26
	v_exp_f32_e32 v26, v26
	v_mul_f32_e32 v23, v61, v23
	v_rcp_f32_e32 v24, v24
	v_rcp_f32_e32 v25, v25
	v_add_f32_e32 v26, 1.0, v26
	v_rcp_f32_e32 v26, v26
	v_pk_fma_f32 v[66:67], v[56:57], v[0:1], v[64:65] op_sel_hi:[1,1,0]
	v_mul_f32_e32 v24, v118, v24
	v_mul_f32_e32 v26, v26, v229
	v_mul_f32_e32 v26, 0xbfb8aa3b, v26
	v_exp_f32_e32 v63, v26
	s_nop 0
	v_mul_f32_e32 v29, v63, v23
	ds_bpermute_b32 v42, v171, v29
	v_sub_f32_e32 v26, 1.0, v63
	v_add_f32_e32 v27, 1.0, v63
	v_mul_f32_e32 v26, v26, v27
	v_sqrt_f32_e32 v62, v26
	s_waitcnt lgkmcnt(0)
	v_mul_f32_e32 v51, v29, v42
	ds_bpermute_b32 v53, v172, v51
	v_cndmask_b32_e64 v46, v42, 1.0, s[50:51]
	v_mul_f32_e32 v26, v113, v25
	s_waitcnt lgkmcnt(0)
	v_mul_f32_e32 v23, v46, v53
	v_cndmask_b32_e64 v40, v23, v46, s[52:53]
	v_mov_b32_e32 v23, v67
	v_pk_mul_f32 v[66:67], v[22:23], v[58:59]
	v_mul_f32_e32 v28, v51, v53
	v_pk_fma_f32 v[22:23], v[22:23], v[58:59], v[66:67] op_sel_hi:[1,1,0]
	s_nop 0
	v_mov_b32_e32 v25, v23
	v_pk_mul_f32 v[68:69], v[24:25], v[60:61]
	s_nop 0
	v_pk_fma_f32 v[22:23], v[24:25], v[60:61], v[68:69] op_sel_hi:[1,1,0]
	v_add_f32_e32 v69, v44, v45
	v_mov_b32_e32 v27, v23
	v_pk_mul_f32 v[70:71], v[26:27], v[62:63]
	s_nop 0
	v_add_f32_e32 v1, v70, v71
	ds_bpermute_b32 v22, v171, v1
	v_add_f32_e32 v71, v36, v37
	s_waitcnt lgkmcnt(0)
	v_cndmask_b32_e64 v23, v22, 0, s[50:51]
	v_fma_f32 v24, v29, v22, v1
	v_fmac_f32_e32 v22, v1, v42
	v_cndmask_b32_e64 v1, v24, v22, s[50:51]
	ds_bpermute_b32 v22, v172, v1
	s_waitcnt lgkmcnt(0)
	v_fma_f32 v24, v46, v22, v23
	v_cndmask_b32_e64 v42, v24, v23, s[52:53]
	v_fma_f32 v23, v51, v22, v1
	v_fmac_f32_e32 v22, v1, v53
	v_cndmask_b32_e64 v29, v23, v22, s[52:53]
	ds_write_b64 v175, v[28:29] offset:58752
	s_waitcnt lgkmcnt(1)
	v_mfma_f32_16x16x32_bf16 v[22:25], v[14:17], v[208:211], 0
	s_waitcnt lgkmcnt(2)
	v_mfma_f32_16x16x32_bf16 v[26:29], v[14:17], v[212:215], 0
	s_waitcnt lgkmcnt(1)
	v_mfma_f32_16x16x32_bf16 v[80:83], v[18:21], v[216:219], v[22:25]
	s_waitcnt lgkmcnt(0)
; #define LAS __attribute__((address_space(3)))
; #define MFMA16(a, b, c) __builtin_amdgcn_mfma_f32_16x16x32_bf16(a, b, c, 0, 0, 0)
; template <bool PHASE_B>
; __device__ __forceinline__ void lru_item(const Params& p, LAS unsigned char* lds, int ci, int ci_next, int jb, const int tid, v4u (&xvn)[3]) {
;     ...
;                 const bf16x8 wa = *(const LAS bf16x8*)(lds + LR_WG + ((dir * 2 + 0) * 64 + 16 * ct + fr) * 144 + (32 * ks + 8 * fq) * 2);
;                 const bf16x8 wx = *(const LAS bf16x8*)(lds + LR_WG + ((dir * 2 + 1) * 64 + 16 * ct + fr) * 144 + (32 * ks + 8 * fq) * 2);
;                 ga = MFMA16(af[ks], wa, ga); gx = MFMA16(af[ks], wx, gx); }
;             const int ch = 16 * ct + fr; const float bav = GC[(dir * 3 + 0) * 64 + ch], bxv = GC[(dir * 3 + 1) * 64 + ch], c8 = GC[(dir * 3 + 2) * 64 + ch];
;             float Al = 1.f, Hl = 0.f;
; #pragma unroll
;             for (int ee = 0; ee < 4; ++ee) { const int e = dir ? 3 - ee : ee;
;                 const float r = __builtin_amdgcn_rcpf(1.f + __expf(-(ga[e] + bav))), ig = __builtin_amdgcn_rcpf(1.f + __expf(-(gx[e] + bxv)));
;                 const float la = -c8 * r; const float a = __expf(la); const float u = __builtin_amdgcn_sqrtf((1.f - a) * (1.f + a)) * (ig * xc[ct][e]);
;                 av[dir][ct][e] = a; uv[dir][ct][e] = u; Hl = a * Hl + u; Al *= a; }
;             const int o = dir ? 3 - fq : fq; const bool odd = (o & 1) != 0, hi2 = (o & 2) != 0;
;             const float A1 = __shfl_xor(Al, 16), H1 = __shfl_xor(Hl, 16);
;             const float pxA = odd ? A1 : 1.f, pxH = odd ? H1 : 0.f;
;             const float gA = Al * A1, gH = odd ? (Al * H1 + Hl) : (A1 * Hl + H1);
;             const float A2 = __shfl_xor(gA, 32), H2 = __shfl_xor(gH, 32);
;             const float PA = hi2 ? pxA * A2 : pxA, PH = hi2 ? (pxA * H2 + pxH) : pxH;
;             const float TA = gA * A2, TH = hi2 ? (gA * H2 + gH) : (A2 * gH + H2);
;             pA[dir][ct] = PA; pH[dir][ct] = PH;
;             ((LAS f32x2*)(lds + LR_SEG))[(dir * 8 + rt) * 64 + ch] = (f32x2){TA, TH};
	v_mfma_f32_16x16x32_bf16 v[22:25], v[18:21], v[220:223], v[26:29]
	ds_read_b32 v224, v174 offset:57216
	ds_read_b32 v225, v174 offset:57472
	ds_read_b32 v226, v174 offset:57728
	ds_read_b128 v[208:211], v132 offset:25856
	ds_read_b128 v[212:215], v132 offset:35072
	ds_read_b128 v[216:219], v132 offset:25920
	ds_read_b128 v[220:223], v132 offset:35136
	s_nop 3
	s_waitcnt lgkmcnt(2)
	v_add_f32_e32 v1, v80, v224
	v_mul_f32_e32 v1, 0xbfb8aa3b, v1
	v_exp_f32_e32 v1, v1
	s_waitcnt lgkmcnt(1)
	v_add_f32_e32 v22, v22, v225
	v_mul_f32_e32 v22, 0xbfb8aa3b, v22
	v_exp_f32_e32 v22, v22
	v_add_f32_e32 v1, 1.0, v1
	v_rcp_f32_e32 v1, v1
	v_add_f32_e32 v23, v23, v225
	v_add_f32_e32 v22, 1.0, v22
	v_rcp_f32_e32 v29, v22
	s_waitcnt lgkmcnt(0)
	v_mul_f32_e32 v1, v1, v226
	v_mul_f32_e32 v1, 0xbfb8aa3b, v1
	v_exp_f32_e32 v72, v1
	v_mul_f32_e32 v23, 0xbfb8aa3b, v23
	v_exp_f32_e32 v23, v23
	v_add_f32_e32 v24, v24, v225
	v_sub_f32_e32 v1, 1.0, v72
	v_add_f32_e32 v22, 1.0, v72
	v_mul_f32_e32 v1, v1, v22
	v_add_f32_e32 v22, v81, v224
	v_mul_f32_e32 v22, 0xbfb8aa3b, v22
	v_exp_f32_e32 v22, v22
	v_add_f32_e32 v23, 1.0, v23
	v_rcp_f32_e32 v23, v23
	v_add_f32_e32 v25, v25, v225
	v_add_f32_e32 v22, 1.0, v22
	v_rcp_f32_e32 v22, v22
	v_mul_f32_e32 v24, 0xbfb8aa3b, v24
	v_mul_f32_e32 v25, 0xbfb8aa3b, v25
	v_sqrt_f32_e32 v1, v1
	v_mul_f32_e32 v22, v22, v226
	v_mul_f32_e32 v22, 0xbfb8aa3b, v22
	v_exp_f32_e32 v75, v22
	v_exp_f32_e32 v24, v24
	v_exp_f32_e32 v25, v25
	v_mul_f32_e32 v73, v69, v29
	v_sub_f32_e32 v22, 1.0, v75
	v_add_f32_e32 v46, 1.0, v75
	v_mul_f32_e32 v22, v22, v46
	v_add_f32_e32 v46, v82, v224
	v_mul_f32_e32 v46, 0xbfb8aa3b, v46
	v_add_f32_e32 v26, v83, v224
	v_exp_f32_e32 v46, v46
	v_mul_f32_e32 v26, 0xbfb8aa3b, v26
	v_exp_f32_e32 v26, v26
	v_sqrt_f32_e32 v74, v22
	v_add_f32_e32 v46, 1.0, v46
	v_rcp_f32_e32 v46, v46
	v_add_f32_e32 v26, 1.0, v26
	v_rcp_f32_e32 v26, v26
	v_mul_f32_e32 v22, v130, v23
	v_mul_f32_e32 v46, v46, v226
	v_mul_f32_e32 v46, 0xbfb8aa3b, v46
	v_mul_f32_e32 v26, v26, v226
	v_exp_f32_e32 v77, v46
	v_mul_f32_e32 v26, 0xbfb8aa3b, v26
	v_exp_f32_e32 v79, v26
	v_mul_f32_e32 v23, v72, v75
	v_sub_f32_e32 v46, 1.0, v77
	v_add_f32_e32 v48, 1.0, v77
	v_mul_f32_e32 v23, v77, v23
	v_mul_f32_e32 v46, v46, v48
	v_mul_f32_e32 v48, v79, v23
	ds_bpermute_b32 v51, v171, v48
	v_add_f32_e32 v24, 1.0, v24
	v_add_f32_e32 v25, 1.0, v25
	v_pk_mul_f32 v[44:45], v[72:73], v[0:1]
	v_rcp_f32_e32 v24, v24
	s_waitcnt lgkmcnt(0)
	v_mul_f32_e32 v55, v48, v51
	ds_bpermute_b32 v57, v172, v55
	v_cndmask_b32_e64 v53, v51, 1.0, s[50:51]
	v_rcp_f32_e32 v25, v25
	v_pk_fma_f32 v[80:81], v[72:73], v[0:1], v[44:45] op_sel_hi:[1,1,0]
	v_sqrt_f32_e32 v76, v46
	s_waitcnt lgkmcnt(0)
	v_mul_f32_e32 v23, v53, v57
	v_cndmask_b32_e64 v46, v23, v53, s[52:53]
	v_mov_b32_e32 v23, v81
	v_sub_f32_e32 v26, 1.0, v79
	v_add_f32_e32 v27, 1.0, v79
	v_pk_mul_f32 v[80:81], v[22:23], v[74:75]
	v_mul_f32_e32 v26, v26, v27
	v_pk_fma_f32 v[22:23], v[22:23], v[74:75], v[80:81] op_sel_hi:[1,1,0]
	v_mul_f32_e32 v24, v128, v24
	v_sqrt_f32_e32 v78, v26
	v_mul_f32_e32 v26, v125, v25
	v_mov_b32_e32 v25, v23
	v_pk_mul_f32 v[82:83], v[24:25], v[76:77]
	v_mul_f32_e32 v28, v55, v57
	v_pk_fma_f32 v[22:23], v[24:25], v[76:77], v[82:83] op_sel_hi:[1,1,0]
	s_nop 0
	v_mov_b32_e32 v27, v23
	v_pk_mul_f32 v[84:85], v[26:27], v[78:79]
	s_nop 0
	v_add_f32_e32 v1, v84, v85
	ds_bpermute_b32 v22, v171, v1
	s_waitcnt lgkmcnt(0)
	v_cndmask_b32_e64 v23, v22, 0, s[50:51]
	v_fma_f32 v24, v48, v22, v1
	v_fmac_f32_e32 v22, v1, v51
	v_cndmask_b32_e64 v1, v24, v22, s[50:51]
	ds_bpermute_b32 v22, v172, v1
	s_waitcnt lgkmcnt(0)
	v_fma_f32 v24, v53, v22, v23
	v_cndmask_b32_e64 v44, v24, v23, s[52:53]
	v_fma_f32 v23, v55, v22, v1
	v_fmac_f32_e32 v22, v1, v57
	v_cndmask_b32_e64 v29, v23, v22, s[52:53]
	ds_write_b64 v175, v[28:29] offset:58880
	s_waitcnt lgkmcnt(1)
	v_mfma_f32_16x16x32_bf16 v[22:25], v[14:17], v[208:211], 0
	s_waitcnt lgkmcnt(2)
	v_mfma_f32_16x16x32_bf16 v[26:29], v[14:17], v[212:215], 0
	s_waitcnt lgkmcnt(1)
	v_mfma_f32_16x16x32_bf16 v[94:97], v[18:21], v[216:219], v[22:25]
	s_waitcnt lgkmcnt(0)
	v_mfma_f32_16x16x32_bf16 v[22:25], v[18:21], v[220:223], v[26:29]
	ds_read_b32 v227, v174 offset:57280
	ds_read_b32 v228, v174 offset:57536
	ds_read_b32 v229, v174 offset:57792
	ds_read_b128 v[208:211], v132 offset:37376
	ds_read_b128 v[212:215], v132 offset:46592
	ds_read_b128 v[216:219], v132 offset:37440
	ds_read_b128 v[220:223], v132 offset:46656
	s_nop 3
	s_waitcnt lgkmcnt(2)
	v_add_f32_e32 v1, v94, v227
	v_mul_f32_e32 v1, 0xbfb8aa3b, v1
	v_exp_f32_e32 v1, v1
	s_waitcnt lgkmcnt(1)
	v_add_f32_e32 v22, v22, v228
	v_mul_f32_e32 v22, 0xbfb8aa3b, v22
	v_exp_f32_e32 v22, v22
	v_add_f32_e32 v1, 1.0, v1
	v_rcp_f32_e32 v1, v1
	v_add_f32_e32 v23, v23, v228
	v_add_f32_e32 v22, 1.0, v22
	v_rcp_f32_e32 v29, v22
	s_waitcnt lgkmcnt(0)
; #define LAS __attribute__((address_space(3)))
; #define MFMA16(a, b, c) __builtin_amdgcn_mfma_f32_16x16x32_bf16(a, b, c, 0, 0, 0)
; template <bool PHASE_B>
; __device__ __forceinline__ void lru_item(const Params& p, LAS unsigned char* lds, int ci, int ci_next, int jb, const int tid, v4u (&xvn)[3]) {
;     ...
;                 const bf16x8 wa = *(const LAS bf16x8*)(lds + LR_WG + ((dir * 2 + 0) * 64 + 16 * ct + fr) * 144 + (32 * ks + 8 * fq) * 2);
;                 const bf16x8 wx = *(const LAS bf16x8*)(lds + LR_WG + ((dir * 2 + 1) * 64 + 16 * ct + fr) * 144 + (32 * ks + 8 * fq) * 2);
;                 ga = MFMA16(af[ks], wa, ga); gx = MFMA16(af[ks], wx, gx); }
;             const int ch = 16 * ct + fr; const float bav = GC[(dir * 3 + 0) * 64 + ch], bxv = GC[(dir * 3 + 1) * 64 + ch], c8 = GC[(dir * 3 + 2) * 64 + ch];
;             float Al = 1.f, Hl = 0.f;
; #pragma unroll
;             for (int ee = 0; ee < 4; ++ee) { const int e = dir ? 3 - ee : ee;
;                 const float r = __builtin_amdgcn_rcpf(1.f + __expf(-(ga[e] + bav))), ig = __builtin_amdgcn_rcpf(1.f + __expf(-(gx[e] + bxv)));
;                 const float la = -c8 * r; const float a = __expf(la); const float u = __builtin_amdgcn_sqrtf((1.f - a) * (1.f + a)) * (ig * xc[ct][e]);
;                 av[dir][ct][e] = a; uv[dir][ct][e] = u; Hl = a * Hl + u; Al *= a; }
;             const int o = dir ? 3 - fq : fq; const bool odd = (o & 1) != 0, hi2 = (o & 2) != 0;
;             const float A1 = __shfl_xor(Al, 16), H1 = __shfl_xor(Hl, 16);
;             const float pxA = odd ? A1 : 1.f, pxH = odd ? H1 : 0.f;
;             const float gA = Al * A1, gH = odd ? (Al * H1 + Hl) : (A1 * Hl + H1);
;             const float A2 = __shfl_xor(gA, 32), H2 = __shfl_xor(gH, 32);
;             const float PA = hi2 ? pxA * A2 : pxA, PH = hi2 ? (pxA * H2 + pxH) : pxH;
;             const float TA = gA * A2, TH = hi2 ? (gA * H2 + gH) : (A2 * gH + H2);
;             pA[dir][ct] = PA; pH[dir][ct] = PH;
;             ((LAS f32x2*)(lds + LR_SEG))[(dir * 8 + rt) * 64 + ch] = (f32x2){TA, TH};
	v_mul_f32_e32 v1, v1, v229
	v_mul_f32_e32 v1, 0xbfb8aa3b, v1
	v_exp_f32_e32 v86, v1
	v_mul_f32_e32 v23, 0xbfb8aa3b, v23
	v_exp_f32_e32 v23, v23
	v_add_f32_e32 v24, v24, v228
	v_sub_f32_e32 v1, 1.0, v86
	v_add_f32_e32 v22, 1.0, v86
	v_mul_f32_e32 v1, v1, v22
	v_add_f32_e32 v22, v95, v227
	v_mul_f32_e32 v22, 0xbfb8aa3b, v22
	v_exp_f32_e32 v22, v22
	v_add_f32_e32 v23, 1.0, v23
	v_rcp_f32_e32 v23, v23
	v_add_f32_e32 v25, v25, v228
	v_add_f32_e32 v22, 1.0, v22
	v_rcp_f32_e32 v22, v22
	v_mul_f32_e32 v24, 0xbfb8aa3b, v24
	v_mul_f32_e32 v25, 0xbfb8aa3b, v25
	v_sqrt_f32_e32 v1, v1
	v_mul_f32_e32 v22, v22, v229
	v_mul_f32_e32 v22, 0xbfb8aa3b, v22
	v_exp_f32_e32 v89, v22
	v_exp_f32_e32 v24, v24
	v_exp_f32_e32 v25, v25
	v_mul_f32_e32 v87, v71, v29
	v_sub_f32_e32 v22, 1.0, v89
	v_add_f32_e32 v48, 1.0, v89
	v_mul_f32_e32 v22, v22, v48
	v_add_f32_e32 v48, v96, v227
	v_mul_f32_e32 v48, 0xbfb8aa3b, v48
	v_add_f32_e32 v26, v97, v227
	v_exp_f32_e32 v48, v48
	v_mul_f32_e32 v26, 0xbfb8aa3b, v26
	v_exp_f32_e32 v26, v26
	v_sqrt_f32_e32 v88, v22
	v_add_f32_e32 v48, 1.0, v48
	v_rcp_f32_e32 v48, v48
	v_add_f32_e32 v26, 1.0, v26
	v_rcp_f32_e32 v26, v26
	v_mul_f32_e32 v22, v31, v23
	v_mul_f32_e32 v48, v48, v229
	v_mul_f32_e32 v48, 0xbfb8aa3b, v48
	v_mul_f32_e32 v26, v26, v229
	v_exp_f32_e32 v91, v48
	v_mul_f32_e32 v26, 0xbfb8aa3b, v26
	v_exp_f32_e32 v93, v26
	v_mul_f32_e32 v23, v86, v89
	v_sub_f32_e32 v48, 1.0, v91
	v_add_f32_e32 v51, 1.0, v91
	v_mul_f32_e32 v23, v91, v23
	v_mul_f32_e32 v48, v48, v51
	v_mul_f32_e32 v51, v93, v23
	ds_bpermute_b32 v53, v171, v51
	v_add_f32_e32 v24, 1.0, v24
	v_add_f32_e32 v25, 1.0, v25
	v_pk_mul_f32 v[36:37], v[86:87], v[0:1]
	v_rcp_f32_e32 v24, v24
	s_waitcnt lgkmcnt(0)
	v_mul_f32_e32 v57, v51, v53
	ds_bpermute_b32 v58, v172, v57
	v_cndmask_b32_e64 v55, v53, 1.0, s[50:51]
	v_rcp_f32_e32 v25, v25
	v_pk_fma_f32 v[94:95], v[86:87], v[0:1], v[36:37] op_sel_hi:[1,1,0]
	v_sqrt_f32_e32 v90, v48
	s_waitcnt lgkmcnt(0)
	v_mul_f32_e32 v23, v55, v58
	v_cndmask_b32_e64 v48, v23, v55, s[52:53]
	v_mov_b32_e32 v23, v95
	v_sub_f32_e32 v26, 1.0, v93
	v_add_f32_e32 v27, 1.0, v93
	v_pk_mul_f32 v[94:95], v[22:23], v[88:89]
	v_mul_f32_e32 v26, v26, v27
	v_pk_fma_f32 v[22:23], v[22:23], v[88:89], v[94:95] op_sel_hi:[1,1,0]
	v_mul_f32_e32 v24, v136, v24
	v_sqrt_f32_e32 v92, v26
	v_mul_f32_e32 v26, v133, v25
	v_mov_b32_e32 v25, v23
	v_pk_mul_f32 v[96:97], v[24:25], v[90:91]
	v_mul_f32_e32 v28, v57, v58
	v_pk_fma_f32 v[22:23], v[24:25], v[90:91], v[96:97] op_sel_hi:[1,1,0]
	s_nop 0
	v_mov_b32_e32 v27, v23
	v_pk_mul_f32 v[98:99], v[26:27], v[92:93]
	s_nop 0
	v_add_f32_e32 v1, v98, v99
	ds_bpermute_b32 v22, v171, v1
	s_waitcnt lgkmcnt(0)
	v_cndmask_b32_e64 v23, v22, 0, s[50:51]
	v_fma_f32 v24, v51, v22, v1
	v_fmac_f32_e32 v22, v1, v53
	v_cndmask_b32_e64 v1, v24, v22, s[50:51]
	ds_bpermute_b32 v22, v172, v1
	s_waitcnt lgkmcnt(0)
	v_fma_f32 v24, v55, v22, v23
	v_cndmask_b32_e64 v36, v24, v23, s[52:53]
	v_fma_f32 v23, v57, v22, v1
	v_fmac_f32_e32 v22, v1, v58
	v_cndmask_b32_e64 v29, v23, v22, s[52:53]
	ds_write_b64 v175, v[28:29] offset:59008
	s_waitcnt lgkmcnt(1)
	v_mfma_f32_16x16x32_bf16 v[22:25], v[14:17], v[208:211], 0
	s_waitcnt lgkmcnt(0)
	v_mfma_f32_16x16x32_bf16 v[102:105], v[14:17], v[212:215], 0
	ds_read_b32 v55, v174 offset:57856
	ds_read_b32 v57, v174 offset:58112
	ds_read_b32 v58, v174 offset:58368
	s_waitcnt lgkmcnt(4)
	v_mfma_f32_16x16x32_bf16 v[26:29], v[18:21], v[216:219], v[22:25]
	s_waitcnt lgkmcnt(3)
	v_mfma_f32_16x16x32_bf16 v[22:25], v[18:21], v[220:223], v[102:105]
	ds_read_b32 v246, v174 offset:57920
	ds_read_b32 v247, v174 offset:58176
	ds_read_b32 v248, v174 offset:58432
	ds_read_b128 v[208:211], v132 offset:39680
	ds_read_b128 v[212:215], v132 offset:48896
	ds_read_b128 v[216:219], v132 offset:39744
	ds_read_b128 v[220:223], v132 offset:48960
	s_waitcnt lgkmcnt(2)
	s_nop 4
	v_add_f32_e32 v1, v29, v55
	v_mul_f32_e32 v1, 0xbfb8aa3b, v1
	v_exp_f32_e32 v1, v1
	s_nop 0
	v_add_f32_e32 v1, 1.0, v1
	v_rcp_f32_e32 v1, v1
	s_waitcnt lgkmcnt(1)
	v_add_f32_e32 v25, v25, v57
	v_mul_f32_e32 v25, 0xbfb8aa3b, v25
	v_exp_f32_e32 v25, v25
	s_waitcnt lgkmcnt(0)
	v_mul_f32_e32 v1, v1, v58
	v_mul_f32_e32 v1, 0xbfb8aa3b, v1
	v_exp_f32_e32 v100, v1
	v_add_f32_e32 v25, 1.0, v25
	v_rcp_f32_e32 v25, v25
	v_add_f32_e32 v23, v23, v57
	v_sub_f32_e32 v1, 1.0, v100
	v_add_f32_e32 v29, 1.0, v100
	v_mul_f32_e32 v1, v1, v29
	v_sqrt_f32_e32 v1, v1
	v_mul_f32_e32 v101, v101, v25
	v_mul_f32_e32 v23, 0xbfb8aa3b, v23
	v_exp_f32_e32 v23, v23
	v_pk_mul_f32 v[102:103], v[100:101], v[0:1]
	v_add_f32_e32 v24, v24, v57
	v_pk_fma_f32 v[114:115], v[100:101], v[0:1], v[102:103] op_sel_hi:[1,1,0]
	v_add_f32_e32 v1, v28, v55
	v_mul_f32_e32 v1, 0xbfb8aa3b, v1
	v_exp_f32_e32 v1, v1
	v_add_f32_e32 v23, 1.0, v23
	v_rcp_f32_e32 v23, v23
	v_mul_f32_e32 v24, 0xbfb8aa3b, v24
	v_add_f32_e32 v1, 1.0, v1
	v_rcp_f32_e32 v1, v1
	v_mul_f32_e32 v23, v108, v23
	v_exp_f32_e32 v24, v24
	v_add_f32_e32 v22, v22, v57
	v_mul_f32_e32 v1, v1, v58
	v_mul_f32_e32 v1, 0xbfb8aa3b, v1
	v_exp_f32_e32 v105, v1
	v_mul_f32_e32 v22, 0xbfb8aa3b, v22
	v_add_f32_e32 v24, 1.0, v24
	v_exp_f32_e32 v22, v22
	v_sub_f32_e32 v1, 1.0, v105
	v_add_f32_e32 v25, 1.0, v105
	v_mul_f32_e32 v1, v1, v25
	v_add_f32_e32 v25, v27, v55
	v_mul_f32_e32 v25, 0xbfb8aa3b, v25
	v_exp_f32_e32 v25, v25
	v_rcp_f32_e32 v24, v24
	v_sqrt_f32_e32 v104, v1
	v_add_f32_e32 v22, 1.0, v22
	v_add_f32_e32 v25, 1.0, v25
	v_rcp_f32_e32 v25, v25
	v_mul_f32_e32 v114, v106, v24
	v_rcp_f32_e32 v22, v22
	v_pk_mul_f32 v[106:107], v[114:115], v[104:105]
	v_mul_f32_e32 v25, v25, v58
	v_mul_f32_e32 v25, 0xbfb8aa3b, v25
	v_exp_f32_e32 v51, v25
	v_add_f32_e32 v1, v106, v107
	v_mul_f32_e32 v24, v100, v105
	v_mul_f32_e32 v22, v110, v22
	v_sub_f32_e32 v25, 1.0, v51
	v_add_f32_e32 v27, 1.0, v51
	v_mul_f32_e32 v25, v25, v27
	v_sqrt_f32_e32 v25, v25
	v_mul_f32_e32 v1, v51, v1
	v_mul_f32_e32 v24, v51, v24
	v_mul_f32_e32 v53, v23, v25
	v_add_f32_e32 v23, v26, v55
	v_mul_f32_e32 v23, 0xbfb8aa3b, v23
	v_exp_f32_e32 v23, v23
	s_nop 0
	v_add_f32_e32 v23, 1.0, v23
	v_rcp_f32_e32 v23, v23
	s_nop 0
	v_mul_f32_e32 v23, v23, v58
	v_mul_f32_e32 v23, 0xbfb8aa3b, v23
	v_exp_f32_e32 v109, v23
	s_nop 0
	v_sub_f32_e32 v23, 1.0, v109
	v_add_f32_e32 v25, 1.0, v109
	v_mul_f32_e32 v23, v23, v25
	v_sqrt_f32_e32 v108, v23
	v_add_f32_e32 v23, v1, v53
	v_pk_mul_f32 v[110:111], v[22:23], v[108:109]
	s_nop 0
	v_add_f32_e32 v1, v110, v111
	v_mul_f32_e32 v22, v109, v24
	ds_bpermute_b32 v23, v171, v22
	ds_bpermute_b32 v24, v171, v1
	s_waitcnt lgkmcnt(1)
; #define LAS __attribute__((address_space(3)))
; #define MFMA16(a, b, c) __builtin_amdgcn_mfma_f32_16x16x32_bf16(a, b, c, 0, 0, 0)
; template <bool PHASE_B>
; __device__ __forceinline__ void lru_item(const Params& p, LAS unsigned char* lds, int ci, int ci_next, int jb, const int tid, v4u (&xvn)[3]) {
;     ...
;                 const bf16x8 wa = *(const LAS bf16x8*)(lds + LR_WG + ((dir * 2 + 0) * 64 + 16 * ct + fr) * 144 + (32 * ks + 8 * fq) * 2);
;                 const bf16x8 wx = *(const LAS bf16x8*)(lds + LR_WG + ((dir * 2 + 1) * 64 + 16 * ct + fr) * 144 + (32 * ks + 8 * fq) * 2);
;                 ga = MFMA16(af[ks], wa, ga); gx = MFMA16(af[ks], wx, gx); }
;             const int ch = 16 * ct + fr; const float bav = GC[(dir * 3 + 0) * 64 + ch], bxv = GC[(dir * 3 + 1) * 64 + ch], c8 = GC[(dir * 3 + 2) * 64 + ch];
;             float Al = 1.f, Hl = 0.f;
; #pragma unroll
;             for (int ee = 0; ee < 4; ++ee) { const int e = dir ? 3 - ee : ee;
;                 const float r = __builtin_amdgcn_rcpf(1.f + __expf(-(ga[e] + bav))), ig = __builtin_amdgcn_rcpf(1.f + __expf(-(gx[e] + bxv)));
;                 const float la = -c8 * r; const float a = __expf(la); const float u = __builtin_amdgcn_sqrtf((1.f - a) * (1.f + a)) * (ig * xc[ct][e]);
;                 av[dir][ct][e] = a; uv[dir][ct][e] = u; Hl = a * Hl + u; Al *= a; }
;             const int o = dir ? 3 - fq : fq; const bool odd = (o & 1) != 0, hi2 = (o & 2) != 0;
;             const float A1 = __shfl_xor(Al, 16), H1 = __shfl_xor(Hl, 16);
;             const float pxA = odd ? A1 : 1.f, pxH = odd ? H1 : 0.f;
;             const float gA = Al * A1, gH = odd ? (Al * H1 + Hl) : (A1 * Hl + H1);
;             const float A2 = __shfl_xor(gA, 32), H2 = __shfl_xor(gH, 32);
;             const float PA = hi2 ? pxA * A2 : pxA, PH = hi2 ? (pxA * H2 + pxH) : pxH;
;             const float TA = gA * A2, TH = hi2 ? (gA * H2 + gH) : (A2 * gH + H2);
;             pA[dir][ct] = PA; pH[dir][ct] = PH;
;             ((LAS f32x2*)(lds + LR_SEG))[(dir * 8 + rt) * 64 + ch] = (f32x2){TA, TH};
	v_mul_f32_e32 v27, v22, v23
	s_waitcnt lgkmcnt(0)
	v_cndmask_b32_e64 v26, v24, 0, s[54:55]
	v_fma_f32 v22, v22, v24, v1
	v_fmac_f32_e32 v24, v1, v23
	v_cndmask_b32_e64 v25, v23, 1.0, s[54:55]
	v_cndmask_b32_e64 v1, v22, v24, s[54:55]
	ds_bpermute_b32 v23, v172, v27
	ds_bpermute_b32 v24, v172, v1
	s_waitcnt lgkmcnt(1)
	v_mul_f32_e32 v22, v25, v23
	v_cndmask_b32_e64 v55, v22, v25, s[56:57]
	s_waitcnt lgkmcnt(0)
	v_fma_f32 v22, v25, v24, v26
	v_fma_f32 v25, v27, v24, v1
	v_fmac_f32_e32 v24, v1, v23
	v_cndmask_b32_e64 v57, v22, v26, s[56:57]
	v_mul_f32_e32 v22, v27, v23
	v_cndmask_b32_e64 v23, v25, v24, s[56:57]
	ds_write_b64 v175, v[22:23] offset:62720
	s_waitcnt lgkmcnt(1)
	v_mfma_f32_16x16x32_bf16 v[22:25], v[14:17], v[208:211], 0
	s_waitcnt lgkmcnt(0)
	v_mfma_f32_16x16x32_bf16 v[114:117], v[14:17], v[212:215], 0
	s_waitcnt lgkmcnt(4)
	v_mfma_f32_16x16x32_bf16 v[26:29], v[18:21], v[216:219], v[22:25]
	s_waitcnt lgkmcnt(3)
	v_mfma_f32_16x16x32_bf16 v[22:25], v[18:21], v[220:223], v[114:117]
	ds_read_b32 v224, v174 offset:57984
	ds_read_b32 v225, v174 offset:58240
	ds_read_b32 v226, v174 offset:58496
	ds_read_b128 v[208:211], v132 offset:41984
	ds_read_b128 v[212:215], v132 offset:51200
	ds_read_b128 v[216:219], v132 offset:42048
	ds_read_b128 v[220:223], v132 offset:51264
	s_waitcnt lgkmcnt(2)
	s_nop 4
	v_add_f32_e32 v1, v29, v246
	v_mul_f32_e32 v1, 0xbfb8aa3b, v1
	v_exp_f32_e32 v1, v1
	s_nop 0
	v_add_f32_e32 v1, 1.0, v1
	v_rcp_f32_e32 v1, v1
	s_waitcnt lgkmcnt(1)
	v_add_f32_e32 v25, v25, v247
	v_mul_f32_e32 v25, 0xbfb8aa3b, v25
	v_exp_f32_e32 v25, v25
	s_waitcnt lgkmcnt(0)
	v_mul_f32_e32 v1, v1, v248
	v_mul_f32_e32 v1, 0xbfb8aa3b, v1
	v_exp_f32_e32 v112, v1
	v_add_f32_e32 v25, 1.0, v25
	v_rcp_f32_e32 v25, v25
	v_add_f32_e32 v23, v23, v247
	v_sub_f32_e32 v1, 1.0, v112
	v_add_f32_e32 v29, 1.0, v112
	v_mul_f32_e32 v1, v1, v29
	v_sqrt_f32_e32 v1, v1
	v_mul_f32_e32 v113, v113, v25
	v_mul_f32_e32 v23, 0xbfb8aa3b, v23
	v_exp_f32_e32 v23, v23
	v_pk_mul_f32 v[114:115], v[112:113], v[0:1]
	v_add_f32_e32 v24, v24, v247
	v_pk_fma_f32 v[126:127], v[112:113], v[0:1], v[114:115] op_sel_hi:[1,1,0]
	v_add_f32_e32 v1, v28, v246
	v_mul_f32_e32 v1, 0xbfb8aa3b, v1
	v_exp_f32_e32 v1, v1
	v_add_f32_e32 v23, 1.0, v23
	v_rcp_f32_e32 v23, v23
	v_mul_f32_e32 v24, 0xbfb8aa3b, v24
	v_add_f32_e32 v1, 1.0, v1
	v_rcp_f32_e32 v1, v1
	v_mul_f32_e32 v23, v120, v23
	v_exp_f32_e32 v24, v24
	v_add_f32_e32 v22, v22, v247
	v_mul_f32_e32 v1, v1, v248
	v_mul_f32_e32 v1, 0xbfb8aa3b, v1
	v_exp_f32_e32 v117, v1
	v_mul_f32_e32 v22, 0xbfb8aa3b, v22
	v_add_f32_e32 v24, 1.0, v24
	v_exp_f32_e32 v22, v22
	v_sub_f32_e32 v1, 1.0, v117
	v_add_f32_e32 v25, 1.0, v117
	v_mul_f32_e32 v1, v1, v25
	v_add_f32_e32 v25, v27, v246
	v_mul_f32_e32 v25, 0xbfb8aa3b, v25
	v_exp_f32_e32 v25, v25
	v_rcp_f32_e32 v24, v24
	v_sqrt_f32_e32 v116, v1
	v_add_f32_e32 v22, 1.0, v22
	v_add_f32_e32 v25, 1.0, v25
	v_rcp_f32_e32 v25, v25
	v_mul_f32_e32 v126, v118, v24
	v_rcp_f32_e32 v22, v22
	v_pk_mul_f32 v[118:119], v[126:127], v[116:117]
	v_mul_f32_e32 v25, v25, v248
	v_mul_f32_e32 v25, 0xbfb8aa3b, v25
	v_exp_f32_e32 v58, v25
	v_add_f32_e32 v1, v118, v119
	v_mul_f32_e32 v24, v112, v117
	v_mul_f32_e32 v22, v122, v22
	v_sub_f32_e32 v25, 1.0, v58
	v_add_f32_e32 v27, 1.0, v58
	v_mul_f32_e32 v25, v25, v27
	v_sqrt_f32_e32 v25, v25
	v_mul_f32_e32 v1, v58, v1
	v_mul_f32_e32 v24, v58, v24
	v_mul_f32_e32 v60, v23, v25
	v_add_f32_e32 v23, v26, v246
	v_mul_f32_e32 v23, 0xbfb8aa3b, v23
	v_exp_f32_e32 v23, v23
	s_nop 0
	v_add_f32_e32 v23, 1.0, v23
	v_rcp_f32_e32 v23, v23
	s_nop 0
	v_mul_f32_e32 v23, v23, v248
	v_mul_f32_e32 v23, 0xbfb8aa3b, v23
	v_exp_f32_e32 v121, v23
	s_nop 0
	v_sub_f32_e32 v23, 1.0, v121
	v_add_f32_e32 v25, 1.0, v121
	v_mul_f32_e32 v23, v23, v25
	v_sqrt_f32_e32 v120, v23
	v_add_f32_e32 v23, v1, v60
	v_pk_mul_f32 v[122:123], v[22:23], v[120:121]
	s_nop 0
	v_add_f32_e32 v1, v122, v123
	v_mul_f32_e32 v22, v121, v24
	ds_bpermute_b32 v23, v171, v22
	ds_bpermute_b32 v24, v171, v1
	s_waitcnt lgkmcnt(1)
	v_mul_f32_e32 v27, v22, v23
	s_waitcnt lgkmcnt(0)
	v_cndmask_b32_e64 v26, v24, 0, s[54:55]
	v_fma_f32 v22, v22, v24, v1
	v_fmac_f32_e32 v24, v1, v23
	v_cndmask_b32_e64 v25, v23, 1.0, s[54:55]
	v_cndmask_b32_e64 v1, v22, v24, s[54:55]
	ds_bpermute_b32 v23, v172, v27
	ds_bpermute_b32 v24, v172, v1
	s_waitcnt lgkmcnt(1)
	v_mul_f32_e32 v22, v25, v23
	v_cndmask_b32_e64 v62, v22, v25, s[56:57]
	s_waitcnt lgkmcnt(0)
	v_fma_f32 v22, v25, v24, v26
	v_fma_f32 v25, v27, v24, v1
	v_fmac_f32_e32 v24, v1, v23
	v_cndmask_b32_e64 v64, v22, v26, s[56:57]
	v_mul_f32_e32 v22, v27, v23
	v_cndmask_b32_e64 v23, v25, v24, s[56:57]
	ds_write_b64 v175, v[22:23] offset:62848
	s_waitcnt lgkmcnt(1)
	v_mfma_f32_16x16x32_bf16 v[22:25], v[14:17], v[208:211], 0
	s_waitcnt lgkmcnt(0)
	v_mfma_f32_16x16x32_bf16 v[138:141], v[14:17], v[212:215], 0
	s_waitcnt lgkmcnt(4)
	v_mfma_f32_16x16x32_bf16 v[26:29], v[18:21], v[216:219], v[22:25]
	s_waitcnt lgkmcnt(3)
	v_mfma_f32_16x16x32_bf16 v[22:25], v[18:21], v[220:223], v[138:141]
	ds_read_b32 v227, v174 offset:58048
	ds_read_b32 v228, v174 offset:58304
	ds_read_b32 v229, v174 offset:58560
	ds_read_b128 v[208:211], v132 offset:44288
	ds_read_b128 v[212:215], v132 offset:53504
	ds_read_b128 v[216:219], v132 offset:44352
	ds_read_b128 v[220:223], v132 offset:53568
	s_waitcnt lgkmcnt(2)
	s_nop 4
	v_add_f32_e32 v1, v29, v224
	v_mul_f32_e32 v1, 0xbfb8aa3b, v1
	v_exp_f32_e32 v1, v1
	s_nop 0
	v_add_f32_e32 v1, 1.0, v1
	v_rcp_f32_e32 v1, v1
	s_waitcnt lgkmcnt(1)
	v_add_f32_e32 v25, v25, v225
	v_mul_f32_e32 v25, 0xbfb8aa3b, v25
	v_exp_f32_e32 v25, v25
	s_waitcnt lgkmcnt(0)
; #define LAS __attribute__((address_space(3)))
; #define MFMA16(a, b, c) __builtin_amdgcn_mfma_f32_16x16x32_bf16(a, b, c, 0, 0, 0)
; template <bool PHASE_B>
; __device__ __forceinline__ void lru_item(const Params& p, LAS unsigned char* lds, int ci, int ci_next, int jb, const int tid, v4u (&xvn)[3]) {
;     ...
;                 const bf16x8 wa = *(const LAS bf16x8*)(lds + LR_WG + ((dir * 2 + 0) * 64 + 16 * ct + fr) * 144 + (32 * ks + 8 * fq) * 2);
;                 const bf16x8 wx = *(const LAS bf16x8*)(lds + LR_WG + ((dir * 2 + 1) * 64 + 16 * ct + fr) * 144 + (32 * ks + 8 * fq) * 2);
;                 ga = MFMA16(af[ks], wa, ga); gx = MFMA16(af[ks], wx, gx); }
;             const int ch = 16 * ct + fr; const float bav = GC[(dir * 3 + 0) * 64 + ch], bxv = GC[(dir * 3 + 1) * 64 + ch], c8 = GC[(dir * 3 + 2) * 64 + ch];
;             float Al = 1.f, Hl = 0.f;
; #pragma unroll
;             for (int ee = 0; ee < 4; ++ee) { const int e = dir ? 3 - ee : ee;
;                 const float r = __builtin_amdgcn_rcpf(1.f + __expf(-(ga[e] + bav))), ig = __builtin_amdgcn_rcpf(1.f + __expf(-(gx[e] + bxv)));
;                 const float la = -c8 * r; const float a = __expf(la); const float u = __builtin_amdgcn_sqrtf((1.f - a) * (1.f + a)) * (ig * xc[ct][e]);
;                 av[dir][ct][e] = a; uv[dir][ct][e] = u; Hl = a * Hl + u; Al *= a; }
;             const int o = dir ? 3 - fq : fq; const bool odd = (o & 1) != 0, hi2 = (o & 2) != 0;
;             const float A1 = __shfl_xor(Al, 16), H1 = __shfl_xor(Hl, 16);
;             const float pxA = odd ? A1 : 1.f, pxH = odd ? H1 : 0.f;
;             const float gA = Al * A1, gH = odd ? (Al * H1 + Hl) : (A1 * Hl + H1);
;             const float A2 = __shfl_xor(gA, 32), H2 = __shfl_xor(gH, 32);
;             const float PA = hi2 ? pxA * A2 : pxA, PH = hi2 ? (pxA * H2 + pxH) : pxH;
;             const float TA = gA * A2, TH = hi2 ? (gA * H2 + gH) : (A2 * gH + H2);
;             pA[dir][ct] = PA; pH[dir][ct] = PH;
;             ((LAS f32x2*)(lds + LR_SEG))[(dir * 8 + rt) * 64 + ch] = (f32x2){TA, TH};
	v_mul_f32_e32 v1, v1, v226
	v_mul_f32_e32 v1, 0xbfb8aa3b, v1
	v_exp_f32_e32 v124, v1
	v_add_f32_e32 v25, 1.0, v25
	v_rcp_f32_e32 v25, v25
	v_add_f32_e32 v24, v24, v225
	v_sub_f32_e32 v1, 1.0, v124
	v_add_f32_e32 v29, 1.0, v124
	v_mul_f32_e32 v1, v1, v29
	v_sqrt_f32_e32 v1, v1
	v_mul_f32_e32 v125, v125, v25
	v_mul_f32_e32 v24, 0xbfb8aa3b, v24
	v_exp_f32_e32 v24, v24
	v_pk_mul_f32 v[126:127], v[124:125], v[0:1]
	v_add_f32_e32 v23, v23, v225
	v_pk_fma_f32 v[134:135], v[124:125], v[0:1], v[126:127] op_sel_hi:[1,1,0]
	v_add_f32_e32 v1, v28, v224
	v_mul_f32_e32 v1, 0xbfb8aa3b, v1
	v_exp_f32_e32 v1, v1
	v_add_f32_e32 v24, 1.0, v24
	v_rcp_f32_e32 v24, v24
	v_mul_f32_e32 v23, 0xbfb8aa3b, v23
	v_add_f32_e32 v1, 1.0, v1
	v_rcp_f32_e32 v1, v1
	v_mul_f32_e32 v134, v128, v24
	v_exp_f32_e32 v23, v23
	v_add_f32_e32 v22, v22, v225
	v_mul_f32_e32 v1, v1, v226
	v_mul_f32_e32 v1, 0xbfb8aa3b, v1
	v_exp_f32_e32 v29, v1
	v_add_f32_e32 v23, 1.0, v23
	v_rcp_f32_e32 v23, v23
	v_mul_f32_e32 v22, 0xbfb8aa3b, v22
	v_sub_f32_e32 v1, 1.0, v29
	v_add_f32_e32 v25, 1.0, v29
	v_mul_f32_e32 v1, v1, v25
	v_add_f32_e32 v25, v27, v224
	v_mul_f32_e32 v25, 0xbfb8aa3b, v25
	v_exp_f32_e32 v25, v25
	v_sqrt_f32_e32 v28, v1
	v_mul_f32_e32 v23, v130, v23
	v_exp_f32_e32 v22, v22
	v_add_f32_e32 v25, 1.0, v25
	v_rcp_f32_e32 v25, v25
	v_pk_mul_f32 v[128:129], v[134:135], v[28:29]
	v_add_f32_e32 v22, 1.0, v22
	v_rcp_f32_e32 v22, v22
	v_mul_f32_e32 v25, v25, v226
	v_mul_f32_e32 v25, 0xbfb8aa3b, v25
	v_exp_f32_e32 v28, v25
	v_add_f32_e32 v1, v128, v129
	v_mul_f32_e32 v24, v124, v29
	v_mul_f32_e32 v22, v69, v22
	v_sub_f32_e32 v25, 1.0, v28
	v_add_f32_e32 v27, 1.0, v28
	v_mul_f32_e32 v25, v25, v27
	v_sqrt_f32_e32 v25, v25
	v_mul_f32_e32 v1, v28, v1
	v_mul_f32_e32 v24, v28, v24
	v_mul_f32_e32 v67, v23, v25
	v_add_f32_e32 v23, v26, v224
	v_mul_f32_e32 v23, 0xbfb8aa3b, v23
	v_exp_f32_e32 v23, v23
	s_nop 0
	v_add_f32_e32 v23, 1.0, v23
	v_rcp_f32_e32 v23, v23
	s_nop 0
	v_mul_f32_e32 v23, v23, v226
	v_mul_f32_e32 v23, 0xbfb8aa3b, v23
	v_exp_f32_e32 v27, v23
	s_nop 0
	v_sub_f32_e32 v23, 1.0, v27
	v_add_f32_e32 v25, 1.0, v27
	v_mul_f32_e32 v23, v23, v25
	v_sqrt_f32_e32 v26, v23
	v_add_f32_e32 v23, v1, v67
	v_pk_mul_f32 v[130:131], v[22:23], v[26:27]
	s_nop 0
	v_add_f32_e32 v1, v130, v131
	v_mul_f32_e32 v22, v27, v24
	ds_bpermute_b32 v23, v171, v22
	ds_bpermute_b32 v24, v171, v1
	s_waitcnt lgkmcnt(1)
	v_mul_f32_e32 v73, v22, v23
	s_waitcnt lgkmcnt(0)
	v_cndmask_b32_e64 v69, v24, 0, s[54:55]
	v_fma_f32 v22, v22, v24, v1
	v_fmac_f32_e32 v24, v1, v23
	v_cndmask_b32_e64 v25, v23, 1.0, s[54:55]
	v_cndmask_b32_e64 v1, v22, v24, s[54:55]
	ds_bpermute_b32 v23, v172, v73
	ds_bpermute_b32 v24, v172, v1
	s_waitcnt lgkmcnt(1)
	v_mul_f32_e32 v22, v25, v23
	v_cndmask_b32_e64 v26, v22, v25, s[56:57]
	s_waitcnt lgkmcnt(0)
	v_fma_f32 v22, v25, v24, v69
	v_fma_f32 v25, v73, v24, v1
	v_fmac_f32_e32 v24, v1, v23
	v_cndmask_b32_e64 v69, v22, v69, s[56:57]
	v_mul_f32_e32 v22, v73, v23
	v_cndmask_b32_e64 v23, v25, v24, s[56:57]
	ds_write_b64 v175, v[22:23] offset:62976
	s_waitcnt lgkmcnt(1)
	v_mfma_f32_16x16x32_bf16 v[22:25], v[14:17], v[208:211], 0
	s_waitcnt lgkmcnt(0)
	v_mfma_f32_16x16x32_bf16 v[14:17], v[14:17], v[212:215], 0
	s_waitcnt lgkmcnt(1)
	v_mfma_f32_16x16x32_bf16 v[22:25], v[18:21], v[216:219], v[22:25]
	s_waitcnt lgkmcnt(0)
	v_mfma_f32_16x16x32_bf16 v[14:17], v[18:21], v[220:223], v[14:17]
	s_waitcnt lgkmcnt(2)
	s_nop 1
	s_nop 2
	v_add_f32_e32 v1, v25, v227
	v_mul_f32_e32 v1, 0xbfb8aa3b, v1
	v_exp_f32_e32 v1, v1
	s_waitcnt lgkmcnt(1)
	s_nop 0
	v_add_f32_e32 v17, v17, v228
	v_mul_f32_e32 v17, 0xbfb8aa3b, v17
	v_exp_f32_e32 v17, v17
	v_add_f32_e32 v1, 1.0, v1
	v_rcp_f32_e32 v1, v1
	v_add_f32_e32 v16, v16, v228
	v_add_f32_e32 v17, 1.0, v17
	v_rcp_f32_e32 v17, v17
	s_waitcnt lgkmcnt(0)
	v_mul_f32_e32 v1, v1, v229
	v_mul_f32_e32 v1, 0xbfb8aa3b, v1
	v_exp_f32_e32 v132, v1
	v_mul_f32_e32 v133, v133, v17
	v_mul_f32_e32 v16, 0xbfb8aa3b, v16
	v_exp_f32_e32 v16, v16
	v_sub_f32_e32 v1, 1.0, v132
	v_add_f32_e32 v18, 1.0, v132
	v_mul_f32_e32 v1, v1, v18
	v_sqrt_f32_e32 v1, v1
	v_add_f32_e32 v16, 1.0, v16
	v_add_f32_e32 v15, v15, v228
	v_rcp_f32_e32 v16, v16
	v_pk_mul_f32 v[134:135], v[132:133], v[0:1]
	v_mul_f32_e32 v15, 0xbfb8aa3b, v15
	v_pk_fma_f32 v[18:19], v[132:133], v[0:1], v[134:135] op_sel_hi:[1,1,0]
	v_add_f32_e32 v1, v24, v227
	v_mul_f32_e32 v1, 0xbfb8aa3b, v1
	v_exp_f32_e32 v1, v1
	v_exp_f32_e32 v15, v15
	v_mul_f32_e32 v18, v136, v16
	v_add_f32_e32 v14, v14, v228
	v_add_f32_e32 v1, 1.0, v1
	v_rcp_f32_e32 v1, v1
	v_add_f32_e32 v15, 1.0, v15
	v_rcp_f32_e32 v15, v15
	v_mul_f32_e32 v14, 0xbfb8aa3b, v14
	v_mul_f32_e32 v1, v1, v229
	v_mul_f32_e32 v1, 0xbfb8aa3b, v1
	v_exp_f32_e32 v25, v1
	v_mul_f32_e32 v15, v31, v15
	v_exp_f32_e32 v14, v14
	v_sub_f32_e32 v1, 1.0, v25
	v_add_f32_e32 v17, 1.0, v25
	v_mul_f32_e32 v1, v1, v17
	v_sqrt_f32_e32 v24, v1
	v_add_f32_e32 v1, v23, v227
	v_mul_f32_e32 v1, 0xbfb8aa3b, v1
	v_exp_f32_e32 v1, v1
	v_pk_mul_f32 v[136:137], v[18:19], v[24:25]
	v_mul_f32_e32 v17, v132, v25
	v_add_f32_e32 v16, v136, v137
	v_add_f32_e32 v1, 1.0, v1
	v_rcp_f32_e32 v1, v1
	v_add_f32_e32 v14, 1.0, v14
	v_rcp_f32_e32 v14, v14
	v_mul_f32_e32 v1, v1, v229
	v_mul_f32_e32 v1, 0xbfb8aa3b, v1
	v_exp_f32_e32 v1, v1
	v_mul_f32_e32 v14, v71, v14
	v_sub_f32_e32 v18, 1.0, v1
	v_add_f32_e32 v19, 1.0, v1
	v_mul_f32_e32 v18, v18, v19
	v_sqrt_f32_e32 v18, v18
	s_nop 0
	v_mul_f32_e32 v24, v15, v18
	v_mul_f32_e32 v15, v1, v16
	v_mul_f32_e32 v16, v1, v17
	v_add_f32_e32 v17, v22, v227
	v_mul_f32_e32 v17, 0xbfb8aa3b, v17
	v_exp_f32_e32 v17, v17
	v_add_f32_e32 v15, v15, v24
	v_add_f32_e32 v17, 1.0, v17
	v_rcp_f32_e32 v17, v17
	s_nop 0
	v_mul_f32_e32 v17, v17, v229
	v_mul_f32_e32 v17, 0xbfb8aa3b, v17
	v_exp_f32_e32 v23, v17
	s_nop 0
	v_sub_f32_e32 v17, 1.0, v23
	v_add_f32_e32 v18, 1.0, v23
	v_mul_f32_e32 v17, v17, v18
	v_sqrt_f32_e32 v22, v17
	s_nop 0
	v_pk_mul_f32 v[138:139], v[14:15], v[22:23]
	s_nop 0
	v_add_f32_e32 v14, v138, v139
	v_mul_f32_e32 v15, v23, v16
	ds_bpermute_b32 v16, v171, v15
	ds_bpermute_b32 v17, v171, v14
	s_waitcnt lgkmcnt(1)
; #define LAS __attribute__((address_space(3)))
; template <bool PHASE_B>
; __device__ __forceinline__ void lru_item(const Params& p, LAS unsigned char* lds, int ci, int ci_next, int jb, const int tid, v4u (&xvn)[3]) {
;     ...
;             ((LAS f32x2*)(lds + LR_SEG))[(dir * 8 + rt) * 64 + ch] = (f32x2){TA, TH};
;     ...
;             for (int ct = 0; ct < 4; ++ct) cin[dir][ct] = ((const float*)(p.ws + WS_CIN))[(size_t)(ci * 2 + dir) * 768 + jb * 64 + 16 * ct + fr];
;         const bf16* gp = (const bf16*)(p.ws + WS_GR) + (size_t)(t0 + (tid >> 2)) * 768 + jb * 64 + (tid & 3) * 16;
;         gv[0] = *(const v4u*)gp; gv[1] = *(const v4u*)(gp + 8);
;     }
;     __syncthreads();
;     if constexpr (!PHASE_B) {
;         if (tid < 128) { const int dir = tid >> 6, ch = tid & 63; float A = 1.f, H = 0.f;
; #pragma unroll
;             for (int q = 0; q < 8; ++q) { const f32x2 sh = ((const LAS f32x2*)(lds + LR_SEG))[(dir * 8 + (dir ? 7 - q : q)) * 64 + ch]; H = sh.x * H + sh.y; A *= sh.x; }
;             ((f32x2*)(p.ws + WS_CAR))[(size_t)(ci * 2 + dir) * 768 + jb * 64 + ch] = (f32x2){A, H}; }
;     } else {
; #pragma unroll
;         for (int dir = 0; dir < 2; ++dir) { const int ot = dir ? 7 - rt : rt;
; #pragma unroll
;             for (int ct = 0; ct < 4; ++ct) { const int ch = 16 * ct + fr; float h = cin[dir][ct];
; #pragma unroll
;                 for (int q = 0; q < 7; ++q) { const f32x2 sh = ((const LAS f32x2*)(lds + LR_SEG))[(dir * 8 + (dir ? 7 - q : q)) * 64 + ch]; const float nh = sh.x * h + sh.y; h = (q < ot) ? nh : h; }
;                 h = pA[dir][ct] * h + pH[dir][ct];
; #pragma unroll
;                 for (int ee = 0; ee < 4; ++ee) { const int e = dir ? 3 - ee : ee; h = av[dir][ct][e] * h + uv[dir][ct][e];
;                     ((LAS float*)(lds + LR_HB))[(dir * LCH + 16 * rt + 4 * fq + e) * 68 + ch] = h; } } }
	v_mul_f32_e32 v20, v15, v16
	s_waitcnt lgkmcnt(0)
	v_cndmask_b32_e64 v19, v17, 0, s[54:55]
	v_fma_f32 v15, v15, v17, v14
	v_fmac_f32_e32 v17, v14, v16
	v_cndmask_b32_e64 v18, v16, 1.0, s[54:55]
	v_cndmask_b32_e64 v15, v15, v17, s[54:55]
	ds_bpermute_b32 v16, v172, v20
	ds_bpermute_b32 v17, v172, v15
	s_waitcnt lgkmcnt(1)
	v_mul_f32_e32 v14, v18, v16
	v_cndmask_b32_e64 v22, v14, v18, s[56:57]
	s_waitcnt lgkmcnt(0)
	v_fma_f32 v14, v18, v17, v19
	v_fma_f32 v18, v20, v17, v15
	v_fmac_f32_e32 v17, v15, v16
	v_cndmask_b32_e64 v31, v14, v19, s[56:57]
	v_mul_f32_e32 v14, v20, v16
	v_cndmask_b32_e64 v15, v18, v17, s[56:57]
	ds_write_b64 v175, v[14:15] offset:63104
	v_mad_i64_i32 v[14:15], s[0:1], s13, v232, v[32:33]
	global_load_dword v78, v[14:15], off
	global_load_dword v81, v[14:15], off offset:64
	global_load_dword v83, v[14:15], off offset:128
	global_load_dword v85, v[14:15], off offset:192
	s_add_i32 s0, s13, 1
	v_mad_i64_i32 v[14:15], s[0:1], s0, v232, v[32:33]
	s_movk_i32 s0, 0x600
	s_nop 0
	v_mad_i64_i32 v[140:141], s[0:1], v196, s0, v[34:35]
	global_load_dword v76, v[14:15], off
	global_load_dword v74, v[14:15], off offset:64
	global_load_dword v73, v[14:15], off offset:128
	global_load_dword v71, v[14:15], off offset:192
	s_nop 0
	global_load_dwordx4 v[14:17], v[140:141], off offset:16
	global_load_dwordx4 v[18:21], v[140:141], off
	s_waitcnt lgkmcnt(0)
	s_barrier
	ds_read_b64 v[208:209], v176 offset:58624
	ds_read_b64 v[210:211], v176 offset:59136
	ds_read_b64 v[212:213], v176 offset:59648
	ds_read_b64 v[214:215], v176 offset:60160
	ds_read_b64 v[216:217], v176 offset:60672
	ds_read_b64 v[218:219], v176 offset:61184
	ds_read_b64 v[220:221], v176 offset:61696
	v_add_u32_e32 v196, s12, v196
	s_add_i32 s13, s13, s86
	s_waitcnt vmcnt(9) lgkmcnt(0)
	v_fmac_f32_e32 v209, v78, v208
	v_cndmask_b32_e64 v78, v78, v209, s[58:59]
	v_fmac_f32_e32 v211, v210, v78
	v_cndmask_b32_e64 v78, v78, v211, s[60:61]
	v_fmac_f32_e32 v213, v212, v78
	v_cndmask_b32_e64 v78, v78, v213, s[62:63]
	v_fmac_f32_e32 v215, v214, v78
	v_cndmask_b32_e64 v78, v78, v215, s[64:65]
	v_fmac_f32_e32 v217, v216, v78
	v_cndmask_b32_e64 v78, v78, v217, s[66:67]
	v_fmac_f32_e32 v219, v218, v78
	v_cndmask_b32_e64 v78, v78, v219, s[68:69]
	v_fmac_f32_e32 v221, v220, v78
	v_cndmask_b32_e64 v78, v78, v221, s[70:71]
	v_fmac_f32_e32 v39, v206, v78
	v_fmac_f32_e32 v49, v38, v39
	v_fmac_f32_e32 v50, v41, v49
	v_fmac_f32_e32 v52, v43, v50
	v_fmac_f32_e32 v54, v47, v52
	ds_write2_b32 v202, v49, v50 offset1:68
	ds_write2_b32 v202, v52, v54 offset0:136 offset1:204
	ds_read_b64 v[222:223], v176 offset:58752
	ds_read_b64 v[224:225], v176 offset:59264
	ds_read_b64 v[226:227], v176 offset:59776
	ds_read_b64 v[228:229], v176 offset:60288
	ds_read_b64 v[234:235], v176 offset:60800
	ds_read_b64 v[236:237], v176 offset:61312
	ds_read_b64 v[238:239], v176 offset:61824
	s_waitcnt vmcnt(0)
	v_lshlrev_b32_e32 v52, 16, v18
	v_and_b32_e32 v18, 0xffff0000, v18
	s_waitcnt lgkmcnt(0)
	v_fmac_f32_e32 v223, v81, v222
	v_cndmask_b32_e64 v41, v81, v223, s[58:59]
	v_fmac_f32_e32 v225, v224, v41
	v_cndmask_b32_e64 v41, v41, v225, s[60:61]
	v_fmac_f32_e32 v227, v226, v41
	v_cndmask_b32_e64 v41, v41, v227, s[62:63]
	v_fmac_f32_e32 v229, v228, v41
	v_cndmask_b32_e64 v41, v41, v229, s[64:65]
	v_fmac_f32_e32 v235, v234, v41
	v_cndmask_b32_e64 v41, v41, v235, s[66:67]
	v_fmac_f32_e32 v237, v236, v41
	v_cndmask_b32_e64 v41, v41, v237, s[68:69]
	v_fmac_f32_e32 v239, v238, v41
	v_cndmask_b32_e64 v38, v41, v239, s[70:71]
	v_fmac_f32_e32 v42, v40, v38
	v_fmac_f32_e32 v65, v56, v42
	v_fmac_f32_e32 v66, v59, v65
	v_fmac_f32_e32 v68, v61, v66
	v_fmac_f32_e32 v70, v63, v68
	ds_write_b32 v177, v65
	ds_write_b32 v178, v66
	ds_write_b32 v179, v68
	ds_write_b32 v180, v70
	ds_read_b64 v[208:209], v176 offset:58880
	ds_read_b64 v[210:211], v176 offset:59392
	ds_read_b64 v[212:213], v176 offset:59904
	ds_read_b64 v[214:215], v176 offset:60416
	ds_read_b64 v[216:217], v176 offset:60928
	ds_read_b64 v[218:219], v176 offset:61440
	ds_read_b64 v[220:221], v176 offset:61952
	s_waitcnt lgkmcnt(0)
	v_fmac_f32_e32 v209, v83, v208
	v_cndmask_b32_e64 v40, v83, v209, s[58:59]
	v_fmac_f32_e32 v211, v210, v40
	v_cndmask_b32_e64 v40, v40, v211, s[60:61]
	v_fmac_f32_e32 v213, v212, v40
	v_cndmask_b32_e64 v40, v40, v213, s[62:63]
	v_fmac_f32_e32 v215, v214, v40
	v_cndmask_b32_e64 v40, v40, v215, s[64:65]
	v_fmac_f32_e32 v217, v216, v40
	v_cndmask_b32_e64 v40, v40, v217, s[66:67]
	v_fmac_f32_e32 v219, v218, v40
	v_cndmask_b32_e64 v40, v40, v219, s[68:69]
	v_fmac_f32_e32 v221, v220, v40
	v_cndmask_b32_e64 v38, v40, v221, s[70:71]
	v_fmac_f32_e32 v44, v46, v38
	v_fmac_f32_e32 v45, v72, v44
	v_fmac_f32_e32 v80, v75, v45
	v_fmac_f32_e32 v82, v77, v80
	v_fmac_f32_e32 v84, v79, v82
	ds_write_b32 v181, v45
	ds_write_b32 v182, v80
	ds_write_b32 v183, v82
	ds_write_b32 v184, v84
	ds_read_b64 v[222:223], v176 offset:59008
	ds_read_b64 v[224:225], v176 offset:59520
	ds_read_b64 v[226:227], v176 offset:60032
	ds_read_b64 v[228:229], v176 offset:60544
	ds_read_b64 v[234:235], v176 offset:61056
	ds_read_b64 v[236:237], v176 offset:61568
	ds_read_b64 v[238:239], v176 offset:62080
	s_waitcnt lgkmcnt(0)
	v_fmac_f32_e32 v223, v85, v222
	v_cndmask_b32_e64 v40, v85, v223, s[58:59]
	v_fmac_f32_e32 v225, v224, v40
	v_cndmask_b32_e64 v40, v40, v225, s[60:61]
	v_fmac_f32_e32 v227, v226, v40
	v_cndmask_b32_e64 v40, v40, v227, s[62:63]
	v_fmac_f32_e32 v229, v228, v40
	v_cndmask_b32_e64 v40, v40, v229, s[64:65]
	v_fmac_f32_e32 v235, v234, v40
	v_cndmask_b32_e64 v40, v40, v235, s[66:67]
	v_fmac_f32_e32 v237, v236, v40
	v_cndmask_b32_e64 v40, v40, v237, s[68:69]
	v_fmac_f32_e32 v239, v238, v40
	v_cndmask_b32_e64 v38, v40, v239, s[70:71]
	v_fmac_f32_e32 v36, v48, v38
	v_fmac_f32_e32 v37, v86, v36
	v_fmac_f32_e32 v94, v89, v37
	v_fmac_f32_e32 v96, v91, v94
	v_fmac_f32_e32 v98, v93, v96
	ds_write_b32 v185, v37
	ds_write_b32 v186, v94
	ds_write_b32 v187, v96
	ds_write_b32 v188, v98
	ds_read2st64_b64 v[36:39], v190 offset0:6 offset1:7
	s_waitcnt lgkmcnt(0)
; #define LAS __attribute__((address_space(3)))
; template <bool PHASE_B>
; __device__ __forceinline__ void lru_item(const Params& p, LAS unsigned char* lds, int ci, int ci_next, int jb, const int tid, v4u (&xvn)[3]) {
;     ...
;         for (int dir = 0; dir < 2; ++dir) { const int ot = dir ? 7 - rt : rt;
; #pragma unroll
;             for (int ct = 0; ct < 4; ++ct) { const int ch = 16 * ct + fr; float h = cin[dir][ct];
; #pragma unroll
;                 for (int q = 0; q < 7; ++q) { const f32x2 sh = ((const LAS f32x2*)(lds + LR_SEG))[(dir * 8 + (dir ? 7 - q : q)) * 64 + ch]; const float nh = sh.x * h + sh.y; h = (q < ot) ? nh : h; }
;                 h = pA[dir][ct] * h + pH[dir][ct];
; #pragma unroll
;                 for (int ee = 0; ee < 4; ++ee) { const int e = dir ? 3 - ee : ee; h = av[dir][ct][e] * h + uv[dir][ct][e];
;                     ((LAS float*)(lds + LR_HB))[(dir * LCH + 16 * rt + 4 * fq + e) * 68 + ch] = h; } } }
;         __syncthreads();
	v_fma_f32 v38, v76, v38, v39
	v_cndmask_b32_e64 v38, v76, v38, s[72:73]
	v_fmac_f32_e32 v37, v36, v38
	v_cndmask_b32_e64 v38, v38, v37, s[74:75]
	ds_read_b64 v[208:209], v176 offset:65280
	ds_read_b64 v[210:211], v176 offset:64768
	ds_read_b64 v[212:213], v176 offset:64256
	ds_read_b64 v[214:215], v176 offset:63744
	ds_read_b64 v[216:217], v176 offset:63232
	s_waitcnt lgkmcnt(0)
	v_fmac_f32_e32 v209, v208, v38
	v_cndmask_b32_e64 v38, v38, v209, s[76:77]
	v_fmac_f32_e32 v211, v210, v38
	v_cndmask_b32_e64 v38, v38, v211, s[78:79]
	v_fmac_f32_e32 v213, v212, v38
	v_cndmask_b32_e64 v38, v38, v213, s[80:81]
	v_fmac_f32_e32 v215, v214, v38
	v_cndmask_b32_e64 v38, v38, v215, s[82:83]
	v_fmac_f32_e32 v217, v216, v38
	v_cndmask_b32_e64 v36, v38, v217, s[84:85]
	v_fmac_f32_e32 v57, v55, v36
	v_fmac_f32_e32 v103, v100, v57
	v_fmac_f32_e32 v106, v105, v103
	v_fmac_f32_e32 v53, v51, v106
	v_add_u32_e32 v36, 0x8800, v202
	v_fmac_f32_e32 v110, v109, v53
	ds_write2_b32 v36, v106, v103 offset0:136 offset1:204
	ds_write2_b32 v36, v110, v53 offset1:68
	ds_read2st64_b64 v[36:39], v191 offset0:6 offset1:7
	v_lshlrev_b32_e32 v53, 16, v19
	v_and_b32_e32 v19, 0xffff0000, v19
	s_waitcnt lgkmcnt(0)
	v_fma_f32 v38, v74, v38, v39
	v_cndmask_b32_e64 v38, v74, v38, s[72:73]
	v_fmac_f32_e32 v37, v36, v38
	v_cndmask_b32_e64 v38, v38, v37, s[74:75]
	ds_read_b64 v[222:223], v176 offset:65408
	ds_read_b64 v[224:225], v176 offset:64896
	ds_read_b64 v[226:227], v176 offset:64384
	ds_read_b64 v[228:229], v176 offset:63872
	ds_read_b64 v[234:235], v176 offset:63360
	s_waitcnt lgkmcnt(0)
	v_fmac_f32_e32 v223, v222, v38
	v_cndmask_b32_e64 v38, v38, v223, s[76:77]
	v_fmac_f32_e32 v225, v224, v38
	v_cndmask_b32_e64 v38, v38, v225, s[78:79]
	v_fmac_f32_e32 v227, v226, v38
	v_cndmask_b32_e64 v38, v38, v227, s[80:81]
	v_fmac_f32_e32 v229, v228, v38
	v_cndmask_b32_e64 v38, v38, v229, s[82:83]
	v_fmac_f32_e32 v235, v234, v38
	v_cndmask_b32_e64 v36, v38, v235, s[84:85]
	v_fmac_f32_e32 v64, v62, v36
	v_fmac_f32_e32 v115, v112, v64
	v_fmac_f32_e32 v118, v117, v115
	v_fmac_f32_e32 v60, v58, v118
	v_add_u32_e32 v36, 0x8800, v203
	v_fmac_f32_e32 v122, v121, v60
	ds_write2_b32 v36, v118, v115 offset0:136 offset1:204
	ds_write2_b32 v36, v122, v60 offset1:68
	ds_read_b64 v[36:37], v192 offset:3584
	s_waitcnt lgkmcnt(0)
	v_fmac_f32_e32 v37, v73, v36
	v_cndmask_b32_e64 v40, v73, v37, s[72:73]
	ds_read2st64_b64 v[36:39], v192 offset0:5 offset1:6
	s_waitcnt lgkmcnt(0)
	v_fma_f32 v38, v38, v40, v39
	v_cndmask_b32_e64 v38, v40, v38, s[74:75]
	v_fmac_f32_e32 v37, v36, v38
	v_cndmask_b32_e64 v38, v38, v37, s[76:77]
	ds_read_b64 v[208:209], v176 offset:65024
	ds_read_b64 v[210:211], v176 offset:64512
	ds_read_b64 v[212:213], v176 offset:64000
	ds_read_b64 v[214:215], v176 offset:63488
	s_waitcnt lgkmcnt(0)
	v_fmac_f32_e32 v209, v208, v38
	v_cndmask_b32_e64 v38, v38, v209, s[78:79]
	v_fmac_f32_e32 v211, v210, v38
	v_cndmask_b32_e64 v38, v38, v211, s[80:81]
	v_fmac_f32_e32 v213, v212, v38
	v_cndmask_b32_e64 v38, v38, v213, s[82:83]
	v_fmac_f32_e32 v215, v214, v38
	v_cndmask_b32_e64 v36, v38, v215, s[84:85]
	v_fmac_f32_e32 v69, v26, v36
	v_fmac_f32_e32 v127, v124, v69
	v_fmac_f32_e32 v128, v29, v127
	v_fmac_f32_e32 v67, v28, v128
	v_add_u32_e32 v26, 0x8800, v204
	v_fmac_f32_e32 v130, v27, v67
	ds_write2_b32 v26, v128, v127 offset0:136 offset1:204
	ds_write2_b32 v26, v130, v67 offset1:68
	ds_read_b64 v[26:27], v194 offset:3584
	s_waitcnt lgkmcnt(0)
	v_fmac_f32_e32 v27, v71, v26
	v_cndmask_b32_e64 v36, v71, v27, s[72:73]
	ds_read2st64_b64 v[26:29], v194 offset0:5 offset1:6
	s_waitcnt lgkmcnt(0)
	v_fma_f32 v28, v28, v36, v29
	v_cndmask_b32_e64 v28, v36, v28, s[74:75]
	v_fmac_f32_e32 v27, v26, v28
	v_cndmask_b32_e64 v28, v28, v27, s[76:77]
	ds_read_b64 v[222:223], v176 offset:65152
	ds_read_b64 v[224:225], v176 offset:64640
	ds_read_b64 v[226:227], v176 offset:64128
	ds_read_b64 v[228:229], v176 offset:63616
	s_waitcnt lgkmcnt(0)
	v_fmac_f32_e32 v223, v222, v28
	v_cndmask_b32_e64 v28, v28, v223, s[78:79]
	v_fmac_f32_e32 v225, v224, v28
	v_cndmask_b32_e64 v28, v28, v225, s[80:81]
	v_fmac_f32_e32 v227, v226, v28
	v_cndmask_b32_e64 v28, v28, v227, s[82:83]
	v_fmac_f32_e32 v229, v228, v28
	v_cndmask_b32_e64 v26, v28, v229, s[84:85]
	v_fmac_f32_e32 v31, v22, v26
	v_fmac_f32_e32 v135, v132, v31
	v_fmac_f32_e32 v136, v25, v135
	v_fmac_f32_e32 v24, v1, v136
	v_add_u32_e32 v22, 0x8800, v205
	v_fmac_f32_e32 v138, v23, v24
	ds_write2_b32 v22, v136, v135 offset0:136 offset1:204
	ds_write2_b32 v22, v138, v24 offset1:68
	s_waitcnt lgkmcnt(0)
	s_barrier
; #define LAS __attribute__((address_space(3)))
; __device__ __forceinline__ unsigned pk2(float lo, float hi) { return f2bf(lo) | (f2bf(hi) << 16); }
; template <bool PHASE_B>
; __device__ __forceinline__ void lru_item(const Params& p, LAS unsigned char* lds, int ci, int ci_next, int jb, const int tid, v4u (&xvn)[3]) {
;     ...
;         { const int t = tid >> 2, c0 = (tid & 3) * 16; bf16* gp = (bf16*)(p.ws + WS_GR) + (size_t)(t0 + t) * 768 + jb * 64 + c0;
;           const LAS float* H0 = (const LAS float*)(lds + LR_HB) + t * 68 + c0; const LAS float* H1 = H0 + LCH * 68;
; #pragma unroll
;           for (int hf = 0; hf < 2; ++hf) { const f32x4 a0 = *(const LAS f32x4*)(H0 + 8 * hf), a1 = *(const LAS f32x4*)(H0 + 8 * hf + 4), b0 = *(const LAS f32x4*)(H1 + 8 * hf), b1 = *(const LAS f32x4*)(H1 + 8 * hf + 4);
;               const v4u g = gv[hf]; v4u o;
;               o.x = pk2(bflo(g.x) * (a0[0] + b0[0]), bfhi(g.x) * (a0[1] + b0[1])); o.y = pk2(bflo(g.y) * (a0[2] + b0[2]), bfhi(g.y) * (a0[3] + b0[3]));
;               o.z = pk2(bflo(g.z) * (a1[0] + b1[0]), bfhi(g.z) * (a1[1] + b1[1])); o.w = pk2(bflo(g.w) * (a1[2] + b1[2]), bfhi(g.w) * (a1[3] + b1[3]));
;               *(v4u*)(gp + 8 * hf) = o; } }
	ds_read_b128 v[22:25], v195
	ds_read_b128 v[26:29], v195 offset:16
	ds_read_b128 v[36:39], v195 offset:32
	ds_read_b128 v[40:43], v195 offset:48
	ds_read_b128 v[44:47], v195 offset:34816
	ds_read_b128 v[48:51], v195 offset:34832
	s_waitcnt lgkmcnt(1)
	v_pk_add_f32 v[24:25], v[24:25], v[46:47]
	v_pk_add_f32 v[22:23], v[22:23], v[44:45]
	v_mov_b32_e32 v45, v24
	v_mov_b32_e32 v24, v23
	v_pk_mul_f32 v[18:19], v[24:25], v[18:19]
	s_waitcnt lgkmcnt(0)
	v_pk_add_f32 v[24:25], v[28:29], v[50:51]
	v_pk_add_f32 v[26:27], v[26:27], v[48:49]
	v_mov_b32_e32 v44, v22
	v_lshlrev_b32_e32 v23, 16, v21
	v_lshlrev_b32_e32 v22, 16, v20
	v_mov_b32_e32 v29, v24
	v_and_b32_e32 v21, 0xffff0000, v21
	v_and_b32_e32 v20, 0xffff0000, v20
	v_mov_b32_e32 v24, v27
	v_mov_b32_e32 v28, v26
	v_pk_mul_f32 v[20:21], v[24:25], v[20:21]
	v_pk_mul_f32 v[44:45], v[44:45], v[52:53]
	v_pk_mul_f32 v[22:23], v[28:29], v[22:23]
	v_bfe_u32 v1, v21, 16, 1
	v_add3_u32 v1, v21, v1, s33
	v_bfe_u32 v26, v23, 16, 1
	v_add3_u32 v23, v23, v26, s33
	v_lshrrev_b32_e32 v21, 16, v23
	v_and_or_b32 v21, v1, s11, v21
	v_cvt_pk_bf16_f32 v20, v22, v20
	v_cvt_pk_bf16_f32 v19, v45, v19
	v_cvt_pk_bf16_f32 v18, v44, v18
	global_store_dwordx4 v[140:141], v[18:21], off
	ds_read_b128 v[18:21], v195 offset:34848
	ds_read_b128 v[22:25], v195 offset:34864
	v_lshlrev_b32_e32 v27, 16, v15
	v_lshlrev_b32_e32 v26, 16, v14
	v_and_b32_e32 v15, 0xffff0000, v15
	s_waitcnt lgkmcnt(1)
	v_pk_add_f32 v[20:21], v[38:39], v[20:21]
	v_pk_add_f32 v[18:19], v[36:37], v[18:19]
	v_mov_b32_e32 v29, v20
	v_and_b32_e32 v14, 0xffff0000, v14
	v_mov_b32_e32 v20, v19
	v_pk_mul_f32 v[14:15], v[20:21], v[14:15]
	s_waitcnt lgkmcnt(0)
	v_pk_add_f32 v[20:21], v[42:43], v[24:25]
	v_pk_add_f32 v[22:23], v[40:41], v[22:23]
	v_mov_b32_e32 v28, v18
	v_lshlrev_b32_e32 v19, 16, v17
	v_lshlrev_b32_e32 v18, 16, v16
	v_mov_b32_e32 v25, v20
	v_and_b32_e32 v17, 0xffff0000, v17
	v_and_b32_e32 v16, 0xffff0000, v16
	v_mov_b32_e32 v20, v23
	v_mov_b32_e32 v24, v22
	v_pk_mul_f32 v[16:17], v[20:21], v[16:17]
	v_pk_mul_f32 v[26:27], v[28:29], v[26:27]
	v_pk_mul_f32 v[18:19], v[24:25], v[18:19]
	v_bfe_u32 v1, v17, 16, 1
	v_bfe_u32 v20, v16, 16, 1
	v_add3_u32 v16, v16, v20, s33
	v_add3_u32 v1, v17, v1, s33
	v_bfe_u32 v21, v18, 16, 1
	v_bfe_u32 v22, v19, 16, 1
	v_add3_u32 v19, v19, v22, s33
	v_add3_u32 v18, v18, v21, s33
	v_lshrrev_b32_e32 v21, 16, v17
	v_lshrrev_b32_e32 v20, 16, v20
	v_lshrrev_b32_e32 v18, 16, v18
	v_lshrrev_b32_e32 v17, 16, v19
	v_and_or_b32 v17, v1, s11, v17
	v_and_or_b32 v16, v16, s11, v18
	v_cvt_pk_bf16_f32 v15, v27, v15
	v_cvt_pk_bf16_f32 v14, v26, v14
	global_store_dwordx4 v[140:141], v[14:17], off offset:16
	s_cbranch_vccnz .LBB0_353

; #define LAS __attribute__((address_space(3)))
; __device__ __forceinline__ unsigned pk2(float lo, float hi) { return f2bf(lo) | (f2bf(hi) << 16); }
; template <bool PHASE_B>
; __device__ __forceinline__ void lru_item(const Params& p, LAS unsigned char* lds, int ci, int ci_next, int jb, const int tid, v4u (&xvn)[3]) {
;     ...
;     for (int ks = 0; ks < 2; ++ks) { const int cb0 = 32 * ks + 8 * fq;
;         f32x4 s0 = *(const LAS f32x4*)(CB + cb0), s1 = *(const LAS f32x4*)(CB + cb0 + 4);
; #pragma unroll
;         for (int tap = 0; tap < 4; ++tap) { const v4u v = *(const LAS v4u*)(lds + LR_XR + (16 * rt + fr + tap) * 144 + cb0 * 2);
;             const f32x4 w0 = *(const LAS f32x4*)(CW + tap * 64 + cb0), w1 = *(const LAS f32x4*)(CW + tap * 64 + cb0 + 4);
;             s0 += (f32x4){bflo(v.x), bfhi(v.x), bflo(v.y), bfhi(v.y)} * w0; s1 += (f32x4){bflo(v.z), bfhi(v.z), bflo(v.w), bfhi(v.w)} * w1; }
;         v4u o; o.x = pk2(s0[0], s0[1]); o.y = pk2(s0[2], s0[3]); o.z = pk2(s1[0], s1[1]); o.w = pk2(s1[2], s1[3]);
;         af[ks] = __builtin_bit_cast(bf16x8, o); }
.LBB0_541:
	ds_read_b128 v[14:17], v88
	ds_read_b128 v[18:21], v78 offset:56832
	ds_read_b128 v[26:29], v78 offset:56848
	ds_read_b128 v[30:33], v78 offset:55808
	ds_read_b128 v[34:37], v78 offset:55824
	ds_read_b128 v[38:41], v88 offset:144
	s_waitcnt lgkmcnt(5)
	v_lshlrev_b32_e32 v42, 16, v14
	v_and_b32_e32 v43, 0xffff0000, v14
	v_lshlrev_b32_e32 v14, 16, v15
	v_and_b32_e32 v15, 0xffff0000, v15
	s_waitcnt lgkmcnt(2)
	v_pk_fma_f32 v[32:33], v[32:33], v[14:15], v[20:21]
	v_lshlrev_b32_e32 v14, 16, v16
	v_and_b32_e32 v15, 0xffff0000, v16
	v_lshlrev_b32_e32 v16, 16, v17
	v_and_b32_e32 v17, 0xffff0000, v17
	v_pk_fma_f32 v[30:31], v[30:31], v[42:43], v[18:19]
	s_waitcnt lgkmcnt(1)
	v_pk_fma_f32 v[26:27], v[34:35], v[14:15], v[26:27]
	v_pk_fma_f32 v[28:29], v[36:37], v[16:17], v[28:29]
	ds_read_b128 v[14:17], v78 offset:56064
	ds_read_b128 v[18:21], v78 offset:56080
	s_waitcnt lgkmcnt(2)
	v_lshlrev_b32_e32 v34, 16, v38
	v_and_b32_e32 v35, 0xffff0000, v38
	v_lshlrev_b32_e32 v36, 16, v39
	v_and_b32_e32 v37, 0xffff0000, v39
	s_waitcnt lgkmcnt(1)
	v_pk_fma_f32 v[34:35], v[14:15], v[34:35], v[30:31]
	v_lshlrev_b32_e32 v14, 16, v41
	v_and_b32_e32 v15, 0xffff0000, v41
	v_pk_fma_f32 v[36:37], v[16:17], v[36:37], v[32:33]
	s_waitcnt lgkmcnt(0)
	v_pk_fma_f32 v[38:39], v[20:21], v[14:15], v[28:29]
	ds_read_b128 v[14:17], v88 offset:288
	v_lshlrev_b32_e32 v30, 16, v40
	v_and_b32_e32 v31, 0xffff0000, v40
	v_pk_fma_f32 v[40:41], v[18:19], v[30:31], v[26:27]
	ds_read_b128 v[18:21], v78 offset:56320
	ds_read_b128 v[26:29], v78 offset:56336
	ds_read_b128 v[30:33], v88 offset:432
	s_waitcnt lgkmcnt(3)
	v_lshlrev_b32_e32 v42, 16, v14
	v_and_b32_e32 v43, 0xffff0000, v14
	v_lshlrev_b32_e32 v14, 16, v15
	v_and_b32_e32 v15, 0xffff0000, v15
	s_waitcnt lgkmcnt(2)
	v_pk_fma_f32 v[36:37], v[20:21], v[14:15], v[36:37]
	v_lshlrev_b32_e32 v14, 16, v16
	v_and_b32_e32 v15, 0xffff0000, v16
	v_lshlrev_b32_e32 v16, 16, v17
	v_and_b32_e32 v17, 0xffff0000, v17
	v_pk_fma_f32 v[34:35], v[18:19], v[42:43], v[34:35]
	s_waitcnt lgkmcnt(1)
	v_pk_fma_f32 v[26:27], v[26:27], v[14:15], v[40:41]
	v_pk_fma_f32 v[28:29], v[28:29], v[16:17], v[38:39]
	ds_read_b128 v[14:17], v78 offset:56576
	ds_read_b128 v[18:21], v78 offset:56592
	s_waitcnt lgkmcnt(2)
	v_lshlrev_b32_e32 v38, 16, v30
	v_and_b32_e32 v39, 0xffff0000, v30
	v_lshlrev_b32_e32 v30, 16, v31
	s_waitcnt lgkmcnt(1)
	v_pk_fma_f32 v[14:15], v[14:15], v[38:39], v[34:35]
	v_and_b32_e32 v31, 0xffff0000, v31
	v_bfe_u32 v1, v14, 16, 1
	v_add3_u32 v1, v14, v1, s33
	v_bfe_u32 v14, v15, 16, 1
	v_pk_fma_f32 v[16:17], v[16:17], v[30:31], v[36:37]
	v_lshrrev_b32_e32 v1, 16, v1
	v_add3_u32 v14, v15, v14, s33
	v_and_or_b32 v14, v14, s11, v1
	v_lshlrev_b32_e32 v30, 16, v32
	v_and_b32_e32 v31, 0xffff0000, v32
	s_waitcnt lgkmcnt(0)
	v_pk_fma_f32 v[18:19], v[18:19], v[30:31], v[26:27]
	v_cvt_pk_bf16_f32 v15, v16, v17
	v_lshlrev_b32_e32 v32, 16, v33
	v_and_b32_e32 v33, 0xffff0000, v33
	v_pk_fma_f32 v[20:21], v[20:21], v[32:33], v[28:29]
	v_cvt_pk_bf16_f32 v16, v18, v19
	v_bfe_u32 v1, v20, 16, 1
	v_bfe_u32 v17, v21, 16, 1
	v_add3_u32 v1, v20, v1, s33
	v_add3_u32 v17, v21, v17, s33
	ds_read_b128 v[18:21], v89
	ds_read_b128 v[26:29], v78 offset:56960
	ds_read_b128 v[30:33], v78 offset:56976
	ds_read_b128 v[34:37], v78 offset:55936
	ds_read_b128 v[38:41], v78 offset:55952
	ds_read_b128 v[42:45], v89 offset:144
	s_waitcnt lgkmcnt(5)
	v_lshlrev_b32_e32 v46, 16, v18
	v_and_b32_e32 v47, 0xffff0000, v18
	v_lshlrev_b32_e32 v18, 16, v19
	v_and_b32_e32 v19, 0xffff0000, v19
	s_waitcnt lgkmcnt(2)
	v_pk_fma_f32 v[36:37], v[36:37], v[18:19], v[28:29]
	v_lshlrev_b32_e32 v18, 16, v20
	v_and_b32_e32 v19, 0xffff0000, v20
	v_lshlrev_b32_e32 v20, 16, v21
	v_and_b32_e32 v21, 0xffff0000, v21
	v_pk_fma_f32 v[34:35], v[34:35], v[46:47], v[26:27]
	s_waitcnt lgkmcnt(1)
	v_pk_fma_f32 v[30:31], v[38:39], v[18:19], v[30:31]
	v_pk_fma_f32 v[32:33], v[40:41], v[20:21], v[32:33]
	ds_read_b128 v[18:21], v78 offset:56192
	ds_read_b128 v[26:29], v78 offset:56208
	s_waitcnt lgkmcnt(2)
	v_lshlrev_b32_e32 v38, 16, v42
	v_and_b32_e32 v39, 0xffff0000, v42
	v_lshlrev_b32_e32 v40, 16, v43
	v_and_b32_e32 v41, 0xffff0000, v43
	s_waitcnt lgkmcnt(1)
	v_pk_fma_f32 v[38:39], v[18:19], v[38:39], v[34:35]
	v_lshlrev_b32_e32 v18, 16, v45
	v_and_b32_e32 v19, 0xffff0000, v45
	v_pk_fma_f32 v[40:41], v[20:21], v[40:41], v[36:37]
	s_waitcnt lgkmcnt(0)
	v_pk_fma_f32 v[42:43], v[28:29], v[18:19], v[32:33]
	ds_read_b128 v[18:21], v89 offset:288
	v_lshlrev_b32_e32 v34, 16, v44
	v_and_b32_e32 v35, 0xffff0000, v44
	v_pk_fma_f32 v[44:45], v[26:27], v[34:35], v[30:31]
	ds_read_b128 v[26:29], v78 offset:56448
	ds_read_b128 v[30:33], v78 offset:56464
	ds_read_b128 v[34:37], v89 offset:432
	s_waitcnt lgkmcnt(3)
	v_lshlrev_b32_e32 v46, 16, v18
	v_and_b32_e32 v47, 0xffff0000, v18
	v_lshlrev_b32_e32 v18, 16, v19
	v_and_b32_e32 v19, 0xffff0000, v19
	s_waitcnt lgkmcnt(2)
	v_pk_fma_f32 v[40:41], v[28:29], v[18:19], v[40:41]
	v_lshlrev_b32_e32 v18, 16, v20
	v_and_b32_e32 v19, 0xffff0000, v20
	v_lshlrev_b32_e32 v20, 16, v21
	v_and_b32_e32 v21, 0xffff0000, v21
	v_pk_fma_f32 v[38:39], v[26:27], v[46:47], v[38:39]
	s_waitcnt lgkmcnt(1)
	v_pk_fma_f32 v[30:31], v[30:31], v[18:19], v[44:45]
	v_pk_fma_f32 v[32:33], v[32:33], v[20:21], v[42:43]
	ds_read_b128 v[18:21], v78 offset:56704
	ds_read_b128 v[26:29], v78 offset:56720
	s_waitcnt lgkmcnt(2)
	v_lshlrev_b32_e32 v42, 16, v34
	v_and_b32_e32 v43, 0xffff0000, v34
	v_lshlrev_b32_e32 v34, 16, v35
	s_waitcnt lgkmcnt(1)
; #define LAS __attribute__((address_space(3)))
; #define MFMA16(a, b, c) __builtin_amdgcn_mfma_f32_16x16x32_bf16(a, b, c, 0, 0, 0)
; template <bool PHASE_B>
; __device__ __forceinline__ void lru_item(const Params& p, LAS unsigned char* lds, int ci, int ci_next, int jb, const int tid, v4u (&xvn)[3]) {
;     ...
;     float xc[4][4];
; #pragma unroll
;     for (int ct = 0; ct < 4; ++ct) { const int ch = 16 * ct + fr; float xr7[7];
; #pragma unroll
;         for (int j = 0; j < 7; ++j) xr7[j] = __builtin_bit_cast(float, (unsigned)(*(const LAS bf16*)(lds + LR_XR + (16 * rt + 4 * fq + j) * 144 + ch * 2)) << 16);
;         const float w0 = CW[ch], w1 = CW[64 + ch], w2 = CW[128 + ch], w3 = CW[192 + ch], b = CB[ch];
; #pragma unroll
;         for (int e = 0; e < 4; ++e) xc[ct][e] = b + xr7[e] * w0 + xr7[e + 1] * w1 + xr7[e + 2] * w2 + xr7[e + 3] * w3; }
;     float av[2][4][4], uv[2][4][4], pA[2][4], pH[2][4];
; #pragma unroll
;     for (int dir = 0; dir < 2; ++dir) {
; #pragma unroll
;         for (int ct = 0; ct < 4; ++ct) {
;             f32x4 ga = (f32x4){0.f, 0.f, 0.f, 0.f}, gx = (f32x4){0.f, 0.f, 0.f, 0.f};
; #pragma unroll
;             for (int ks = 0; ks < 2; ++ks) {
;                 const bf16x8 wa = *(const LAS bf16x8*)(lds + LR_WG + ((dir * 2 + 0) * 64 + 16 * ct + fr) * 144 + (32 * ks + 8 * fq) * 2);
;                 const bf16x8 wx = *(const LAS bf16x8*)(lds + LR_WG + ((dir * 2 + 1) * 64 + 16 * ct + fr) * 144 + (32 * ks + 8 * fq) * 2);
;                 ga = MFMA16(af[ks], wa, ga); gx = MFMA16(af[ks], wx, gx); }
;             const int ch = 16 * ct + fr; const float bav = GC[(dir * 3 + 0) * 64 + ch], bxv = GC[(dir * 3 + 1) * 64 + ch], c8 = GC[(dir * 3 + 2) * 64 + ch];
;             float Al = 1.f, Hl = 0.f;
; #pragma unroll
;             for (int ee = 0; ee < 4; ++ee) { const int e = dir ? 3 - ee : ee;
;                 const float r = __builtin_amdgcn_rcpf(1.f + __expf(-(ga[e] + bav))), ig = __builtin_amdgcn_rcpf(1.f + __expf(-(gx[e] + bxv)));
;                 const float la = -c8 * r; const float a = __expf(la); const float u = __builtin_amdgcn_sqrtf((1.f - a) * (1.f + a)) * (ig * xc[ct][e]);
;                 av[dir][ct][e] = a; uv[dir][ct][e] = u; Hl = a * Hl + u; Al *= a; }
	v_pk_fma_f32 v[18:19], v[18:19], v[42:43], v[38:39]
	v_and_b32_e32 v35, 0xffff0000, v35
	v_pk_fma_f32 v[20:21], v[20:21], v[34:35], v[40:41]
	v_cvt_pk_bf16_f32 v18, v18, v19
	v_bfe_u32 v19, v20, 16, 1
	v_lshlrev_b32_e32 v34, 16, v36
	v_and_b32_e32 v35, 0xffff0000, v36
	v_lshlrev_b32_e32 v36, 16, v37
	v_and_b32_e32 v37, 0xffff0000, v37
	v_add3_u32 v19, v20, v19, s33
	v_bfe_u32 v20, v21, 16, 1
	s_waitcnt lgkmcnt(0)
	v_pk_fma_f32 v[28:29], v[28:29], v[36:37], v[32:33]
	v_pk_fma_f32 v[26:27], v[26:27], v[34:35], v[30:31]
	v_lshrrev_b32_e32 v19, 16, v19
	v_add3_u32 v20, v21, v20, s33
	v_and_or_b32 v19, v20, s11, v19
	v_bfe_u32 v20, v26, 16, 1
	v_bfe_u32 v23, v29, 16, 1
	v_add3_u32 v20, v26, v20, s33
	v_bfe_u32 v21, v27, 16, 1
	v_add3_u32 v32, v29, v23, s33
	v_add_u32_e32 v23, v80, v81
	v_add_u32_e32 v30, 0xd800, v82
	v_add_u32_e32 v58, 0xdc00, v82
	v_lshrrev_b32_e32 v20, 16, v20
	v_add3_u32 v21, v27, v21, s33
	ds_read_u16 v49, v23
	ds_read_u16 v51, v23 offset:144
	ds_read_u16 v60, v23 offset:288
	ds_read_u16 v26, v23 offset:864
	ds_read_u16 v70, v23 offset:432
	ds_read_u16 v109, v23 offset:576
	ds_read_u16 v116, v90
	ds_read_u16 v110, v23 offset:720
	ds_read2_b32 v[46:47], v30 offset0:128 offset1:144
	ds_read2_b32 v[40:41], v30 offset0:192 offset1:208
	ds_read2_b32 v[52:53], v58 offset1:16
	ds_read2_b32 v[44:45], v58 offset0:64 offset1:80
	ds_read2_b32 v[34:35], v58 offset0:128 offset1:144
	ds_read_u16 v117, v90 offset:144
	ds_read_u16 v118, v90 offset:288
	ds_read_u16 v119, v90 offset:432
	ds_read_u16 v23, v90 offset:864
	ds_read_u16 v120, v90 offset:576
	ds_read_u16 v123, v91
	ds_read_u16 v122, v91 offset:144
	ds_read_u16 v121, v90 offset:720
	v_and_or_b32 v20, v21, s11, v20
	v_bfe_u32 v21, v28, 16, 1
	s_waitcnt lgkmcnt(4)
	v_lshlrev_b32_e32 v50, 16, v23
	v_add_u32_e32 v23, v85, v79
	v_add3_u32 v21, v28, v21, s33
	v_lshlrev_b32_e32 v48, 16, v26
	ds_read_u16 v124, v91 offset:288
	ds_read_u16 v125, v91 offset:432
	ds_read_u16 v126, v91 offset:576
	ds_read_u16 v127, v91 offset:720
	ds_read_u16 v31, v91 offset:864
	ds_read_u16 v43, v92
	ds_read_u16 v61, v92 offset:144
	ds_read_u16 v103, v92 offset:288
	ds_read_b128 v[26:29], v23 offset:18944
	v_perm_b32 v17, v17, v1, s65
	ds_read2_b32 v[38:39], v30 offset0:160 offset1:176
	ds_read_b128 v[54:57], v23 offset:28160
	ds_read_b128 v[62:65], v23 offset:19008
	v_perm_b32 v21, v32, v21, s65
	s_waitcnt lgkmcnt(3)
	v_mfma_f32_16x16x32_bf16 v[66:69], v[14:17], v[26:29], 0
	v_lshlrev_b32_e32 v42, 16, v31
	ds_read2_b32 v[30:31], v30 offset0:224 offset1:240
	ds_read_b128 v[104:107], v23 offset:28224
	ds_read2_b32 v[36:37], v58 offset0:32 offset1:48
	ds_read2_b32 v[32:33], v58 offset0:96 offset1:112
	ds_read2_b32 v[26:27], v58 offset0:160 offset1:176
	s_waitcnt lgkmcnt(6)
	v_mfma_f32_16x16x32_bf16 v[54:57], v[14:17], v[54:57], 0
	v_lshlrev_b32_e32 v71, 16, v49
	v_lshlrev_b32_e32 v122, 16, v122
	v_lshlrev_b32_e32 v123, 16, v123
	s_waitcnt lgkmcnt(5)
	v_mfma_f32_16x16x32_bf16 v[62:65], v[18:21], v[62:65], v[66:69]
	s_nop 2
	ds_read_b32 v66, v93 offset:57088
	ds_read_u16 v128, v92 offset:432
	ds_read_u16 v102, v92 offset:576
	ds_read_u16 v29, v92 offset:720
	ds_read_u16 v1, v92 offset:864
	v_mov_b32_e32 v67, v46
	s_waitcnt lgkmcnt(4)
	v_add_f32_e32 v28, v62, v66
	v_mfma_f32_16x16x32_bf16 v[56:59], v[18:21], v[104:107], v[54:57]
	ds_read_b32 v217, v93 offset:57344
	ds_read_b32 v218, v93 offset:57600
	ds_read_b32 v219, v93 offset:57152
	ds_read_b128 v[198:201], v23 offset:21248
	ds_read_b128 v[202:205], v23 offset:21312
	ds_read_b128 v[206:209], v23 offset:30464
	ds_read_b128 v[210:213], v23 offset:30528
	s_nop 2
	v_mul_f32_e32 v28, 0xbfb8aa3b, v28
	v_exp_f32_e32 v28, v28
	s_waitcnt lgkmcnt(1)
	v_add_f32_e32 v56, v56, v217
	v_mul_f32_e32 v56, 0xbfb8aa3b, v56
	v_exp_f32_e32 v56, v56
	v_add_f32_e32 v28, 1.0, v28
	v_rcp_f32_e32 v62, v28
	v_lshlrev_b32_e32 v28, 16, v1
	v_add_f32_e32 v1, 1.0, v56
	v_rcp_f32_e32 v129, v1
	s_waitcnt lgkmcnt(0)
	v_mul_f32_e32 v1, v62, v218
	v_mul_f32_e32 v1, 0xbfb8aa3b, v1
	v_exp_f32_e32 v56, v1
	v_add_f32_e32 v1, v63, v66
	v_mul_f32_e32 v1, 0xbfb8aa3b, v1
	v_exp_f32_e32 v1, v1
	v_add_f32_e32 v57, v57, v217
	v_sub_f32_e32 v62, 1.0, v56
	v_add_f32_e32 v63, 1.0, v56
	v_add_f32_e32 v1, 1.0, v1
	v_rcp_f32_e32 v1, v1
	v_mul_f32_e32 v57, 0xbfb8aa3b, v57
	v_mul_f32_e32 v62, v62, v63
	v_exp_f32_e32 v57, v57
	v_mul_f32_e32 v1, v1, v218
	v_mul_f32_e32 v1, 0xbfb8aa3b, v1
	v_exp_f32_e32 v130, v1
	v_sqrt_f32_e32 v1, v62
	v_add_f32_e32 v62, v64, v66
	v_mul_f32_e32 v62, 0xbfb8aa3b, v62
	v_exp_f32_e32 v62, v62
	v_add_f32_e32 v57, 1.0, v57
	v_rcp_f32_e32 v131, v57
	v_sub_f32_e32 v57, 1.0, v130
	v_add_f32_e32 v63, 1.0, v130
	v_mul_f32_e32 v57, v57, v63
	v_sqrt_f32_e32 v63, v57
	v_add_f32_e32 v57, 1.0, v62
	v_rcp_f32_e32 v57, v57
	v_add_f32_e32 v58, v58, v217
	v_mul_f32_e32 v58, 0xbfb8aa3b, v58
	v_exp_f32_e32 v58, v58
	v_mul_f32_e32 v57, v57, v218
	v_mul_f32_e32 v57, 0xbfb8aa3b, v57
	v_exp_f32_e32 v105, v57
	v_add_f32_e32 v62, v65, v66
	v_mul_f32_e32 v62, 0xbfb8aa3b, v62
	v_exp_f32_e32 v62, v62
	v_add_f32_e32 v58, 1.0, v58
	v_rcp_f32_e32 v132, v58
	v_sub_f32_e32 v58, 1.0, v105
	v_add_f32_e32 v64, 1.0, v105
	v_mul_f32_e32 v58, v58, v64
	v_sqrt_f32_e32 v65, v58
	v_add_f32_e32 v58, 1.0, v62
	v_rcp_f32_e32 v58, v58
	v_add_f32_e32 v54, v59, v217
	v_mul_f32_e32 v54, 0xbfb8aa3b, v54
	v_exp_f32_e32 v54, v54
	v_mul_f32_e32 v55, v58, v218
	v_mul_f32_e32 v55, 0xbfb8aa3b, v55
	v_exp_f32_e32 v59, v55
	v_add_f32_e32 v54, 1.0, v54
	v_rcp_f32_e32 v58, v54
	v_mov_b32_e32 v66, v40
	v_sub_f32_e32 v54, 1.0, v59
	v_add_f32_e32 v55, 1.0, v59
	v_mul_f32_e32 v54, v54, v55
	v_sqrt_f32_e32 v133, v54
	v_lshlrev_b32_e32 v55, 16, v60
; template <bool PHASE_B>
; __device__ __forceinline__ void lru_item(const Params& p, LAS unsigned char* lds, int ci, int ci_next, int jb, const int tid, v4u (&xvn)[3]) {
;     ...
;     for (int ct = 0; ct < 4; ++ct) { const int ch = 16 * ct + fr; float xr7[7];
; #pragma unroll
;         for (int j = 0; j < 7; ++j) xr7[j] = __builtin_bit_cast(float, (unsigned)(*(const LAS bf16*)(lds + LR_XR + (16 * rt + 4 * fq + j) * 144 + ch * 2)) << 16);
;         const float w0 = CW[ch], w1 = CW[64 + ch], w2 = CW[128 + ch], w3 = CW[192 + ch], b = CB[ch];
; #pragma unroll
;         for (int e = 0; e < 4; ++e) xc[ct][e] = b + xr7[e] * w0 + xr7[e + 1] * w1 + xr7[e + 2] * w2 + xr7[e + 3] * w3; }
;     float av[2][4][4], uv[2][4][4], pA[2][4], pH[2][4];
; #pragma unroll
;     for (int dir = 0; dir < 2; ++dir) {
; #pragma unroll
;         for (int ct = 0; ct < 4; ++ct) {
;             f32x4 ga = (f32x4){0.f, 0.f, 0.f, 0.f}, gx = (f32x4){0.f, 0.f, 0.f, 0.f};
; #pragma unroll
;             for (int ks = 0; ks < 2; ++ks) {
;                 const bf16x8 wa = *(const LAS bf16x8*)(lds + LR_WG + ((dir * 2 + 0) * 64 + 16 * ct + fr) * 144 + (32 * ks + 8 * fq) * 2);
;                 const bf16x8 wx = *(const LAS bf16x8*)(lds + LR_WG + ((dir * 2 + 1) * 64 + 16 * ct + fr) * 144 + (32 * ks + 8 * fq) * 2);
;                 ga = MFMA16(af[ks], wa, ga); gx = MFMA16(af[ks], wx, gx); }
;             const int ch = 16 * ct + fr; const float bav = GC[(dir * 3 + 0) * 64 + ch], bxv = GC[(dir * 3 + 1) * 64 + ch], c8 = GC[(dir * 3 + 2) * 64 + ch];
;             float Al = 1.f, Hl = 0.f;
; #pragma unroll
;             for (int ee = 0; ee < 4; ++ee) { const int e = dir ? 3 - ee : ee;
;                 const float r = __builtin_amdgcn_rcpf(1.f + __expf(-(ga[e] + bav))), ig = __builtin_amdgcn_rcpf(1.f + __expf(-(gx[e] + bxv)));
;                 const float la = -c8 * r; const float a = __expf(la); const float u = __builtin_amdgcn_sqrtf((1.f - a) * (1.f + a)) * (ig * xc[ct][e]);
;                 av[dir][ct][e] = a; uv[dir][ct][e] = u; Hl = a * Hl + u; Al *= a; }
;             const int o = dir ? 3 - fq : fq; const bool odd = (o & 1) != 0, hi2 = (o & 2) != 0;
;             const float A1 = __shfl_xor(Al, 16), H1 = __shfl_xor(Hl, 16);
;             const float pxA = odd ? A1 : 1.f, pxH = odd ? H1 : 0.f;
;             const float gA = Al * A1, gH = odd ? (Al * H1 + Hl) : (A1 * Hl + H1);
	v_lshlrev_b32_e32 v54, 16, v70
	v_lshlrev_b32_e32 v70, 16, v51
	v_pk_mul_f32 v[106:107], v[66:67], v[70:71]
	v_pk_mov_b32 v[70:71], v[54:55], v[70:71] op_sel:[1,0]
	v_pk_mul_f32 v[68:69], v[66:67], v[54:55]
	v_pk_mul_f32 v[66:67], v[66:67], v[70:71]
	v_add_f32_e32 v49, v107, v34
	v_add_f32_e32 v51, v67, v34
	v_mov_b32_e32 v62, v40
	v_add_f32_e32 v40, v69, v34
	v_fma_f32 v108, v46, v54, v34
	v_add_f32_e32 v34, v106, v49
	v_add_f32_e32 v46, v66, v51
	v_lshlrev_b32_e32 v107, 16, v109
	v_lshlrev_b32_e32 v106, 16, v110
	v_mov_b32_e32 v66, v44
	v_mov_b32_e32 v67, v52
	v_pk_mul_f32 v[110:111], v[66:67], v[54:55]
	v_pk_mov_b32 v[54:55], v[106:107], v[54:55] op_sel:[1,0]
	v_add_f32_e32 v40, v68, v40
	v_pk_mul_f32 v[112:113], v[66:67], v[54:55]
	v_pk_mul_f32 v[114:115], v[66:67], v[106:107]
	v_add_f32_e32 v49, v113, v46
	v_lshlrev_b32_e32 v67, 16, v118
	v_lshlrev_b32_e32 v66, 16, v119
	v_mov_b32_e32 v46, v41
	v_lshlrev_b32_e32 v68, 16, v117
	v_lshlrev_b32_e32 v69, 16, v116
	v_pk_mul_f32 v[70:71], v[46:47], v[68:69]
	v_pk_mov_b32 v[68:69], v[66:67], v[68:69] op_sel:[1,0]
	v_mul_f32_e32 v57, v56, v130
	v_pk_mul_f32 v[68:69], v[46:47], v[68:69]
	v_mul_f32_e32 v57, v105, v57
	v_mul_f32_e32 v104, v52, v106
	v_pk_mul_f32 v[54:55], v[46:47], v[66:67]
	v_add_f32_e32 v52, v71, v35
	v_add_f32_e32 v46, v69, v35
	v_mov_b32_e32 v64, v44
	v_mul_f32_e32 v44, v59, v57
	v_add_f32_e32 v113, v115, v40
	v_add_f32_e32 v40, v55, v35
	v_fmac_f32_e32 v35, v47, v66
	v_add_f32_e32 v55, v70, v52
	v_add_f32_e32 v57, v68, v46
	v_lshlrev_b32_e32 v47, 16, v120
	v_lshlrev_b32_e32 v46, 16, v121
	v_mov_b32_e32 v52, v45
	v_add_f32_e32 v34, v111, v34
	v_pk_mul_f32 v[70:71], v[52:53], v[66:67]
	v_pk_mov_b32 v[66:67], v[46:47], v[66:67] op_sel:[1,0]
	v_add_f32_e32 v34, v110, v34
	v_pk_mul_f32 v[68:69], v[52:53], v[66:67]
	v_add_f32_e32 v40, v54, v40
	v_add_f32_e32 v69, v69, v57
	v_mul_f32_e32 v57, v34, v129
	v_mul_f32_e32 v54, v53, v46
	v_pk_mul_f32 v[66:67], v[52:53], v[46:47]
	v_pk_mul_f32 v[52:53], v[56:57], v[0:1]
	v_add_f32_e32 v67, v67, v40
	v_add_f32_e32 v1, v52, v53
	v_add_f32_e32 v40, v112, v49
	v_mul_f32_e32 v109, v130, v1
	v_mul_f32_e32 v53, v40, v131
	v_mov_b32_e32 v52, v107
	v_pk_fma_f32 v[52:53], v[62:63], v[52:53], v[108:109]
	v_add_f32_e32 v46, v114, v113
	v_pk_add_f32 v[56:57], v[104:105], v[52:53]
	v_pk_mul_f32 v[52:53], v[104:105], v[52:53]
	v_mul_f32_e32 v49, v46, v132
	v_mov_b32_e32 v57, v53
	v_pk_fma_f32 v[52:53], v[64:65], v[48:49], v[56:57]
	ds_bpermute_b32 v51, v83, v44
	v_pk_mul_f32 v[48:49], v[52:53], v[58:59]
	v_lshlrev_b32_e32 v121, 16, v124
	v_fmac_f32_e32 v49, v48, v133
	ds_bpermute_b32 v1, v83, v49
	s_waitcnt lgkmcnt(1)
	v_mul_f32_e32 v60, v44, v51
	ds_bpermute_b32 v111, v84, v60
	v_lshlrev_b32_e32 v120, 16, v125
	v_mov_b32_e32 v116, v30
	s_waitcnt lgkmcnt(1)
	v_fma_f32 v44, v44, v1, v49
	v_fmac_f32_e32 v1, v49, v51
	v_cndmask_b32_e64 v1, v44, v1, s[42:43]
	ds_bpermute_b32 v44, v84, v1
	v_mov_b32_e32 v117, v38
	v_pk_mul_f32 v[58:59], v[116:117], v[122:123]
	v_pk_mov_b32 v[56:57], v[120:121], v[122:123] op_sel:[1,0]
	v_pk_mul_f32 v[118:119], v[116:117], v[120:121]
	v_add_f32_e32 v48, v59, v26
	v_pk_mul_f32 v[62:63], v[116:117], v[56:57]
	v_add_f32_e32 v71, v71, v55
	v_add_f32_e32 v55, v119, v26
	v_add_f32_e32 v49, v63, v26
	v_fma_f32 v56, v38, v120, v26
	v_add_f32_e32 v26, v58, v48
	s_waitcnt lgkmcnt(0)
	v_fma_f32 v48, v60, v44, v1
	v_fmac_f32_e32 v44, v1, v111
	v_mul_f32_e32 v106, v60, v111
	v_cndmask_b32_e64 v107, v48, v44, s[44:45]
	ds_write_b64 v86, v[106:107] offset:58624
	v_add_f32_e32 v38, v62, v49
	s_waitcnt lgkmcnt(2)
	v_mfma_f32_16x16x32_bf16 v[112:115], v[14:17], v[198:201], 0
	v_mov_b32_e32 v122, v32
	v_mov_b32_e32 v123, v36
	v_lshlrev_b32_e32 v58, 16, v127
	v_pk_mul_f32 v[62:63], v[122:123], v[120:121]
	v_add_f32_e32 v53, v118, v55
	v_mul_f32_e32 v60, v36, v58
	v_add_f32_e32 v36, v63, v26
	s_waitcnt lgkmcnt(2)
	v_mfma_f32_16x16x32_bf16 v[108:111], v[18:21], v[202:205], v[112:115]
	ds_read_b32 v51, v93 offset:57408
	ds_read_b32 v57, v93 offset:57664
	v_lshlrev_b32_e32 v59, 16, v126
	v_pk_mov_b32 v[48:49], v[58:59], v[120:121] op_sel:[1,0]
	v_mfma_f32_16x16x32_bf16 v[104:107], v[14:17], v[206:209], 0
	s_waitcnt lgkmcnt(2)
	s_nop 1
	v_add_f32_e32 v1, v108, v219
	v_mul_f32_e32 v1, 0xbfb8aa3b, v1
	v_exp_f32_e32 v1, v1
	v_mfma_f32_16x16x32_bf16 v[104:107], v[18:21], v[210:213], v[104:107]
	ds_read_b32 v220, v93 offset:57216
	ds_read_b128 v[198:201], v23 offset:23552
	ds_read_b128 v[202:205], v23 offset:23616
	ds_read_b128 v[206:209], v23 offset:32768
	ds_read_b128 v[210:213], v23 offset:32832
	v_mul_f32_e64 v64, v122, v48
	v_mul_f32_e64 v65, v123, v49
	v_lshlrev_b32_e32 v117, 16, v103
	v_add_f32_e32 v1, 1.0, v1
	v_rcp_f32_e32 v1, v1
	v_lshlrev_b32_e32 v116, 16, v128
	s_waitcnt lgkmcnt(1)
	s_nop 0
	v_add_f32_e32 v44, v104, v51
	v_mul_f32_e32 v44, 0xbfb8aa3b, v44
	v_exp_f32_e32 v44, v44
	s_waitcnt lgkmcnt(0)
; #define LAS __attribute__((address_space(3)))
; #define MFMA16(a, b, c) __builtin_amdgcn_mfma_f32_16x16x32_bf16(a, b, c, 0, 0, 0)
; template <bool PHASE_B>
; __device__ __forceinline__ void lru_item(const Params& p, LAS unsigned char* lds, int ci, int ci_next, int jb, const int tid, v4u (&xvn)[3]) {
;     ...
;             for (int ks = 0; ks < 2; ++ks) {
;                 const bf16x8 wa = *(const LAS bf16x8*)(lds + LR_WG + ((dir * 2 + 0) * 64 + 16 * ct + fr) * 144 + (32 * ks + 8 * fq) * 2);
;                 const bf16x8 wx = *(const LAS bf16x8*)(lds + LR_WG + ((dir * 2 + 1) * 64 + 16 * ct + fr) * 144 + (32 * ks + 8 * fq) * 2);
;                 ga = MFMA16(af[ks], wa, ga); gx = MFMA16(af[ks], wx, gx); }
;             const int ch = 16 * ct + fr; const float bav = GC[(dir * 3 + 0) * 64 + ch], bxv = GC[(dir * 3 + 1) * 64 + ch], c8 = GC[(dir * 3 + 2) * 64 + ch];
;             float Al = 1.f, Hl = 0.f;
; #pragma unroll
;             for (int ee = 0; ee < 4; ++ee) { const int e = dir ? 3 - ee : ee;
;                 const float r = __builtin_amdgcn_rcpf(1.f + __expf(-(ga[e] + bav))), ig = __builtin_amdgcn_rcpf(1.f + __expf(-(gx[e] + bxv)));
;                 const float la = -c8 * r; const float a = __expf(la); const float u = __builtin_amdgcn_sqrtf((1.f - a) * (1.f + a)) * (ig * xc[ct][e]);
;                 av[dir][ct][e] = a; uv[dir][ct][e] = u; Hl = a * Hl + u; Al *= a; }
;             const int o = dir ? 3 - fq : fq; const bool odd = (o & 1) != 0, hi2 = (o & 2) != 0;
;             const float A1 = __shfl_xor(Al, 16), H1 = __shfl_xor(Hl, 16);
;             const float pxA = odd ? A1 : 1.f, pxH = odd ? H1 : 0.f;
;             const float gA = Al * A1, gH = odd ? (Al * H1 + Hl) : (A1 * Hl + H1);
;             const float A2 = __shfl_xor(gA, 32), H2 = __shfl_xor(gH, 32);
;             const float PA = hi2 ? pxA * A2 : pxA, PH = hi2 ? (pxA * H2 + pxH) : pxH;
;             const float TA = gA * A2, TH = hi2 ? (gA * H2 + gH) : (A2 * gH + H2);
;             pA[dir][ct] = PA; pH[dir][ct] = PH;
;             ((LAS f32x2*)(lds + LR_SEG))[(dir * 8 + rt) * 64 + ch] = (f32x2){TA, TH};
	v_mul_f32_e32 v1, v1, v57
	v_mul_f32_e32 v1, 0xbfb8aa3b, v1
	v_add_f32_e32 v44, 1.0, v44
	v_rcp_f32_e32 v63, v44
	v_exp_f32_e32 v44, v1
	v_add_f32_e32 v1, v109, v219
	v_mul_f32_e32 v1, 0xbfb8aa3b, v1
	v_exp_f32_e32 v1, v1
	v_sub_f32_e32 v48, 1.0, v44
	v_add_f32_e32 v49, 1.0, v44
	v_mul_f32_e32 v48, v48, v49
	v_add_f32_e32 v1, 1.0, v1
	v_rcp_f32_e32 v1, v1
	v_add_f32_e32 v49, v105, v51
	v_mul_f32_e32 v49, 0xbfb8aa3b, v49
	v_exp_f32_e32 v49, v49
	v_mul_f32_e32 v1, v1, v57
	v_mul_f32_e32 v1, 0xbfb8aa3b, v1
	v_exp_f32_e32 v108, v1
	v_sqrt_f32_e32 v1, v48
	v_add_f32_e32 v48, 1.0, v49
	v_add_f32_e32 v49, v110, v219
	v_mul_f32_e32 v49, 0xbfb8aa3b, v49
	v_add_f32_e32 v26, v111, v219
	v_exp_f32_e32 v55, v49
	v_mul_f32_e32 v26, 0xbfb8aa3b, v26
	v_exp_f32_e32 v26, v26
	v_rcp_f32_e32 v109, v48
	v_sub_f32_e32 v48, 1.0, v108
	v_add_f32_e32 v49, 1.0, v108
	v_mul_f32_e32 v48, v48, v49
	v_sqrt_f32_e32 v49, v48
	v_add_f32_e32 v48, 1.0, v55
	v_rcp_f32_e32 v48, v48
	v_add_f32_e32 v26, 1.0, v26
	v_rcp_f32_e32 v26, v26
	v_add_f32_e32 v55, v106, v51
	v_mul_f32_e32 v48, v48, v57
	v_add_f32_e32 v51, v107, v51
	v_mul_f32_e32 v55, 0xbfb8aa3b, v55
	v_mul_f32_e32 v48, 0xbfb8aa3b, v48
	v_mul_f32_e32 v51, 0xbfb8aa3b, v51
	v_mul_f32_e32 v26, v26, v57
	v_exp_f32_e32 v104, v55
	v_exp_f32_e32 v55, v48
	v_exp_f32_e32 v51, v51
	v_mul_f32_e32 v26, 0xbfb8aa3b, v26
	v_exp_f32_e32 v107, v26
	v_mul_f32_e32 v48, v44, v108
	v_mul_f32_e32 v26, v55, v48
	v_add_f32_e32 v48, 1.0, v51
	v_add_f32_e32 v104, 1.0, v104
	v_rcp_f32_e32 v106, v48
	v_sub_f32_e32 v48, 1.0, v107
	v_add_f32_e32 v51, 1.0, v107
	v_rcp_f32_e32 v110, v104
	v_sub_f32_e32 v104, 1.0, v55
	v_add_f32_e32 v105, 1.0, v55
	v_mul_f32_e32 v48, v48, v51
	v_mul_f32_e32 v104, v104, v105
	v_sqrt_f32_e32 v57, v48
	v_mov_b32_e32 v48, v41
	v_mul_f32_e32 v41, v107, v26
	v_add_f32_e32 v26, v70, v71
	v_sqrt_f32_e32 v105, v104
	v_mov_b32_e32 v104, v45
	v_mul_f32_e32 v45, v26, v63
	v_pk_mul_f32 v[44:45], v[44:45], v[0:1]
	v_mov_b32_e32 v70, v35
	v_add_f32_e32 v1, v44, v45
	v_add_f32_e32 v44, v68, v69
	v_mul_f32_e32 v71, v108, v1
	v_mul_f32_e32 v69, v44, v109
	v_mov_b32_e32 v68, v47
	v_pk_fma_f32 v[48:49], v[48:49], v[68:69], v[70:71]
	ds_bpermute_b32 v111, v83, v41
	v_pk_add_f32 v[68:69], v[54:55], v[48:49]
	v_pk_mul_f32 v[48:49], v[54:55], v[48:49]
	v_add_f32_e32 v35, v65, v38
	v_add_f32_e32 v48, v66, v67
	v_mov_b32_e32 v69, v49
	v_mul_f32_e32 v51, v48, v110
	v_pk_fma_f32 v[54:55], v[104:105], v[50:51], v[68:69]
	s_waitcnt lgkmcnt(0)
	v_mul_f32_e32 v38, v41, v111
	v_pk_mul_f32 v[50:51], v[54:55], v[106:107]
	ds_bpermute_b32 v45, v84, v38
	v_fmac_f32_e32 v51, v50, v57
	ds_bpermute_b32 v1, v83, v51
	v_pk_mul_f32 v[70:71], v[122:123], v[58:59]
	s_waitcnt lgkmcnt(1)
	v_mul_f32_e32 v50, v38, v45
	v_add_f32_e32 v47, v71, v53
	s_waitcnt lgkmcnt(0)
	v_fma_f32 v41, v41, v1, v51
	v_fmac_f32_e32 v1, v51, v111
	v_cndmask_b32_e64 v1, v41, v1, s[42:43]
	ds_bpermute_b32 v41, v84, v1
	s_waitcnt lgkmcnt(0)
	v_fma_f32 v38, v38, v41, v1
	v_fmac_f32_e32 v41, v1, v45
	v_cndmask_b32_e64 v51, v38, v41, s[44:45]
	ds_write_b64 v86, v[50:51] offset:58752
	s_waitcnt lgkmcnt(2)
	v_mfma_f32_16x16x32_bf16 v[66:69], v[14:17], v[198:201], 0
	v_lshlrev_b32_e32 v51, 16, v43
	s_waitcnt lgkmcnt(2)
	v_mfma_f32_16x16x32_bf16 v[66:69], v[18:21], v[202:205], v[66:69]
	v_mov_b32_e32 v38, v31
	v_lshlrev_b32_e32 v50, 16, v61
	v_pk_mul_f32 v[120:121], v[38:39], v[50:51]
	v_mfma_f32_16x16x32_bf16 v[104:107], v[14:17], v[206:209], 0
	v_pk_mov_b32 v[50:51], v[116:117], v[50:51] op_sel:[1,0]
	s_waitcnt lgkmcnt(0)
	s_nop 1
	v_add_f32_e32 v1, v66, v220
	v_mul_f32_e32 v1, 0xbfb8aa3b, v1
	v_pk_mul_f32 v[118:119], v[38:39], v[116:117]
	v_pk_mul_f32 v[108:109], v[38:39], v[50:51]
	v_mfma_f32_16x16x32_bf16 v[104:107], v[18:21], v[210:213], v[104:107]
	ds_read_b32 v214, v93 offset:57472
	ds_read_b32 v215, v93 offset:57728
	ds_read_b32 v216, v93 offset:57280
	ds_read_b128 v[198:201], v23 offset:25856
	ds_read_b128 v[202:205], v23 offset:25920
	ds_read_b128 v[206:209], v23 offset:35072
	ds_read_b128 v[210:213], v23 offset:35136
	v_exp_f32_e32 v1, v1
	v_add_f32_e32 v61, v68, v220
	v_mul_f32_e32 v61, 0xbfb8aa3b, v61
	s_waitcnt lgkmcnt(1)
	s_nop 1
	v_add_f32_e32 v50, v104, v214
	v_add_f32_e32 v1, 1.0, v1
	v_mul_f32_e32 v50, 0xbfb8aa3b, v50
	v_rcp_f32_e32 v1, v1
	v_exp_f32_e32 v50, v50
	v_exp_f32_e32 v61, v61
	v_mov_b32_e32 v68, v32
	s_waitcnt lgkmcnt(0)
	v_mul_f32_e32 v1, v1, v215
	v_add_f32_e32 v50, 1.0, v50
	v_mul_f32_e32 v1, 0xbfb8aa3b, v1
	v_rcp_f32_e32 v51, v50
	v_exp_f32_e32 v50, v1
	v_add_f32_e32 v1, v67, v220
	v_mul_f32_e32 v1, 0xbfb8aa3b, v1
	v_exp_f32_e32 v1, v1
	v_sub_f32_e32 v55, 1.0, v50
	v_add_f32_e32 v57, 1.0, v50
	v_mul_f32_e32 v55, v55, v57
	v_add_f32_e32 v1, 1.0, v1
	v_rcp_f32_e32 v1, v1
	v_add_f32_e32 v57, v105, v214
	v_mul_f32_e32 v57, 0xbfb8aa3b, v57
	v_exp_f32_e32 v57, v57
	v_mul_f32_e32 v1, v1, v215
	v_mul_f32_e32 v1, 0xbfb8aa3b, v1
	v_exp_f32_e32 v58, v1
	v_add_f32_e32 v43, v69, v220
	v_mul_f32_e32 v43, 0xbfb8aa3b, v43
	v_sqrt_f32_e32 v1, v55
	v_add_f32_e32 v55, 1.0, v57
	v_sub_f32_e32 v57, 1.0, v58
	v_add_f32_e32 v63, 1.0, v58
	v_exp_f32_e32 v43, v43
	v_mul_f32_e32 v57, v57, v63
	v_sqrt_f32_e32 v67, v57
	v_add_f32_e32 v57, 1.0, v61
	v_rcp_f32_e32 v57, v57
	v_add_f32_e32 v43, 1.0, v43
	v_rcp_f32_e32 v43, v43
	v_add_f32_e32 v61, v106, v214
	v_mul_f32_e32 v57, v57, v215
	v_mul_f32_e32 v61, 0xbfb8aa3b, v61
	v_mul_f32_e32 v57, 0xbfb8aa3b, v57
	v_add_f32_e32 v38, v107, v214
	v_exp_f32_e32 v63, v61
	v_exp_f32_e32 v61, v57
	v_mul_f32_e32 v38, 0xbfb8aa3b, v38
	v_mul_f32_e32 v43, v43, v215
	v_exp_f32_e32 v38, v38
	v_mul_f32_e32 v43, 0xbfb8aa3b, v43
	v_exp_f32_e32 v105, v43
	v_sub_f32_e32 v65, 1.0, v61
	v_add_f32_e32 v66, 1.0, v61
	v_rcp_f32_e32 v55, v55
	v_mul_f32_e32 v65, v65, v66
	v_add_f32_e32 v38, 1.0, v38
	v_mov_b32_e32 v66, v30
	v_add_f32_e32 v30, v62, v36
	v_rcp_f32_e32 v104, v38
	v_sub_f32_e32 v38, 1.0, v105
	v_add_f32_e32 v49, 1.0, v105
	v_mul_f32_e32 v51, v30, v51
	v_mul_f32_e32 v57, v50, v58
	v_mul_f32_e32 v38, v38, v49
	v_pk_mul_f32 v[50:51], v[50:51], v[0:1]
	v_add_f32_e32 v63, 1.0, v63
	v_sqrt_f32_e32 v49, v38
	v_add_f32_e32 v1, v50, v51
	v_add_f32_e32 v38, v64, v35
	v_rcp_f32_e32 v63, v63
	v_mul_f32_e32 v43, v61, v57
	v_mul_f32_e32 v57, v58, v1
	v_mul_f32_e32 v51, v38, v55
	v_mov_b32_e32 v50, v59
	v_sqrt_f32_e32 v69, v65
	v_pk_fma_f32 v[50:51], v[66:67], v[50:51], v[56:57]
	v_mul_f32_e32 v32, v105, v43
	v_pk_add_f32 v[56:57], v[60:61], v[50:51]
	v_pk_mul_f32 v[50:51], v[60:61], v[50:51]
	ds_bpermute_b32 v65, v83, v32
	v_add_f32_e32 v50, v70, v47
	v_mov_b32_e32 v57, v51
	v_mul_f32_e32 v43, v50, v63
	v_pk_fma_f32 v[56:57], v[68:69], v[42:43], v[56:57]
	s_waitcnt lgkmcnt(0)
; #define LAS __attribute__((address_space(3)))
; #define MFMA16(a, b, c) __builtin_amdgcn_mfma_f32_16x16x32_bf16(a, b, c, 0, 0, 0)
; template <bool PHASE_B>
; __device__ __forceinline__ void lru_item(const Params& p, LAS unsigned char* lds, int ci, int ci_next, int jb, const int tid, v4u (&xvn)[3]) {
;     ...
;             for (int ks = 0; ks < 2; ++ks) {
;                 const bf16x8 wa = *(const LAS bf16x8*)(lds + LR_WG + ((dir * 2 + 0) * 64 + 16 * ct + fr) * 144 + (32 * ks + 8 * fq) * 2);
;                 const bf16x8 wx = *(const LAS bf16x8*)(lds + LR_WG + ((dir * 2 + 1) * 64 + 16 * ct + fr) * 144 + (32 * ks + 8 * fq) * 2);
;                 ga = MFMA16(af[ks], wa, ga); gx = MFMA16(af[ks], wx, gx); }
;             const int ch = 16 * ct + fr; const float bav = GC[(dir * 3 + 0) * 64 + ch], bxv = GC[(dir * 3 + 1) * 64 + ch], c8 = GC[(dir * 3 + 2) * 64 + ch];
;             float Al = 1.f, Hl = 0.f;
; #pragma unroll
;             for (int ee = 0; ee < 4; ++ee) { const int e = dir ? 3 - ee : ee;
;                 const float r = __builtin_amdgcn_rcpf(1.f + __expf(-(ga[e] + bav))), ig = __builtin_amdgcn_rcpf(1.f + __expf(-(gx[e] + bxv)));
;                 const float la = -c8 * r; const float a = __expf(la); const float u = __builtin_amdgcn_sqrtf((1.f - a) * (1.f + a)) * (ig * xc[ct][e]);
;                 av[dir][ct][e] = a; uv[dir][ct][e] = u; Hl = a * Hl + u; Al *= a; }
;             const int o = dir ? 3 - fq : fq; const bool odd = (o & 1) != 0, hi2 = (o & 2) != 0;
;             const float A1 = __shfl_xor(Al, 16), H1 = __shfl_xor(Hl, 16);
;             const float pxA = odd ? A1 : 1.f, pxH = odd ? H1 : 0.f;
;             const float gA = Al * A1, gH = odd ? (Al * H1 + Hl) : (A1 * Hl + H1);
;             const float A2 = __shfl_xor(gA, 32), H2 = __shfl_xor(gH, 32);
;             const float PA = hi2 ? pxA * A2 : pxA, PH = hi2 ? (pxA * H2 + pxH) : pxH;
;             const float TA = gA * A2, TH = hi2 ? (gA * H2 + gH) : (A2 * gH + H2);
;             pA[dir][ct] = PA; pH[dir][ct] = PH;
;             ((LAS f32x2*)(lds + LR_SEG))[(dir * 8 + rt) * 64 + ch] = (f32x2){TA, TH};
	v_mul_f32_e32 v36, v32, v65
	v_pk_mul_f32 v[42:43], v[56:57], v[104:105]
	v_add_f32_e32 v41, v119, v27
	v_fmac_f32_e32 v43, v42, v49
	ds_bpermute_b32 v1, v83, v43
	v_add_f32_e32 v45, v121, v27
	v_add_f32_e32 v53, v109, v27
	v_fmac_f32_e32 v27, v39, v116
	ds_bpermute_b32 v39, v84, v36
	s_waitcnt lgkmcnt(1)
	v_fma_f32 v32, v32, v1, v43
	v_fmac_f32_e32 v1, v43, v65
	v_cndmask_b32_e64 v1, v32, v1, s[42:43]
	ds_bpermute_b32 v32, v84, v1
	s_waitcnt lgkmcnt(1)
	v_mul_f32_e32 v58, v36, v39
	v_lshlrev_b32_e32 v43, 16, v102
	v_lshlrev_b32_e32 v42, 16, v29
	v_add_f32_e32 v35, v120, v45
	s_waitcnt lgkmcnt(0)
	v_fma_f32 v36, v36, v32, v1
	v_fmac_f32_e32 v32, v1, v39
	v_cndmask_b32_e64 v59, v36, v32, s[44:45]
	ds_write_b64 v86, v[58:59] offset:58880
	s_waitcnt lgkmcnt(2)
	v_mfma_f32_16x16x32_bf16 v[58:61], v[14:17], v[198:201], 0
	v_add_f32_e32 v45, v108, v53
	s_waitcnt lgkmcnt(2)
	v_mfma_f32_16x16x32_bf16 v[58:61], v[18:21], v[202:205], v[58:61]
	v_mov_b32_e32 v36, v33
	v_pk_mov_b32 v[108:109], v[42:43], v[116:117] op_sel:[1,0]
	v_mul_f32_e32 v70, v37, v42
	v_mfma_f32_16x16x32_bf16 v[62:65], v[14:17], v[206:209], 0
	v_mul_f32_e64 v106, v36, v116
	v_mul_f32_e64 v107, v37, v117
	s_waitcnt lgkmcnt(0)
	s_nop 0
	v_add_f32_e32 v1, v58, v216
	v_mul_f32_e32 v1, 0xbfb8aa3b, v1
	v_pk_mul_f32 v[108:109], v[36:37], v[108:109]
	v_pk_mul_f32 v[66:67], v[36:37], v[42:43]
	v_mfma_f32_16x16x32_bf16 v[62:65], v[18:21], v[210:213], v[62:65]
	ds_read_b32 v217, v93 offset:57536
	ds_read_b32 v218, v93 offset:57792
	ds_read_b32 v219, v93 offset:57856
	ds_read_b128 v[198:201], v23 offset:37376
	ds_read_b128 v[202:205], v23 offset:37440
	ds_read_b128 v[206:209], v23 offset:46592
	ds_read_b128 v[210:213], v23 offset:46656
	v_exp_f32_e32 v1, v1
	v_add_f32_e32 v29, v107, v35
	v_add_f32_e32 v35, v109, v45
	s_waitcnt lgkmcnt(1)
	s_nop 1
	v_add_f32_e32 v36, v62, v217
	v_add_f32_e32 v1, 1.0, v1
	v_mul_f32_e32 v36, 0xbfb8aa3b, v36
	v_rcp_f32_e32 v1, v1
	v_exp_f32_e32 v36, v36
	v_add_f32_e32 v51, v60, v216
	v_mul_f32_e32 v51, 0xbfb8aa3b, v51
	s_waitcnt lgkmcnt(0)
	v_mul_f32_e32 v1, v1, v218
	v_add_f32_e32 v36, 1.0, v36
	v_mul_f32_e32 v1, 0xbfb8aa3b, v1
	v_rcp_f32_e32 v42, v36
	v_exp_f32_e32 v36, v1
	v_add_f32_e32 v1, v59, v216
	v_mul_f32_e32 v1, 0xbfb8aa3b, v1
	v_exp_f32_e32 v1, v1
	v_sub_f32_e32 v45, 1.0, v36
	v_add_f32_e32 v47, 1.0, v36
	v_mul_f32_e32 v45, v45, v47
	v_add_f32_e32 v1, 1.0, v1
	v_rcp_f32_e32 v1, v1
	v_add_f32_e32 v47, v63, v217
	v_mul_f32_e32 v47, 0xbfb8aa3b, v47
	v_exp_f32_e32 v47, v47
	v_mul_f32_e32 v1, v1, v218
	v_mul_f32_e32 v1, 0xbfb8aa3b, v1
	v_exp_f32_e32 v49, v1
	v_add_f32_e32 v32, v61, v216
	v_mul_f32_e32 v32, 0xbfb8aa3b, v32
	v_exp_f32_e32 v51, v51
	v_exp_f32_e32 v32, v32
	v_sqrt_f32_e32 v1, v45
	v_add_f32_e32 v45, 1.0, v47
	v_sub_f32_e32 v47, 1.0, v49
	v_add_f32_e32 v53, 1.0, v49
	v_mul_f32_e32 v47, v47, v53
	v_sqrt_f32_e32 v59, v47
	v_add_f32_e32 v47, 1.0, v51
	v_add_f32_e32 v32, 1.0, v32
	v_rcp_f32_e32 v47, v47
	v_rcp_f32_e32 v32, v32
	v_add_f32_e32 v51, v64, v217
	v_add_f32_e32 v37, v65, v217
	v_mul_f32_e32 v47, v47, v218
	v_mul_f32_e32 v37, 0xbfb8aa3b, v37
	v_mul_f32_e32 v32, v32, v218
	v_mul_f32_e32 v47, 0xbfb8aa3b, v47
	v_exp_f32_e32 v37, v37
	v_mul_f32_e32 v32, 0xbfb8aa3b, v32
	v_exp_f32_e32 v71, v47
	v_exp_f32_e32 v63, v32
	v_mul_f32_e32 v51, 0xbfb8aa3b, v51
	v_mul_f32_e32 v47, v36, v49
	v_add_f32_e32 v37, 1.0, v37
	v_exp_f32_e32 v51, v51
	v_mul_f32_e32 v32, v71, v47
	v_rcp_f32_e32 v62, v37
	v_sub_f32_e32 v37, 1.0, v63
	v_add_f32_e32 v39, 1.0, v63
	v_rcp_f32_e32 v45, v45
	v_mul_f32_e32 v37, v37, v39
	v_mov_b32_e32 v58, v31
	v_mul_f32_e32 v31, v63, v32
	v_add_f32_e32 v32, v106, v29
	v_sqrt_f32_e32 v39, v37
	v_mul_f32_e32 v37, v32, v42
	v_pk_mul_f32 v[36:37], v[36:37], v[0:1]
	v_add_f32_e32 v51, 1.0, v51
	v_sub_f32_e32 v53, 1.0, v71
	v_add_f32_e32 v55, 1.0, v71
	v_add_f32_e32 v1, v36, v37
	v_add_f32_e32 v36, v108, v35
	v_rcp_f32_e32 v51, v51
	v_mul_f32_e32 v53, v53, v55
	v_mul_f32_e32 v65, v49, v1
	v_mov_b32_e32 v64, v27
	v_mul_f32_e32 v69, v36, v45
	v_mov_b32_e32 v68, v43
	v_add_f32_e32 v41, v118, v41
	v_sqrt_f32_e32 v61, v53
	v_pk_fma_f32 v[42:43], v[58:59], v[68:69], v[64:65]
	v_add_f32_e32 v41, v67, v41
	v_pk_add_f32 v[58:59], v[70:71], v[42:43]
	v_pk_mul_f32 v[42:43], v[70:71], v[42:43]
	v_mov_b32_e32 v60, v33
	v_add_f32_e32 v42, v66, v41
	v_mov_b32_e32 v59, v43
	v_mul_f32_e32 v29, v42, v51
	v_pk_fma_f32 v[28:29], v[60:61], v[28:29], v[58:59]
	ds_bpermute_b32 v33, v83, v31
	v_pk_mul_f32 v[58:59], v[28:29], v[62:63]
	s_waitcnt lgkmcnt(0)
	v_mul_f32_e32 v27, v31, v33
	v_fmac_f32_e32 v59, v58, v39
	ds_bpermute_b32 v1, v83, v59
	ds_bpermute_b32 v29, v84, v27
	s_waitcnt lgkmcnt(1)
	v_fma_f32 v31, v31, v1, v59
	v_fmac_f32_e32 v1, v59, v33
	v_cndmask_b32_e64 v1, v31, v1, s[42:43]
	ds_bpermute_b32 v31, v84, v1
	s_waitcnt lgkmcnt(1)
	v_mul_f32_e32 v58, v27, v29
	s_waitcnt lgkmcnt(0)
	v_fma_f32 v27, v27, v31, v1
	v_fmac_f32_e32 v31, v1, v29
	v_cndmask_b32_e64 v59, v27, v31, s[44:45]
	ds_write_b64 v86, v[58:59] offset:59008
	s_waitcnt lgkmcnt(1)
	v_mfma_f32_16x16x32_bf16 v[58:61], v[14:17], v[198:201], 0
	ds_read_b32 v29, v93 offset:58112
	ds_read_b32 v31, v93 offset:58368
	s_waitcnt lgkmcnt(5)
	v_mfma_f32_16x16x32_bf16 v[58:61], v[18:21], v[202:205], v[58:61]
	s_waitcnt lgkmcnt(4)
	v_mfma_f32_16x16x32_bf16 v[66:69], v[14:17], v[206:209], 0
	s_waitcnt lgkmcnt(3)
	v_mfma_f32_16x16x32_bf16 v[62:65], v[18:21], v[210:213], v[66:69]
	ds_read_b32 v220, v93 offset:57920
	ds_read_b32 v221, v93 offset:58176
	ds_read_b32 v222, v93 offset:58432
	ds_read_b128 v[198:201], v23 offset:39680
	ds_read_b128 v[202:205], v23 offset:39744
	ds_read_b128 v[206:209], v23 offset:48896
	ds_read_b128 v[210:213], v23 offset:48960
	s_waitcnt lgkmcnt(2)
; #define LAS __attribute__((address_space(3)))
; #define MFMA16(a, b, c) __builtin_amdgcn_mfma_f32_16x16x32_bf16(a, b, c, 0, 0, 0)
; template <bool PHASE_B>
; __device__ __forceinline__ void lru_item(const Params& p, LAS unsigned char* lds, int ci, int ci_next, int jb, const int tid, v4u (&xvn)[3]) {
;     ...
;             for (int ks = 0; ks < 2; ++ks) {
;                 const bf16x8 wa = *(const LAS bf16x8*)(lds + LR_WG + ((dir * 2 + 0) * 64 + 16 * ct + fr) * 144 + (32 * ks + 8 * fq) * 2);
;                 const bf16x8 wx = *(const LAS bf16x8*)(lds + LR_WG + ((dir * 2 + 1) * 64 + 16 * ct + fr) * 144 + (32 * ks + 8 * fq) * 2);
;                 ga = MFMA16(af[ks], wa, ga); gx = MFMA16(af[ks], wx, gx); }
;             const int ch = 16 * ct + fr; const float bav = GC[(dir * 3 + 0) * 64 + ch], bxv = GC[(dir * 3 + 1) * 64 + ch], c8 = GC[(dir * 3 + 2) * 64 + ch];
;             float Al = 1.f, Hl = 0.f;
; #pragma unroll
;             for (int ee = 0; ee < 4; ++ee) { const int e = dir ? 3 - ee : ee;
;                 const float r = __builtin_amdgcn_rcpf(1.f + __expf(-(ga[e] + bav))), ig = __builtin_amdgcn_rcpf(1.f + __expf(-(gx[e] + bxv)));
;                 const float la = -c8 * r; const float a = __expf(la); const float u = __builtin_amdgcn_sqrtf((1.f - a) * (1.f + a)) * (ig * xc[ct][e]);
;                 av[dir][ct][e] = a; uv[dir][ct][e] = u; Hl = a * Hl + u; Al *= a; }
;             const int o = dir ? 3 - fq : fq; const bool odd = (o & 1) != 0, hi2 = (o & 2) != 0;
;             const float A1 = __shfl_xor(Al, 16), H1 = __shfl_xor(Hl, 16);
;             const float pxA = odd ? A1 : 1.f, pxH = odd ? H1 : 0.f;
;             const float gA = Al * A1, gH = odd ? (Al * H1 + Hl) : (A1 * Hl + H1);
;             const float A2 = __shfl_xor(gA, 32), H2 = __shfl_xor(gH, 32);
;             const float PA = hi2 ? pxA * A2 : pxA, PH = hi2 ? (pxA * H2 + pxH) : pxH;
;             const float TA = gA * A2, TH = hi2 ? (gA * H2 + gH) : (A2 * gH + H2);
;             pA[dir][ct] = PA; pH[dir][ct] = PH;
;             ((LAS f32x2*)(lds + LR_SEG))[(dir * 8 + rt) * 64 + ch] = (f32x2){TA, TH};
	s_nop 2
	v_add_f32_e32 v1, v61, v219
	v_mul_f32_e32 v1, 0xbfb8aa3b, v1
	v_exp_f32_e32 v1, v1
	s_nop 0
	v_add_f32_e32 v1, 1.0, v1
	v_rcp_f32_e32 v1, v1
	s_waitcnt lgkmcnt(1)
	v_add_f32_e32 v33, v65, v29
	v_mul_f32_e32 v33, 0xbfb8aa3b, v33
	v_exp_f32_e32 v33, v33
	s_waitcnt lgkmcnt(0)
	v_mul_f32_e32 v1, v1, v31
	v_mul_f32_e32 v1, 0xbfb8aa3b, v1
	v_exp_f32_e32 v66, v1
	v_add_f32_e32 v1, 1.0, v33
	v_rcp_f32_e32 v33, v1
	v_sub_f32_e32 v1, 1.0, v66
	v_add_f32_e32 v35, 1.0, v66
	v_mul_f32_e32 v1, v1, v35
	v_add_f32_e32 v35, v60, v219
	v_mul_f32_e32 v35, 0xbfb8aa3b, v35
	v_exp_f32_e32 v35, v35
	v_mul_f32_e32 v67, v52, v33
	v_sqrt_f32_e32 v1, v1
	v_mul_f32_e32 v52, 0, v66
	v_add_f32_e32 v33, 1.0, v35
	v_rcp_f32_e32 v33, v33
	v_add_f32_e32 v35, v64, v29
	v_mul_f32_e32 v35, 0xbfb8aa3b, v35
	v_exp_f32_e32 v35, v35
	v_mul_f32_e32 v33, v33, v31
	v_mul_f32_e32 v33, 0xbfb8aa3b, v33
	v_exp_f32_e32 v53, v33
	s_nop 0
	v_pk_fma_f32 v[60:61], v[66:67], v[0:1], v[52:53] op_sel_hi:[1,1,0]
	v_add_f32_e32 v1, 1.0, v35
	v_rcp_f32_e32 v52, v1
	v_sub_f32_e32 v1, 1.0, v53
	v_add_f32_e32 v33, 1.0, v53
	v_mul_f32_e32 v1, v1, v33
	v_add_f32_e32 v33, v59, v219
	v_mul_f32_e32 v33, 0xbfb8aa3b, v33
	v_sqrt_f32_e32 v1, v1
	v_exp_f32_e32 v33, v33
	v_add_f32_e32 v27, v58, v219
	v_mov_b32_e32 v47, v61
	v_mul_f32_e32 v27, 0xbfb8aa3b, v27
	v_pk_mul_f32 v[46:47], v[46:47], v[52:53]
	v_exp_f32_e32 v27, v27
	v_fmac_f32_e32 v47, v46, v1
	v_add_f32_e32 v1, 1.0, v33
	v_rcp_f32_e32 v1, v1
	v_add_f32_e32 v27, 1.0, v27
	v_add_f32_e32 v33, v63, v29
	v_rcp_f32_e32 v27, v27
	v_mul_f32_e32 v33, 0xbfb8aa3b, v33
	v_mul_f32_e32 v1, v1, v31
	v_exp_f32_e32 v33, v33
	v_mul_f32_e32 v1, 0xbfb8aa3b, v1
	v_exp_f32_e32 v61, v1
	v_add_f32_e32 v29, v62, v29
	v_mul_f32_e32 v29, 0xbfb8aa3b, v29
	v_mul_f32_e32 v27, v27, v31
	v_exp_f32_e32 v29, v29
	v_mul_f32_e32 v27, 0xbfb8aa3b, v27
	v_add_f32_e32 v33, 1.0, v33
	v_mov_b32_e32 v41, v47
	v_exp_f32_e32 v47, v27
	v_rcp_f32_e32 v60, v33
	v_sub_f32_e32 v33, 1.0, v61
	v_add_f32_e32 v35, 1.0, v61
	v_mul_f32_e32 v33, v33, v35
	v_sqrt_f32_e32 v33, v33
	v_add_f32_e32 v27, 1.0, v29
	v_rcp_f32_e32 v46, v27
	v_sub_f32_e32 v27, 1.0, v47
	v_add_f32_e32 v29, 1.0, v47
	v_mul_f32_e32 v27, v27, v29
	v_pk_mul_f32 v[40:41], v[40:41], v[60:61]
	v_sqrt_f32_e32 v27, v27
	v_fmac_f32_e32 v41, v40, v33
	v_mul_f32_e32 v1, v66, v53
	v_mov_b32_e32 v35, v41
	v_mul_f32_e32 v1, v61, v1
	v_pk_mul_f32 v[34:35], v[34:35], v[46:47]
	v_mul_f32_e32 v1, v47, v1
	v_fmac_f32_e32 v35, v34, v27
	ds_bpermute_b32 v27, v83, v1
	ds_bpermute_b32 v29, v83, v35
	s_waitcnt lgkmcnt(1)
	v_mul_f32_e32 v31, v1, v27
	s_waitcnt lgkmcnt(0)
	v_fma_f32 v1, v1, v29, v35
	v_fmac_f32_e32 v29, v35, v27
	v_cndmask_b32_e64 v1, v1, v29, s[46:47]
	ds_bpermute_b32 v27, v84, v31
	ds_bpermute_b32 v29, v84, v1
	s_waitcnt lgkmcnt(1)
	v_mul_f32_e32 v34, v31, v27
	s_waitcnt lgkmcnt(0)
	v_fma_f32 v31, v31, v29, v1
	v_fmac_f32_e32 v29, v1, v27
	v_cndmask_b32_e64 v35, v31, v29, s[48:49]
	ds_write_b64 v86, v[34:35] offset:62720
	s_waitcnt lgkmcnt(1)
	v_mfma_f32_16x16x32_bf16 v[58:61], v[14:17], v[198:201], 0
	s_waitcnt lgkmcnt(5)
	v_mfma_f32_16x16x32_bf16 v[58:61], v[18:21], v[202:205], v[58:61]
	s_waitcnt lgkmcnt(4)
	v_mfma_f32_16x16x32_bf16 v[66:69], v[14:17], v[206:209], 0
	s_waitcnt lgkmcnt(3)
	v_mfma_f32_16x16x32_bf16 v[62:65], v[18:21], v[210:213], v[66:69]
	ds_read_b32 v214, v93 offset:57984
	ds_read_b32 v215, v93 offset:58240
	ds_read_b32 v216, v93 offset:58496
	ds_read_b128 v[198:201], v23 offset:41984
	ds_read_b128 v[202:205], v23 offset:42048
	ds_read_b128 v[206:209], v23 offset:51200
	ds_read_b128 v[210:213], v23 offset:51264
	s_waitcnt lgkmcnt(2)
	s_nop 2
	v_add_f32_e32 v1, v61, v220
	v_mul_f32_e32 v1, 0xbfb8aa3b, v1
	v_exp_f32_e32 v1, v1
	s_nop 0
	v_add_f32_e32 v1, 1.0, v1
	v_rcp_f32_e32 v1, v1
	s_waitcnt lgkmcnt(1)
	v_add_f32_e32 v33, v65, v221
	v_mul_f32_e32 v33, 0xbfb8aa3b, v33
	v_exp_f32_e32 v33, v33
	s_waitcnt lgkmcnt(0)
	v_mul_f32_e32 v1, v1, v222
	v_mul_f32_e32 v1, 0xbfb8aa3b, v1
	v_exp_f32_e32 v34, v1
	v_add_f32_e32 v1, 1.0, v33
	v_rcp_f32_e32 v33, v1
	v_sub_f32_e32 v1, 1.0, v34
	v_add_f32_e32 v35, 1.0, v34
	v_mul_f32_e32 v1, v1, v35
	v_add_f32_e32 v35, v60, v220
	v_mul_f32_e32 v35, 0xbfb8aa3b, v35
	v_exp_f32_e32 v37, v35
	v_mul_f32_e32 v35, v54, v33
	v_sqrt_f32_e32 v1, v1
	v_mul_f32_e32 v40, 0, v34
	v_add_f32_e32 v33, 1.0, v37
	v_rcp_f32_e32 v33, v33
	v_add_f32_e32 v37, v64, v221
	v_mul_f32_e32 v37, 0xbfb8aa3b, v37
	v_exp_f32_e32 v37, v37
	v_mul_f32_e32 v33, v33, v222
	v_mul_f32_e32 v33, 0xbfb8aa3b, v33
	v_exp_f32_e32 v41, v33
	s_nop 0
	v_pk_fma_f32 v[46:47], v[34:35], v[0:1], v[40:41] op_sel_hi:[1,1,0]
	v_add_f32_e32 v1, 1.0, v37
	v_rcp_f32_e32 v40, v1
	v_sub_f32_e32 v1, 1.0, v41
	v_add_f32_e32 v33, 1.0, v41
	v_mul_f32_e32 v1, v1, v33
	v_add_f32_e32 v33, v59, v220
	v_mul_f32_e32 v33, 0xbfb8aa3b, v33
	v_sqrt_f32_e32 v1, v1
	v_exp_f32_e32 v33, v33
	v_mov_b32_e32 v49, v47
	v_add_f32_e32 v27, v58, v220
	v_pk_mul_f32 v[46:47], v[48:49], v[40:41]
	v_mul_f32_e32 v27, 0xbfb8aa3b, v27
	v_fmac_f32_e32 v47, v46, v1
	v_add_f32_e32 v1, 1.0, v33
	v_add_f32_e32 v33, v63, v221
	v_exp_f32_e32 v27, v27
	v_rcp_f32_e32 v1, v1
	v_mul_f32_e32 v33, 0xbfb8aa3b, v33
	v_exp_f32_e32 v33, v33
	v_add_f32_e32 v27, 1.0, v27
	v_mul_f32_e32 v1, v1, v222
	v_rcp_f32_e32 v27, v27
	v_mul_f32_e32 v1, 0xbfb8aa3b, v1
	v_add_f32_e32 v33, 1.0, v33
	v_exp_f32_e32 v35, v1
	v_mul_f32_e32 v1, v34, v41
	v_rcp_f32_e32 v34, v33
	v_add_f32_e32 v29, v62, v221
	v_mul_f32_e32 v29, 0xbfb8aa3b, v29
	v_mul_f32_e32 v27, v27, v222
	v_mov_b32_e32 v45, v47
	v_exp_f32_e32 v29, v29
	v_mul_f32_e32 v27, 0xbfb8aa3b, v27
	v_pk_mul_f32 v[40:41], v[44:45], v[34:35]
	v_exp_f32_e32 v45, v27
	v_sub_f32_e32 v33, 1.0, v35
	v_add_f32_e32 v37, 1.0, v35
	v_mul_f32_e32 v33, v33, v37
	v_sqrt_f32_e32 v33, v33
	v_add_f32_e32 v27, 1.0, v29
	v_rcp_f32_e32 v44, v27
	v_sub_f32_e32 v27, 1.0, v45
	v_add_f32_e32 v29, 1.0, v45
	v_mul_f32_e32 v27, v27, v29
	v_sqrt_f32_e32 v29, v27
	v_fmac_f32_e32 v41, v40, v33
	v_mov_b32_e32 v27, v41
	v_mul_f32_e32 v1, v35, v1
	v_pk_mul_f32 v[26:27], v[26:27], v[44:45]
	v_mul_f32_e32 v1, v45, v1
	v_fmac_f32_e32 v27, v26, v29
	ds_bpermute_b32 v26, v83, v1
	ds_bpermute_b32 v29, v83, v27
	s_waitcnt lgkmcnt(1)
; #define LAS __attribute__((address_space(3)))
; #define MFMA16(a, b, c) __builtin_amdgcn_mfma_f32_16x16x32_bf16(a, b, c, 0, 0, 0)
; template <bool PHASE_B>
; __device__ __forceinline__ void lru_item(const Params& p, LAS unsigned char* lds, int ci, int ci_next, int jb, const int tid, v4u (&xvn)[3]) {
;     ...
;             for (int ks = 0; ks < 2; ++ks) {
;                 const bf16x8 wa = *(const LAS bf16x8*)(lds + LR_WG + ((dir * 2 + 0) * 64 + 16 * ct + fr) * 144 + (32 * ks + 8 * fq) * 2);
;                 const bf16x8 wx = *(const LAS bf16x8*)(lds + LR_WG + ((dir * 2 + 1) * 64 + 16 * ct + fr) * 144 + (32 * ks + 8 * fq) * 2);
;                 ga = MFMA16(af[ks], wa, ga); gx = MFMA16(af[ks], wx, gx); }
;             const int ch = 16 * ct + fr; const float bav = GC[(dir * 3 + 0) * 64 + ch], bxv = GC[(dir * 3 + 1) * 64 + ch], c8 = GC[(dir * 3 + 2) * 64 + ch];
;             float Al = 1.f, Hl = 0.f;
; #pragma unroll
;             for (int ee = 0; ee < 4; ++ee) { const int e = dir ? 3 - ee : ee;
;                 const float r = __builtin_amdgcn_rcpf(1.f + __expf(-(ga[e] + bav))), ig = __builtin_amdgcn_rcpf(1.f + __expf(-(gx[e] + bxv)));
;                 const float la = -c8 * r; const float a = __expf(la); const float u = __builtin_amdgcn_sqrtf((1.f - a) * (1.f + a)) * (ig * xc[ct][e]);
;                 av[dir][ct][e] = a; uv[dir][ct][e] = u; Hl = a * Hl + u; Al *= a; }
;             const int o = dir ? 3 - fq : fq; const bool odd = (o & 1) != 0, hi2 = (o & 2) != 0;
;             const float A1 = __shfl_xor(Al, 16), H1 = __shfl_xor(Hl, 16);
;             const float pxA = odd ? A1 : 1.f, pxH = odd ? H1 : 0.f;
;             const float gA = Al * A1, gH = odd ? (Al * H1 + Hl) : (A1 * Hl + H1);
;             const float A2 = __shfl_xor(gA, 32), H2 = __shfl_xor(gH, 32);
;             const float PA = hi2 ? pxA * A2 : pxA, PH = hi2 ? (pxA * H2 + pxH) : pxH;
;             const float TA = gA * A2, TH = hi2 ? (gA * H2 + gH) : (A2 * gH + H2);
;             pA[dir][ct] = PA; pH[dir][ct] = PH;
;             ((LAS f32x2*)(lds + LR_SEG))[(dir * 8 + rt) * 64 + ch] = (f32x2){TA, TH};
	v_mul_f32_e32 v31, v1, v26
	s_waitcnt lgkmcnt(0)
	v_fma_f32 v1, v1, v29, v27
	v_fmac_f32_e32 v29, v27, v26
	v_cndmask_b32_e64 v1, v1, v29, s[46:47]
	ds_bpermute_b32 v27, v84, v31
	ds_bpermute_b32 v29, v84, v1
	s_waitcnt lgkmcnt(1)
	v_mul_f32_e32 v26, v31, v27
	s_waitcnt lgkmcnt(0)
	v_fma_f32 v31, v31, v29, v1
	v_fmac_f32_e32 v29, v1, v27
	v_cndmask_b32_e64 v27, v31, v29, s[48:49]
	ds_write_b64 v86, v[26:27] offset:62848
	s_waitcnt lgkmcnt(1)
	v_mfma_f32_16x16x32_bf16 v[44:47], v[14:17], v[198:201], 0
	s_waitcnt lgkmcnt(5)
	v_mfma_f32_16x16x32_bf16 v[44:47], v[18:21], v[202:205], v[44:47]
	s_waitcnt lgkmcnt(4)
	v_mfma_f32_16x16x32_bf16 v[58:61], v[14:17], v[206:209], 0
	s_waitcnt lgkmcnt(3)
	v_mfma_f32_16x16x32_bf16 v[52:55], v[18:21], v[210:213], v[58:61]
	ds_read_b32 v217, v93 offset:58048
	ds_read_b32 v218, v93 offset:58304
	ds_read_b32 v219, v93 offset:58560
	ds_read_b128 v[198:201], v23 offset:44288
	ds_read_b128 v[202:205], v23 offset:44352
	ds_read_b128 v[206:209], v23 offset:53504
	ds_read_b128 v[210:213], v23 offset:53568
	s_waitcnt lgkmcnt(2)
	s_nop 2
	v_add_f32_e32 v1, v47, v214
	v_mul_f32_e32 v1, 0xbfb8aa3b, v1
	v_exp_f32_e32 v1, v1
	s_nop 0
	v_add_f32_e32 v1, 1.0, v1
	v_rcp_f32_e32 v1, v1
	s_waitcnt lgkmcnt(1)
	v_add_f32_e32 v26, v55, v215
	v_mul_f32_e32 v26, 0xbfb8aa3b, v26
	v_exp_f32_e32 v27, v26
	s_waitcnt lgkmcnt(0)
	v_mul_f32_e32 v1, v1, v216
	v_mul_f32_e32 v1, 0xbfb8aa3b, v1
	v_exp_f32_e32 v26, v1
	v_add_f32_e32 v1, 1.0, v27
	v_rcp_f32_e32 v27, v1
	v_add_f32_e32 v37, v54, v215
	v_sub_f32_e32 v1, 1.0, v26
	v_add_f32_e32 v34, 1.0, v26
	v_mul_f32_e32 v1, v1, v34
	v_add_f32_e32 v34, v46, v214
	v_mul_f32_e32 v34, 0xbfb8aa3b, v34
	v_exp_f32_e32 v35, v34
	v_mul_f32_e32 v37, 0xbfb8aa3b, v37
	v_sqrt_f32_e32 v1, v1
	v_exp_f32_e32 v37, v37
	v_add_f32_e32 v35, 1.0, v35
	v_rcp_f32_e32 v35, v35
	v_mul_f32_e32 v27, v56, v27
	v_mul_f32_e32 v34, 0, v26
	v_mul_f32_e32 v35, v35, v216
	v_mul_f32_e32 v35, 0xbfb8aa3b, v35
	v_exp_f32_e32 v35, v35
	s_nop 0
	v_pk_fma_f32 v[40:41], v[26:27], v[0:1], v[34:35] op_sel_hi:[1,1,0]
	v_add_f32_e32 v1, 1.0, v37
	v_rcp_f32_e32 v34, v1
	v_sub_f32_e32 v1, 1.0, v35
	v_add_f32_e32 v27, 1.0, v35
	v_mul_f32_e32 v1, v1, v27
	v_add_f32_e32 v27, v45, v214
	v_mul_f32_e32 v27, 0xbfb8aa3b, v27
	v_sqrt_f32_e32 v1, v1
	v_exp_f32_e32 v27, v27
	v_mov_b32_e32 v51, v41
	v_pk_mul_f32 v[40:41], v[50:51], v[34:35]
	v_add_f32_e32 v29, v44, v214
	v_fmac_f32_e32 v41, v40, v1
	v_add_f32_e32 v1, 1.0, v27
	v_rcp_f32_e32 v1, v1
	v_add_f32_e32 v27, v53, v215
	v_mul_f32_e32 v27, 0xbfb8aa3b, v27
	v_exp_f32_e32 v34, v27
	v_mul_f32_e32 v1, v1, v216
	v_mul_f32_e32 v1, 0xbfb8aa3b, v1
	v_exp_f32_e32 v27, v1
	v_mul_f32_e32 v1, v26, v35
	v_add_f32_e32 v26, 1.0, v34
	v_mul_f32_e32 v29, 0xbfb8aa3b, v29
	v_rcp_f32_e32 v26, v26
	v_exp_f32_e32 v29, v29
	v_sub_f32_e32 v34, 1.0, v27
	v_add_f32_e32 v35, 1.0, v27
	v_mul_f32_e32 v34, v34, v35
	v_mov_b32_e32 v39, v41
	v_sqrt_f32_e32 v37, v34
	v_pk_mul_f32 v[34:35], v[38:39], v[26:27]
	v_add_f32_e32 v26, 1.0, v29
	v_rcp_f32_e32 v26, v26
	v_add_f32_e32 v29, v52, v215
	v_mul_f32_e32 v29, 0xbfb8aa3b, v29
	v_exp_f32_e32 v29, v29
	v_mul_f32_e32 v26, v26, v216
	v_mul_f32_e32 v26, 0xbfb8aa3b, v26
	v_exp_f32_e32 v39, v26
	v_add_f32_e32 v26, 1.0, v29
	v_rcp_f32_e32 v38, v26
	v_fmac_f32_e32 v35, v34, v37
	v_sub_f32_e32 v26, 1.0, v39
	v_add_f32_e32 v29, 1.0, v39
	v_mul_f32_e32 v26, v26, v29
	v_sqrt_f32_e32 v29, v26
	v_mov_b32_e32 v31, v35
	v_mul_f32_e32 v1, v27, v1
	v_pk_mul_f32 v[26:27], v[30:31], v[38:39]
	v_mul_f32_e32 v1, v39, v1
	v_fmac_f32_e32 v27, v26, v29
	ds_bpermute_b32 v26, v83, v1
	ds_bpermute_b32 v29, v83, v27
	s_waitcnt lgkmcnt(1)
	v_mul_f32_e32 v30, v1, v26
	s_waitcnt lgkmcnt(0)
	v_fma_f32 v1, v1, v29, v27
	v_fmac_f32_e32 v29, v27, v26
	v_cndmask_b32_e64 v1, v1, v29, s[46:47]
	ds_bpermute_b32 v27, v84, v30
	ds_bpermute_b32 v29, v84, v1
	s_waitcnt lgkmcnt(1)
	v_mul_f32_e32 v26, v30, v27
	s_waitcnt lgkmcnt(0)
	v_fma_f32 v30, v30, v29, v1
	v_fmac_f32_e32 v29, v1, v27
	v_cndmask_b32_e64 v27, v30, v29, s[48:49]
	ds_write_b64 v86, v[26:27] offset:62976
	s_waitcnt lgkmcnt(1)
	v_mfma_f32_16x16x32_bf16 v[38:41], v[14:17], v[198:201], 0
	s_waitcnt lgkmcnt(5)
	v_mfma_f32_16x16x32_bf16 v[38:41], v[18:21], v[202:205], v[38:41]
	s_waitcnt lgkmcnt(4)
	v_mfma_f32_16x16x32_bf16 v[14:17], v[14:17], v[206:209], 0
	s_waitcnt lgkmcnt(3)
	v_mfma_f32_16x16x32_bf16 v[14:17], v[18:21], v[210:213], v[14:17]
	s_waitcnt lgkmcnt(2)
; #define LAS __attribute__((address_space(3)))
; template <bool PHASE_B>
; __device__ __forceinline__ void lru_item(const Params& p, LAS unsigned char* lds, int ci, int ci_next, int jb, const int tid, v4u (&xvn)[3]) {
;     ...
;             const int ch = 16 * ct + fr; const float bav = GC[(dir * 3 + 0) * 64 + ch], bxv = GC[(dir * 3 + 1) * 64 + ch], c8 = GC[(dir * 3 + 2) * 64 + ch];
;             float Al = 1.f, Hl = 0.f;
; #pragma unroll
;             for (int ee = 0; ee < 4; ++ee) { const int e = dir ? 3 - ee : ee;
;                 const float r = __builtin_amdgcn_rcpf(1.f + __expf(-(ga[e] + bav))), ig = __builtin_amdgcn_rcpf(1.f + __expf(-(gx[e] + bxv)));
;                 const float la = -c8 * r; const float a = __expf(la); const float u = __builtin_amdgcn_sqrtf((1.f - a) * (1.f + a)) * (ig * xc[ct][e]);
;                 av[dir][ct][e] = a; uv[dir][ct][e] = u; Hl = a * Hl + u; Al *= a; }
;             const int o = dir ? 3 - fq : fq; const bool odd = (o & 1) != 0, hi2 = (o & 2) != 0;
;             const float A1 = __shfl_xor(Al, 16), H1 = __shfl_xor(Hl, 16);
;             const float pxA = odd ? A1 : 1.f, pxH = odd ? H1 : 0.f;
;             const float gA = Al * A1, gH = odd ? (Al * H1 + Hl) : (A1 * Hl + H1);
;             const float A2 = __shfl_xor(gA, 32), H2 = __shfl_xor(gH, 32);
;             const float PA = hi2 ? pxA * A2 : pxA, PH = hi2 ? (pxA * H2 + pxH) : pxH;
;             const float TA = gA * A2, TH = hi2 ? (gA * H2 + gH) : (A2 * gH + H2);
;             pA[dir][ct] = PA; pH[dir][ct] = PH;
;             ((LAS f32x2*)(lds + LR_SEG))[(dir * 8 + rt) * 64 + ch] = (f32x2){TA, TH};
;     ...
;     __syncthreads();
;     if constexpr (!PHASE_B) {
;         if (tid < 128) { const int dir = tid >> 6, ch = tid & 63; float A = 1.f, H = 0.f;
; #pragma unroll
;             for (int q = 0; q < 8; ++q) { const f32x2 sh = ((const LAS f32x2*)(lds + LR_SEG))[(dir * 8 + (dir ? 7 - q : q)) * 64 + ch]; H = sh.x * H + sh.y; A *= sh.x; }
;             ((f32x2*)(p.ws + WS_CAR))[(size_t)(ci * 2 + dir) * 768 + jb * 64 + ch] = (f32x2){A, H}; }
	s_nop 2
	v_add_f32_e32 v1, v41, v217
	v_mul_f32_e32 v1, 0xbfb8aa3b, v1
	v_exp_f32_e32 v1, v1
	s_nop 0
	v_add_f32_e32 v1, 1.0, v1
	v_rcp_f32_e32 v1, v1
	s_waitcnt lgkmcnt(1)
	v_add_f32_e32 v17, v17, v218
	v_mul_f32_e32 v17, 0xbfb8aa3b, v17
	v_exp_f32_e32 v17, v17
	s_waitcnt lgkmcnt(0)
	v_mul_f32_e32 v1, v1, v219
	v_mul_f32_e32 v1, 0xbfb8aa3b, v1
	v_exp_f32_e32 v18, v1
	v_add_f32_e32 v1, 1.0, v17
	v_rcp_f32_e32 v17, v1
	v_add_f32_e32 v16, v16, v218
	v_sub_f32_e32 v1, 1.0, v18
	v_add_f32_e32 v19, 1.0, v18
	v_mul_f32_e32 v1, v1, v19
	v_add_f32_e32 v19, v40, v217
	v_mul_f32_e32 v19, 0xbfb8aa3b, v19
	v_exp_f32_e32 v21, v19
	v_mul_f32_e32 v19, v28, v17
	v_mul_f32_e32 v16, 0xbfb8aa3b, v16
	v_sqrt_f32_e32 v1, v1
	v_add_f32_e32 v17, 1.0, v21
	v_rcp_f32_e32 v17, v17
	v_exp_f32_e32 v16, v16
	v_mul_f32_e32 v20, 0, v18
	v_pk_fma_f32 v[20:21], v[18:19], v[0:1], v[20:21] op_sel_hi:[1,1,0]
	v_mul_f32_e32 v17, v17, v219
	v_mul_f32_e32 v17, 0xbfb8aa3b, v17
	v_exp_f32_e32 v17, v17
	v_add_f32_e32 v1, 1.0, v16
	v_rcp_f32_e32 v16, v1
	v_mov_b32_e32 v43, v21
	v_sub_f32_e32 v1, 1.0, v17
	v_add_f32_e32 v19, 1.0, v17
	v_mul_f32_e32 v1, v1, v19
	v_add_f32_e32 v19, v39, v217
	v_mul_f32_e32 v19, 0xbfb8aa3b, v19
	v_sqrt_f32_e32 v1, v1
	v_exp_f32_e32 v19, v19
	v_pk_mul_f32 v[20:21], v[42:43], v[16:17]
	v_add_f32_e32 v15, v15, v218
	v_fmac_f32_e32 v21, v20, v1
	v_add_f32_e32 v1, 1.0, v19
	v_rcp_f32_e32 v1, v1
	v_mul_f32_e32 v15, 0xbfb8aa3b, v15
	v_exp_f32_e32 v15, v15
	v_add_f32_e32 v14, v14, v218
	v_mul_f32_e32 v1, v1, v219
	v_mul_f32_e32 v1, 0xbfb8aa3b, v1
	v_exp_f32_e32 v19, v1
	v_add_f32_e32 v15, 1.0, v15
	v_mul_f32_e32 v1, v18, v17
	v_rcp_f32_e32 v18, v15
	v_sub_f32_e32 v15, 1.0, v19
	v_add_f32_e32 v16, 1.0, v19
	v_mul_f32_e32 v15, v15, v16
	v_add_f32_e32 v16, v38, v217
	v_mul_f32_e32 v16, 0xbfb8aa3b, v16
	v_exp_f32_e32 v20, v16
	v_sqrt_f32_e32 v23, v15
	v_mul_f32_e32 v14, 0xbfb8aa3b, v14
	v_exp_f32_e32 v14, v14
	v_add_f32_e32 v15, 1.0, v20
	v_rcp_f32_e32 v15, v15
	v_mov_b32_e32 v37, v21
	v_pk_mul_f32 v[16:17], v[36:37], v[18:19]
	v_add_f32_e32 v14, 1.0, v14
	v_mul_f32_e32 v15, v15, v219
	v_mul_f32_e32 v15, 0xbfb8aa3b, v15
	v_exp_f32_e32 v15, v15
	v_fmac_f32_e32 v17, v16, v23
	v_rcp_f32_e32 v14, v14
	v_mov_b32_e32 v33, v17
	v_sub_f32_e32 v16, 1.0, v15
	v_add_f32_e32 v18, 1.0, v15
	v_mul_f32_e32 v16, v16, v18
	v_sqrt_f32_e32 v18, v16
	v_mul_f32_e32 v1, v19, v1
	v_pk_mul_f32 v[16:17], v[32:33], v[14:15]
	v_mul_f32_e32 v1, v15, v1
	v_fmac_f32_e32 v17, v16, v18
	ds_bpermute_b32 v14, v83, v1
	ds_bpermute_b32 v15, v83, v17
	s_waitcnt lgkmcnt(1)
	v_mul_f32_e32 v16, v1, v14
	s_waitcnt lgkmcnt(0)
	v_fma_f32 v1, v1, v15, v17
	v_fmac_f32_e32 v15, v17, v14
	v_cndmask_b32_e64 v1, v1, v15, s[46:47]
	ds_bpermute_b32 v15, v84, v16
	ds_bpermute_b32 v17, v84, v1
	s_waitcnt lgkmcnt(1)
	v_mul_f32_e32 v14, v16, v15
	s_waitcnt lgkmcnt(0)
	v_fma_f32 v16, v16, v17, v1
	v_fmac_f32_e32 v17, v1, v15
	v_cndmask_b32_e64 v15, v16, v17, s[48:49]
	ds_write_b64 v86, v[14:15] offset:63104
	s_waitcnt vmcnt(0) lgkmcnt(0)
	s_barrier
	s_and_saveexec_b64 s[12:13], s[50:51]
	s_cbranch_execz .LBB0_528
	ds_read_b64 v[14:15], v94 offset:58624
	ds_read_b64 v[16:17], v95 offset:58624
	ds_read_b64 v[18:19], v96 offset:58624
	ds_read_b64 v[20:21], v97 offset:58624
	s_waitcnt lgkmcnt(3)
	v_fma_f32 v1, 0, v14, v15
	s_waitcnt lgkmcnt(2)
	v_pk_mul_f32 v[14:15], v[14:15], v[16:17]
	v_fmac_f32_e32 v17, v16, v1
	s_waitcnt lgkmcnt(1)
	v_fma_f32 v1, v18, v17, v19
	ds_read_b64 v[16:17], v98 offset:58624
	ds_read_b64 v[26:27], v99 offset:58624
	ds_read_b64 v[28:29], v100 offset:58624
	ds_read_b64 v[30:31], v101 offset:58624
	s_waitcnt lgkmcnt(4)
	v_fma_f32 v1, v20, v1, v21
	v_mov_b32_e32 v32, v14
	v_mov_b32_e32 v34, v18
	s_waitcnt lgkmcnt(3)
	v_fma_f32 v33, v16, v1, v17
	s_waitcnt lgkmcnt(2)
	v_mov_b32_e32 v35, v26
	v_pk_mul_f32 v[14:15], v[14:15], v[18:19]
	v_pk_fma_f32 v[18:19], v[32:33], v[34:35], v[26:27]
	v_pk_mul_f32 v[14:15], v[14:15], v[20:21]
	s_waitcnt lgkmcnt(1)
	v_mov_b32_e32 v17, v28
	v_mov_b32_e32 v15, v19
	v_pk_mul_f32 v[18:19], v[14:15], v[16:17]
	v_pk_fma_f32 v[14:15], v[14:15], v[16:17], v[28:29]
	v_pk_mul_f32 v[18:19], v[18:19], v[26:27]
	v_mov_b32_e32 v16, v28
	v_mov_b32_e32 v14, v18
	s_waitcnt lgkmcnt(0)
	v_mov_b32_e32 v17, v30
	v_pk_mul_f32 v[18:19], v[18:19], v[28:29]
	v_pk_fma_f32 v[14:15], v[14:15], v[16:17], v[30:31]
	v_pk_mul_f32 v[18:19], v[18:19], v[30:31]
	s_nop 0
	v_mov_b32_e32 v19, v15
	v_mad_i64_i32 v[14:15], s[60:61], v87, s64, v[24:25]
	global_store_dwordx2 v[14:15], v[18:19], off
	s_branch .LBB0_528
